# no s_setprio in K-loops; last-layer down->final-norm seam is a 4-WG local barrier with the final norm rows remapped to the owning panel group
# speedup vs baseline: 1.1168x; 1.0100x over previous
; __device__ __forceinline__ unsigned xb_ld(unsigned* p)              { return __hip_atomic_load(p, __ATOMIC_RELAXED, __HIP_MEMORY_SCOPE_AGENT); }
; __device__ __forceinline__ unsigned xb_add(unsigned* p, unsigned v) { return __hip_atomic_fetch_add(p, v, __ATOMIC_RELAXED, __HIP_MEMORY_SCOPE_AGENT); }
; #define XB_SPIN(cond, bar) do { unsigned _sp = 0; while (cond) { __builtin_amdgcn_s_sleep(1); \
;     if ((++_sp & 255u) == 0u) { if (xb_ld(&(bar)[XB_TMO])) break; if (_sp > XB_SPIN_CAP) { atomicAdd(&(bar)[XB_TMO], 1u); break; } } } } while (0)
; __device__ __forceinline__ void xcd_barrier(const XcdBarrier& b) {
;     asm volatile("s_waitcnt vmcnt(0)" ::: "memory");
;     __syncthreads();
;     if (threadIdx.x == 0) {
;         unsigned* bar = b.bar;
;         __builtin_amdgcn_s_waitcnt(0);
;         unsigned nloc = b.st[0], nx = b.st[1];
;         if (nloc == 0u) { xcd_barrier_complete(bar, b.x, nloc, nx); b.st[0] = nloc; b.st[1] = nx; }
;         const unsigned old = xb_add(&bar[XB_XSUB(b.x)], 1u);
;         const unsigned gen = old / nloc;
;         if (old + 1u == (gen + 1u) * nloc) {
;             __builtin_amdgcn_fence(__ATOMIC_RELEASE, "agent");
;             asm volatile("s_waitcnt vmcnt(0)" ::: "memory");
;             const unsigned og = xb_add(&bar[XB_TOP], 1u);
;             const unsigned tg = og / nx;
;             if (og + 1u == (tg + 1u) * nx) xb_add(&bar[XB_TOPGEN], 1u);
;             else XB_SPIN(xb_ld(&bar[XB_TOPGEN]) == tg, bar);
;             __builtin_amdgcn_fence(__ATOMIC_ACQUIRE, "agent");
;             xb_add(&bar[XB_XGEN(b.x)], 1u);
;             asm volatile("s_waitcnt vmcnt(0)" ::: "memory");
;         } else {
;             XB_SPIN(xb_ld(&bar[XB_XGEN(b.x)]) == gen, bar);
;             __builtin_amdgcn_fence(__ATOMIC_ACQUIRE, "agent");
;             asm volatile("s_waitcnt vmcnt(0)" ::: "memory");
;         }
;     }
;     __syncthreads();
; }
.Llb6_entry:
	s_waitcnt vmcnt(0)
	s_waitcnt vmcnt(0) lgkmcnt(0)
	s_barrier
	s_mov_b64 s[4:5], exec
	s_add_u32 s100, s100, 4
	v_readlane_b32 s2, v252, 11
	v_readlane_b32 s3, v252, 12
	s_and_b64 s[2:3], s[4:5], s[2:3]
	s_mov_b64 exec, s[2:3]
	s_cbranch_execz .Llb6_done
	v_mov_b32_e32 v2, 0
	v_mov_b32_e32 v3, 1
	s_and_b32 s3, s100, 3
	s_and_b32 s2, s100, -4
	s_cmp_lg_u32 s3, 0
	s_cbranch_scc1 .Llb6_haveflag
	global_load_dword v4, v2, s[98:99] offset:128 sc1
	s_waitcnt vmcnt(0)
	v_readfirstlane_b32 s8, v4
	s_bcnt1_i32_b32 s8, s8
	s_cmp_eq_u32 s8, 1
	s_cselect_b32 s3, 1, 2
	s_or_b32 s100, s100, s3

; __device__ __forceinline__ unsigned xb_ld(unsigned* p)              { return __hip_atomic_load(p, __ATOMIC_RELAXED, __HIP_MEMORY_SCOPE_AGENT); }
; __device__ __forceinline__ unsigned xb_add(unsigned* p, unsigned v) { return __hip_atomic_fetch_add(p, v, __ATOMIC_RELAXED, __HIP_MEMORY_SCOPE_AGENT); }
; #define XB_SPIN(cond, bar) do { unsigned _sp = 0; while (cond) { __builtin_amdgcn_s_sleep(1); \
;     if ((++_sp & 255u) == 0u) { if (xb_ld(&(bar)[XB_TMO])) break; if (_sp > XB_SPIN_CAP) { atomicAdd(&(bar)[XB_TMO], 1u); break; } } } } while (0)
; __device__ __forceinline__ void xcd_barrier(const XcdBarrier& b) {
;     asm volatile("s_waitcnt vmcnt(0)" ::: "memory");
;     __syncthreads();
;     if (threadIdx.x == 0) {
;         unsigned* bar = b.bar;
;         __builtin_amdgcn_s_waitcnt(0);
;         unsigned nloc = b.st[0], nx = b.st[1];
;         if (nloc == 0u) { xcd_barrier_complete(bar, b.x, nloc, nx); b.st[0] = nloc; b.st[1] = nx; }
;         const unsigned old = xb_add(&bar[XB_XSUB(b.x)], 1u);
;         const unsigned gen = old / nloc;
;         if (old + 1u == (gen + 1u) * nloc) {
;             __builtin_amdgcn_fence(__ATOMIC_RELEASE, "agent");
;             asm volatile("s_waitcnt vmcnt(0)" ::: "memory");
;             const unsigned og = xb_add(&bar[XB_TOP], 1u);
;             const unsigned tg = og / nx;
;             if (og + 1u == (tg + 1u) * nx) xb_add(&bar[XB_TOPGEN], 1u);
;             else XB_SPIN(xb_ld(&bar[XB_TOPGEN]) == tg, bar);
;             __builtin_amdgcn_fence(__ATOMIC_ACQUIRE, "agent");
;             xb_add(&bar[XB_XGEN(b.x)], 1u);
;             asm volatile("s_waitcnt vmcnt(0)" ::: "memory");
;         } else {
;             XB_SPIN(xb_ld(&bar[XB_XGEN(b.x)]) == gen, bar);
;             __builtin_amdgcn_fence(__ATOMIC_ACQUIRE, "agent");
;             asm volatile("s_waitcnt vmcnt(0)" ::: "memory");
;         }
;     }
;     __syncthreads();
; }
.Llb6_done:
	s_or_b64 exec, exec, s[4:5]
	s_waitcnt lgkmcnt(0)
	s_barrier
	s_branch .LBB0_108

; #define PG8_STAGE(bufoff, gbase, voff) do { _Pragma("unroll") for (int _i = 0; _i < 2; ++_i) \
;         __builtin_amdgcn_global_load_lds((const unsigned*)((const char*)(gbase) + (voff)[_i]), (PG8_LAS unsigned*)(lds + (bufoff) + ldsw + _i * 8192), 16, 0, 0); } while (0)
; #define PG8_LDA(dst, b, h) do { _Pragma("unroll") for (int m = 0; m < 4; ++m) _Pragma("unroll") for (int k = 0; k < 2; ++k) dst[m][k] = *(const PG8_LAS bf16x8*)(lds + PG8_SA(b, h) + aoff + m * 2048 + k * 1024); } while (0)
; #define PG8_LDB(dst, b, h) do { _Pragma("unroll") for (int n = 0; n < 2; ++n) _Pragma("unroll") for (int k = 0; k < 2; ++k) dst[n][k] = *(const PG8_LAS bf16x8*)(lds + PG8_SB(b, h) + boff + n * 2048 + k * 1024); } while (0)
; #define PG8_MMA(ai, bj, At, Bt) do { __builtin_amdgcn_s_setprio(1); _Pragma("unroll") for (int m = 0; m < 4; ++m) _Pragma("unroll") for (int n = 0; n < 2; ++n) _Pragma("unroll") for (int k = 0; k < 2; ++k) \
;         acc[ai][bj][m][n] = __builtin_amdgcn_mfma_f32_16x16x32_bf16(Bt[n][k], At[m][k], acc[ai][bj][m][n], 0, 0, 0); __builtin_amdgcn_s_setprio(0); } while (0)
; #define PG8_WAIT_V(n) asm volatile("s_waitcnt vmcnt(" #n ")" ::: "memory")
; #define PG8_WAIT_L(n) asm volatile("s_waitcnt lgkmcnt(" #n ")" ::: "memory")
; #define PG8_BAR __builtin_amdgcn_s_barrier()
; #define PG8_SCHED __builtin_amdgcn_sched_barrier(0)
;     ...
;         for (int t = 0; t < nt; t += 2) {
;             const bool last = (t == nt - 2);
;             const char* a1 = cA + (size_t)(t + 1) * kstep;
;             const char* a2 = last ? nA : cA + (size_t)(t + 2) * kstep; const char* b2 = last ? nB : cB + (size_t)(t + 2) * kstep;
;             const char* a3 = a2 + kstep; const char* b3 = b2 + kstep;
;             if (last && has_next) S.a_ready(nxt);
;             if constexpr (SP2) {
;             PG8_LDB(B0, 0, 0); PG8_LDB(B1, 0, 1); PG8_SCHED; PG8_LDA(At, 0, 0); PG8_STAGE(PG8_SA(1, 1), a1 + hstepA, voffA);
;             PG8_WAIT_V(8); PG8_WAIT_L(0); PG8_BAR; PG8_MMA(0, 0, At, B0); PG8_MMA(0, 1, At, B1); PG8_BAR; PG8_SCHED;
;             PG8_LDA(At, 0, 1); PG8_STAGE(PG8_SB(0, 0), b2, voffB); PG8_STAGE(PG8_SB(0, 1), b2 + hstepB, voffB); PG8_STAGE(PG8_SA(0, 0), a2, voffA);
;             PG8_WAIT_V(8); PG8_WAIT_L(0); PG8_BAR; PG8_MMA(1, 0, At, B0); PG8_MMA(1, 1, At, B1); PG8_BAR; PG8_SCHED;
.LBB0_127:
	s_ashr_i32 s91, s90, 31
	s_lshl_b64 s[10:11], s[90:91], 19
	s_add_u32 s22, s44, s10
	s_addc_u32 s23, s45, s11
	s_lshl_b64 s[10:11], s[88:89], 9
	s_add_u32 s94, s22, s10
	s_addc_u32 s95, s23, s11
	s_andn2_b64 vcc, exec, s[72:73]
	s_cbranch_vccnz .LBB0_130
	s_and_b64 s[10:11], s[40:41], exec
	s_cselect_b32 s10, s95, s9
	s_cselect_b32 s11, s94, s8
	s_add_u32 s22, s6, 0x100
	s_addc_u32 s23, s7, 0
	s_add_u32 s6, s8, 0x40080
	s_addc_u32 s7, s9, 0
	s_mov_b32 s8, 0
	s_add_i32 s24, s8, 2
	s_add_u32 s25, s6, 0xfffc0080
	s_addc_u32 s9, s7, -1
	s_add_i32 s27, 0, 0x10000
	s_cmp_eq_u32 s18, s8
	s_cselect_b32 s9, s10, s9
	s_cselect_b32 s8, s11, s25
	v_add_u32_e32 v152, s27, v159
	s_cselect_b32 s35, s93, s23
	s_cselect_b32 s34, s92, s22
	s_add_i32 s25, 0, 0x14000
	ds_read_b128 v[144:147], v152
	ds_read_b128 v[148:151], v152 offset:1024
	ds_read_b128 v[154:157], v152 offset:2048
	ds_read_b128 v[160:163], v152 offset:3072
	v_add_u32_e32 v152, s25, v159
	ds_read_b128 v[172:175], v152
	ds_read_b128 v[180:183], v152 offset:1024
	ds_read_b128 v[184:187], v152 offset:2048
	ds_read_b128 v[188:191], v152 offset:3072
	v_lshl_add_u64 v[164:165], s[6:7], 0, v[142:143]
	s_add_i32 m0, s2, 0xc000
	ds_read_b128 v[192:195], v179
	ds_read_b128 v[196:199], v179 offset:1024
	ds_read_b128 v[200:203], v179 offset:2048
	ds_read_b128 v[204:207], v179 offset:3072
	ds_read_b128 v[208:211], v179 offset:4096
	ds_read_b128 v[212:215], v179 offset:5120
	ds_read_b128 v[216:219], v179 offset:6144
	ds_read_b128 v[220:223], v179 offset:7168
	global_load_lds_dwordx4 v[164:165], off
	v_lshl_add_u64 v[164:165], s[6:7], 0, v[140:141]
	s_add_i32 m0, s2, 0xe000
	s_nop 0
	global_load_lds_dwordx4 v[164:165], off
	s_waitcnt vmcnt(8)
	s_waitcnt lgkmcnt(0)
	s_barrier
	s_waitcnt lgkmcnt(0)
	v_mfma_f32_16x16x32_bf16 v[126:129], v[144:147], v[192:195], 0
	v_mfma_f32_16x16x32_bf16 v[122:125], v[154:157], v[192:195], 0
	v_mfma_f32_16x16x32_bf16 v[110:113], v[144:147], v[200:203], 0
	v_mfma_f32_16x16x32_bf16 v[106:109], v[154:157], v[200:203], 0
	v_mfma_f32_16x16x32_bf16 v[94:97], v[144:147], v[208:211], 0
	v_mfma_f32_16x16x32_bf16 v[90:93], v[154:157], v[208:211], 0
	v_mfma_f32_16x16x32_bf16 v[78:81], v[144:147], v[216:219], 0
	v_mfma_f32_16x16x32_bf16 v[74:77], v[154:157], v[216:219], 0
	v_mfma_f32_16x16x32_bf16 v[126:129], v[148:151], v[196:199], v[126:129]
	v_mfma_f32_16x16x32_bf16 v[122:125], v[160:163], v[196:199], v[122:125]
	v_mfma_f32_16x16x32_bf16 v[110:113], v[148:151], v[204:207], v[110:113]
	v_mfma_f32_16x16x32_bf16 v[106:109], v[160:163], v[204:207], v[106:109]
	v_mfma_f32_16x16x32_bf16 v[94:97], v[148:151], v[212:215], v[94:97]
	v_mfma_f32_16x16x32_bf16 v[90:93], v[160:163], v[212:215], v[90:93]
	v_mfma_f32_16x16x32_bf16 v[78:81], v[148:151], v[220:223], v[78:81]
	v_mfma_f32_16x16x32_bf16 v[74:77], v[160:163], v[220:223], v[74:77]
	v_mfma_f32_16x16x32_bf16 v[118:121], v[172:175], v[192:195], 0
	v_mfma_f32_16x16x32_bf16 v[114:117], v[184:187], v[192:195], 0
	v_mfma_f32_16x16x32_bf16 v[102:105], v[172:175], v[200:203], 0
	v_mfma_f32_16x16x32_bf16 v[98:101], v[184:187], v[200:203], 0
	v_mfma_f32_16x16x32_bf16 v[86:89], v[172:175], v[208:211], 0
	v_mfma_f32_16x16x32_bf16 v[82:85], v[184:187], v[208:211], 0
	v_mfma_f32_16x16x32_bf16 v[70:73], v[172:175], v[216:219], 0
	v_mfma_f32_16x16x32_bf16 v[66:69], v[184:187], v[216:219], 0
	v_mfma_f32_16x16x32_bf16 v[118:121], v[180:183], v[196:199], v[118:121]
	v_mfma_f32_16x16x32_bf16 v[114:117], v[188:191], v[196:199], v[114:117]
	v_mfma_f32_16x16x32_bf16 v[102:105], v[180:183], v[204:207], v[102:105]
	v_mfma_f32_16x16x32_bf16 v[98:101], v[188:191], v[204:207], v[98:101]
	v_mfma_f32_16x16x32_bf16 v[86:89], v[180:183], v[212:215], v[86:89]
	v_mfma_f32_16x16x32_bf16 v[82:85], v[188:191], v[212:215], v[82:85]
	v_mfma_f32_16x16x32_bf16 v[70:73], v[180:183], v[220:223], v[70:73]
	v_mfma_f32_16x16x32_bf16 v[66:69], v[188:191], v[220:223], v[66:69]
	s_barrier
	s_add_i32 s27, s27, s0
	v_lshl_add_u64 v[164:165], s[34:35], 0, v[134:135]
	s_mov_b32 m0, s27
	ds_read_b128 v[192:195], v179 offset:16384
	ds_read_b128 v[196:199], v179 offset:17408
	ds_read_b128 v[200:203], v179 offset:18432
	ds_read_b128 v[204:207], v179 offset:19456
	ds_read_b128 v[208:211], v179 offset:20480
	ds_read_b128 v[212:215], v179 offset:21504
	ds_read_b128 v[216:219], v179 offset:22528
	ds_read_b128 v[220:223], v179 offset:23552
	global_load_lds_dwordx4 v[164:165], off
	s_add_i32 m0, s27, 0x2000
	v_lshl_add_u64 v[168:169], s[34:35], 0, v[130:131]
	s_add_u32 s34, s34, s42
	s_addc_u32 s35, s35, s43
	s_add_i32 s25, s25, s0
	global_load_lds_dwordx4 v[168:169], off
	v_lshl_add_u64 v[170:171], s[34:35], 0, v[134:135]
	s_mov_b32 m0, s25
	v_lshl_add_u64 v[176:177], s[34:35], 0, v[130:131]
	global_load_lds_dwordx4 v[170:171], off
	s_add_i32 m0, s25, 0x2000
	v_lshl_add_u64 v[224:225], s[8:9], 0, v[136:137]
	global_load_lds_dwordx4 v[176:177], off
	s_mov_b32 m0, s2
	v_lshl_add_u64 v[226:227], s[8:9], 0, v[132:133]
	global_load_lds_dwordx4 v[224:225], off
	s_mov_b32 m0, s3
	s_nop 0
	global_load_lds_dwordx4 v[226:227], off
	s_waitcnt vmcnt(8)
	s_waitcnt lgkmcnt(0)
	s_barrier
; #define PG8_STAGE(bufoff, gbase, voff) do { _Pragma("unroll") for (int _i = 0; _i < 2; ++_i) \
;         __builtin_amdgcn_global_load_lds((const unsigned*)((const char*)(gbase) + (voff)[_i]), (PG8_LAS unsigned*)(lds + (bufoff) + ldsw + _i * 8192), 16, 0, 0); } while (0)
; #define PG8_LDA(dst, b, h) do { _Pragma("unroll") for (int m = 0; m < 4; ++m) _Pragma("unroll") for (int k = 0; k < 2; ++k) dst[m][k] = *(const PG8_LAS bf16x8*)(lds + PG8_SA(b, h) + aoff + m * 2048 + k * 1024); } while (0)
; #define PG8_LDB(dst, b, h) do { _Pragma("unroll") for (int n = 0; n < 2; ++n) _Pragma("unroll") for (int k = 0; k < 2; ++k) dst[n][k] = *(const PG8_LAS bf16x8*)(lds + PG8_SB(b, h) + boff + n * 2048 + k * 1024); } while (0)
; #define PG8_MMA(ai, bj, At, Bt) do { __builtin_amdgcn_s_setprio(1); _Pragma("unroll") for (int m = 0; m < 4; ++m) _Pragma("unroll") for (int n = 0; n < 2; ++n) _Pragma("unroll") for (int k = 0; k < 2; ++k) \
;         acc[ai][bj][m][n] = __builtin_amdgcn_mfma_f32_16x16x32_bf16(Bt[n][k], At[m][k], acc[ai][bj][m][n], 0, 0, 0); __builtin_amdgcn_s_setprio(0); } while (0)
; #define PG8_WAIT_V(n) asm volatile("s_waitcnt vmcnt(" #n ")" ::: "memory")
; #define PG8_WAIT_L(n) asm volatile("s_waitcnt lgkmcnt(" #n ")" ::: "memory")
; #define PG8_BAR __builtin_amdgcn_s_barrier()
; #define PG8_SCHED __builtin_amdgcn_sched_barrier(0)
;     ...
;             PG8_WAIT_V(8); PG8_WAIT_L(0); PG8_BAR; PG8_MMA(1, 0, At, B0); PG8_MMA(1, 1, At, B1); PG8_BAR; PG8_SCHED;
;             PG8_LDB(B0, 1, 0); PG8_LDB(B1, 1, 1); PG8_SCHED; PG8_LDA(At, 1, 0); PG8_STAGE(PG8_SA(0, 1), a2 + hstepA, voffA);
;             PG8_WAIT_V(8); PG8_WAIT_L(0); PG8_BAR; PG8_MMA(0, 0, At, B0); PG8_MMA(0, 1, At, B1); PG8_BAR; PG8_SCHED;
	s_waitcnt lgkmcnt(0)
	v_mfma_f32_16x16x32_bf16 v[62:65], v[144:147], v[192:195], 0
	v_mfma_f32_16x16x32_bf16 v[58:61], v[154:157], v[192:195], 0
	v_mfma_f32_16x16x32_bf16 v[46:49], v[144:147], v[200:203], 0
	v_mfma_f32_16x16x32_bf16 v[42:45], v[154:157], v[200:203], 0
	v_mfma_f32_16x16x32_bf16 v[30:33], v[144:147], v[208:211], 0
	v_mfma_f32_16x16x32_bf16 v[26:29], v[154:157], v[208:211], 0
	v_mfma_f32_16x16x32_bf16 v[14:17], v[144:147], v[216:219], 0
	v_mfma_f32_16x16x32_bf16 v[10:13], v[154:157], v[216:219], 0
	v_mfma_f32_16x16x32_bf16 v[62:65], v[148:151], v[196:199], v[62:65]
	v_mfma_f32_16x16x32_bf16 v[58:61], v[160:163], v[196:199], v[58:61]
	v_mfma_f32_16x16x32_bf16 v[46:49], v[148:151], v[204:207], v[46:49]
	v_mfma_f32_16x16x32_bf16 v[42:45], v[160:163], v[204:207], v[42:45]
	v_mfma_f32_16x16x32_bf16 v[30:33], v[148:151], v[212:215], v[30:33]
	v_mfma_f32_16x16x32_bf16 v[26:29], v[160:163], v[212:215], v[26:29]
	v_mfma_f32_16x16x32_bf16 v[14:17], v[148:151], v[220:223], v[14:17]
	v_mfma_f32_16x16x32_bf16 v[10:13], v[160:163], v[220:223], v[10:13]
	v_mfma_f32_16x16x32_bf16 v[54:57], v[172:175], v[192:195], 0
	v_mfma_f32_16x16x32_bf16 v[50:53], v[184:187], v[192:195], 0
	v_mfma_f32_16x16x32_bf16 v[38:41], v[172:175], v[200:203], 0
	v_mfma_f32_16x16x32_bf16 v[34:37], v[184:187], v[200:203], 0
	v_mfma_f32_16x16x32_bf16 v[22:25], v[172:175], v[208:211], 0
	v_mfma_f32_16x16x32_bf16 v[18:21], v[184:187], v[208:211], 0
	v_mfma_f32_16x16x32_bf16 v[6:9], v[172:175], v[216:219], 0
	v_mfma_f32_16x16x32_bf16 v[2:5], v[184:187], v[216:219], 0
	v_mfma_f32_16x16x32_bf16 v[54:57], v[180:183], v[196:199], v[54:57]
	v_mfma_f32_16x16x32_bf16 v[50:53], v[188:191], v[196:199], v[50:53]
	v_mfma_f32_16x16x32_bf16 v[38:41], v[180:183], v[204:207], v[38:41]
	v_mfma_f32_16x16x32_bf16 v[34:37], v[188:191], v[204:207], v[34:37]
	v_mfma_f32_16x16x32_bf16 v[22:25], v[180:183], v[212:215], v[22:25]
	v_mfma_f32_16x16x32_bf16 v[18:21], v[188:191], v[212:215], v[18:21]
	v_mfma_f32_16x16x32_bf16 v[6:9], v[180:183], v[220:223], v[6:9]
	v_mfma_f32_16x16x32_bf16 v[2:5], v[188:191], v[220:223], v[2:5]
	s_barrier
	s_add_i32 s25, 0, 0x18000
	v_add_u32_e32 v152, s25, v159
	s_add_i32 s27, 0, 0x1c000
	ds_read_b128 v[144:147], v152
	ds_read_b128 v[148:151], v152 offset:1024
	ds_read_b128 v[154:157], v152 offset:2048
	ds_read_b128 v[160:163], v152 offset:3072
	v_add_u32_e32 v152, s27, v159
	ds_read_b128 v[172:175], v152
	ds_read_b128 v[180:183], v152 offset:1024
	ds_read_b128 v[184:187], v152 offset:2048
	ds_read_b128 v[188:191], v152 offset:3072
	s_add_u32 s8, s8, 0x40000
	s_addc_u32 s9, s9, 0
	s_mov_b32 m0, s12
	v_lshl_add_u64 v[228:229], s[8:9], 0, v[136:137]
	ds_read_b128 v[192:195], v179 offset:32768
	ds_read_b128 v[196:199], v179 offset:33792
	ds_read_b128 v[200:203], v179 offset:34816
	ds_read_b128 v[204:207], v179 offset:35840
	ds_read_b128 v[208:211], v179 offset:36864
	ds_read_b128 v[212:215], v179 offset:37888
	ds_read_b128 v[216:219], v179 offset:38912
	ds_read_b128 v[220:223], v179 offset:39936
	global_load_lds_dwordx4 v[228:229], off
	v_lshl_add_u64 v[228:229], s[8:9], 0, v[132:133]
	s_mov_b32 m0, s13
	s_nop 0
	global_load_lds_dwordx4 v[228:229], off
	s_waitcnt vmcnt(8)
	s_waitcnt lgkmcnt(0)
	s_barrier
	s_waitcnt lgkmcnt(0)
	v_mfma_f32_16x16x32_bf16 v[126:129], v[144:147], v[192:195], v[126:129]
	v_mfma_f32_16x16x32_bf16 v[122:125], v[154:157], v[192:195], v[122:125]
	v_mfma_f32_16x16x32_bf16 v[110:113], v[144:147], v[200:203], v[110:113]
	v_mfma_f32_16x16x32_bf16 v[106:109], v[154:157], v[200:203], v[106:109]
	v_mfma_f32_16x16x32_bf16 v[94:97], v[144:147], v[208:211], v[94:97]
	v_mfma_f32_16x16x32_bf16 v[90:93], v[154:157], v[208:211], v[90:93]
	v_mfma_f32_16x16x32_bf16 v[78:81], v[144:147], v[216:219], v[78:81]
	v_mfma_f32_16x16x32_bf16 v[74:77], v[154:157], v[216:219], v[74:77]
	v_mfma_f32_16x16x32_bf16 v[126:129], v[148:151], v[196:199], v[126:129]
	v_mfma_f32_16x16x32_bf16 v[122:125], v[160:163], v[196:199], v[122:125]
	v_mfma_f32_16x16x32_bf16 v[110:113], v[148:151], v[204:207], v[110:113]
	v_mfma_f32_16x16x32_bf16 v[106:109], v[160:163], v[204:207], v[106:109]
	v_mfma_f32_16x16x32_bf16 v[94:97], v[148:151], v[212:215], v[94:97]
	v_mfma_f32_16x16x32_bf16 v[90:93], v[160:163], v[212:215], v[90:93]
	v_mfma_f32_16x16x32_bf16 v[78:81], v[148:151], v[220:223], v[78:81]
	v_mfma_f32_16x16x32_bf16 v[74:77], v[160:163], v[220:223], v[74:77]
	v_mfma_f32_16x16x32_bf16 v[118:121], v[172:175], v[192:195], v[118:121]
	v_mfma_f32_16x16x32_bf16 v[114:117], v[184:187], v[192:195], v[114:117]
	v_mfma_f32_16x16x32_bf16 v[102:105], v[172:175], v[200:203], v[102:105]
	v_mfma_f32_16x16x32_bf16 v[98:101], v[184:187], v[200:203], v[98:101]
	v_mfma_f32_16x16x32_bf16 v[86:89], v[172:175], v[208:211], v[86:89]
	v_mfma_f32_16x16x32_bf16 v[82:85], v[184:187], v[208:211], v[82:85]
	v_mfma_f32_16x16x32_bf16 v[70:73], v[172:175], v[216:219], v[70:73]
	v_mfma_f32_16x16x32_bf16 v[66:69], v[184:187], v[216:219], v[66:69]
	v_mfma_f32_16x16x32_bf16 v[118:121], v[180:183], v[196:199], v[118:121]
	v_mfma_f32_16x16x32_bf16 v[114:117], v[188:191], v[196:199], v[114:117]
	v_mfma_f32_16x16x32_bf16 v[102:105], v[180:183], v[204:207], v[102:105]
	v_mfma_f32_16x16x32_bf16 v[98:101], v[188:191], v[204:207], v[98:101]
	v_mfma_f32_16x16x32_bf16 v[86:89], v[180:183], v[212:215], v[86:89]
	v_mfma_f32_16x16x32_bf16 v[82:85], v[188:191], v[212:215], v[82:85]
	v_mfma_f32_16x16x32_bf16 v[70:73], v[180:183], v[220:223], v[70:73]
	v_mfma_f32_16x16x32_bf16 v[66:69], v[188:191], v[220:223], v[66:69]
	s_barrier
; #define PG8_STAGE(bufoff, gbase, voff) do { _Pragma("unroll") for (int _i = 0; _i < 2; ++_i) \
;         __builtin_amdgcn_global_load_lds((const unsigned*)((const char*)(gbase) + (voff)[_i]), (PG8_LAS unsigned*)(lds + (bufoff) + ldsw + _i * 8192), 16, 0, 0); } while (0)
; #define PG8_LDA(dst, b, h) do { _Pragma("unroll") for (int m = 0; m < 4; ++m) _Pragma("unroll") for (int k = 0; k < 2; ++k) dst[m][k] = *(const PG8_LAS bf16x8*)(lds + PG8_SA(b, h) + aoff + m * 2048 + k * 1024); } while (0)
; #define PG8_LDB(dst, b, h) do { _Pragma("unroll") for (int n = 0; n < 2; ++n) _Pragma("unroll") for (int k = 0; k < 2; ++k) dst[n][k] = *(const PG8_LAS bf16x8*)(lds + PG8_SB(b, h) + boff + n * 2048 + k * 1024); } while (0)
; #define PG8_MMA(ai, bj, At, Bt) do { __builtin_amdgcn_s_setprio(1); _Pragma("unroll") for (int m = 0; m < 4; ++m) _Pragma("unroll") for (int n = 0; n < 2; ++n) _Pragma("unroll") for (int k = 0; k < 2; ++k) \
;         acc[ai][bj][m][n] = __builtin_amdgcn_mfma_f32_16x16x32_bf16(Bt[n][k], At[m][k], acc[ai][bj][m][n], 0, 0, 0); __builtin_amdgcn_s_setprio(0); } while (0)
; #define PG8_WAIT_V(n) asm volatile("s_waitcnt vmcnt(" #n ")" ::: "memory")
; #define PG8_WAIT_L(n) asm volatile("s_waitcnt lgkmcnt(" #n ")" ::: "memory")
; #define PG8_BAR __builtin_amdgcn_s_barrier()
; #define PG8_SCHED __builtin_amdgcn_sched_barrier(0)
;     ...
;         for (int t = 0; t < nt; t += 2) {
;             const bool last = (t == nt - 2);
;             const char* a1 = cA + (size_t)(t + 1) * kstep;
;             const char* a2 = last ? nA : cA + (size_t)(t + 2) * kstep; const char* b2 = last ? nB : cB + (size_t)(t + 2) * kstep;
;             const char* a3 = a2 + kstep; const char* b3 = b2 + kstep;
;             if (last && has_next) S.a_ready(nxt);
;             if constexpr (SP2) {
;             PG8_LDB(B0, 0, 0); PG8_LDB(B1, 0, 1); PG8_SCHED; PG8_LDA(At, 0, 0); PG8_STAGE(PG8_SA(1, 1), a1 + hstepA, voffA);
;             PG8_WAIT_V(8); PG8_WAIT_L(0); PG8_BAR; PG8_MMA(0, 0, At, B0); PG8_MMA(0, 1, At, B1); PG8_BAR; PG8_SCHED;
;     ...
;             PG8_LDA(At, 1, 1); PG8_STAGE(PG8_SB(1, 0), b3, voffB); PG8_STAGE(PG8_SB(1, 1), b3 + hstepB, voffB); PG8_STAGE(PG8_SA(1, 0), a3, voffA);
;             PG8_WAIT_V(8); PG8_WAIT_L(0); PG8_BAR; PG8_MMA(1, 0, At, B0); PG8_MMA(1, 1, At, B1); PG8_BAR; PG8_SCHED;
	s_add_i32 s8, s25, s0
	v_lshl_add_u64 v[164:165], v[164:165], 0, s[62:63]
	s_mov_b32 m0, s8
	ds_read_b128 v[192:195], v179 offset:49152
	ds_read_b128 v[196:199], v179 offset:50176
	ds_read_b128 v[200:203], v179 offset:51200
	ds_read_b128 v[204:207], v179 offset:52224
	ds_read_b128 v[208:211], v179 offset:53248
	ds_read_b128 v[212:215], v179 offset:54272
	ds_read_b128 v[216:219], v179 offset:55296
	ds_read_b128 v[220:223], v179 offset:56320
	global_load_lds_dwordx4 v[164:165], off
	v_lshl_add_u64 v[164:165], v[168:169], 0, s[62:63]
	s_add_i32 m0, s8, 0x2000
	s_add_i32 s8, s27, s0
	global_load_lds_dwordx4 v[164:165], off
	v_lshl_add_u64 v[164:165], v[170:171], 0, s[62:63]
	s_mov_b32 m0, s8
	s_nop 0
	global_load_lds_dwordx4 v[164:165], off
	v_lshl_add_u64 v[164:165], v[176:177], 0, s[62:63]
	s_add_i32 m0, s8, 0x2000
	s_nop 0
	global_load_lds_dwordx4 v[164:165], off
	v_lshl_add_u64 v[164:165], v[224:225], 0, s[62:63]
	s_mov_b32 m0, s16
	s_nop 0
	global_load_lds_dwordx4 v[164:165], off
	v_lshl_add_u64 v[164:165], v[226:227], 0, s[62:63]
	s_mov_b32 m0, s17
	s_nop 0
	global_load_lds_dwordx4 v[164:165], off
	s_waitcnt vmcnt(8)
	s_waitcnt lgkmcnt(0)
	s_barrier
	s_waitcnt lgkmcnt(0)
	v_mfma_f32_16x16x32_bf16 v[62:65], v[144:147], v[192:195], v[62:65]
	v_mfma_f32_16x16x32_bf16 v[58:61], v[154:157], v[192:195], v[58:61]
	v_mfma_f32_16x16x32_bf16 v[46:49], v[144:147], v[200:203], v[46:49]
	v_mfma_f32_16x16x32_bf16 v[42:45], v[154:157], v[200:203], v[42:45]
	v_mfma_f32_16x16x32_bf16 v[30:33], v[144:147], v[208:211], v[30:33]
	v_mfma_f32_16x16x32_bf16 v[26:29], v[154:157], v[208:211], v[26:29]
	v_mfma_f32_16x16x32_bf16 v[14:17], v[144:147], v[216:219], v[14:17]
	v_mfma_f32_16x16x32_bf16 v[10:13], v[154:157], v[216:219], v[10:13]
	v_mfma_f32_16x16x32_bf16 v[62:65], v[148:151], v[196:199], v[62:65]
	v_mfma_f32_16x16x32_bf16 v[58:61], v[160:163], v[196:199], v[58:61]
	v_mfma_f32_16x16x32_bf16 v[46:49], v[148:151], v[204:207], v[46:49]
	v_mfma_f32_16x16x32_bf16 v[42:45], v[160:163], v[204:207], v[42:45]
	v_mfma_f32_16x16x32_bf16 v[30:33], v[148:151], v[212:215], v[30:33]
	v_mfma_f32_16x16x32_bf16 v[26:29], v[160:163], v[212:215], v[26:29]
	v_mfma_f32_16x16x32_bf16 v[14:17], v[148:151], v[220:223], v[14:17]
	v_mfma_f32_16x16x32_bf16 v[10:13], v[160:163], v[220:223], v[10:13]
	v_mfma_f32_16x16x32_bf16 v[54:57], v[172:175], v[192:195], v[54:57]
	v_mfma_f32_16x16x32_bf16 v[50:53], v[184:187], v[192:195], v[50:53]
	v_mfma_f32_16x16x32_bf16 v[38:41], v[172:175], v[200:203], v[38:41]
	v_mfma_f32_16x16x32_bf16 v[34:37], v[184:187], v[200:203], v[34:37]
	v_mfma_f32_16x16x32_bf16 v[22:25], v[172:175], v[208:211], v[22:25]
	v_mfma_f32_16x16x32_bf16 v[18:21], v[184:187], v[208:211], v[18:21]
	v_mfma_f32_16x16x32_bf16 v[6:9], v[172:175], v[216:219], v[6:9]
	v_mfma_f32_16x16x32_bf16 v[2:5], v[184:187], v[216:219], v[2:5]
	v_mfma_f32_16x16x32_bf16 v[54:57], v[180:183], v[196:199], v[54:57]
	v_mfma_f32_16x16x32_bf16 v[50:53], v[188:191], v[196:199], v[50:53]
	v_mfma_f32_16x16x32_bf16 v[38:41], v[180:183], v[204:207], v[38:41]
	v_mfma_f32_16x16x32_bf16 v[34:37], v[188:191], v[204:207], v[34:37]
	v_mfma_f32_16x16x32_bf16 v[22:25], v[180:183], v[212:215], v[22:25]
	v_mfma_f32_16x16x32_bf16 v[18:21], v[188:191], v[212:215], v[18:21]
	v_mfma_f32_16x16x32_bf16 v[6:9], v[180:183], v[220:223], v[6:9]
	v_mfma_f32_16x16x32_bf16 v[2:5], v[188:191], v[220:223], v[2:5]
	s_barrier
	s_add_u32 s22, s22, 0x100
	s_addc_u32 s23, s23, 0
	s_add_u32 s6, s6, 0x100
	s_addc_u32 s7, s7, 0
	s_cmp_ge_i32 s24, s14
	s_mov_b32 s8, s24
	s_cbranch_scc1 .LBB0_130
.LBB0_129:
	s_add_i32 s24, s8, 2
	s_add_u32 s25, s6, 0xfffc0080
	s_addc_u32 s9, s7, -1
	s_add_i32 s27, 0, 0x10000
	s_cmp_eq_u32 s18, s8
	s_cselect_b32 s9, s10, s9
	s_cselect_b32 s8, s11, s25
	v_add_u32_e32 v152, s27, v159
	s_cselect_b32 s35, s93, s23
	s_cselect_b32 s34, s92, s22
	s_add_i32 s25, 0, 0x14000
	ds_read_b128 v[144:147], v152
	ds_read_b128 v[148:151], v152 offset:1024
	ds_read_b128 v[154:157], v152 offset:2048
	ds_read_b128 v[160:163], v152 offset:3072
	v_add_u32_e32 v152, s25, v159
	ds_read_b128 v[172:175], v152
	ds_read_b128 v[180:183], v152 offset:1024
	ds_read_b128 v[184:187], v152 offset:2048
	ds_read_b128 v[188:191], v152 offset:3072
	v_lshl_add_u64 v[164:165], s[6:7], 0, v[142:143]
	s_add_i32 m0, s2, 0xc000
	ds_read_b128 v[192:195], v179
	ds_read_b128 v[196:199], v179 offset:1024
	ds_read_b128 v[200:203], v179 offset:2048
	ds_read_b128 v[204:207], v179 offset:3072
	ds_read_b128 v[208:211], v179 offset:4096
	ds_read_b128 v[212:215], v179 offset:5120
	ds_read_b128 v[216:219], v179 offset:6144
	ds_read_b128 v[220:223], v179 offset:7168
	global_load_lds_dwordx4 v[164:165], off
	v_lshl_add_u64 v[164:165], s[6:7], 0, v[140:141]
	s_add_i32 m0, s2, 0xe000
	s_nop 0
	global_load_lds_dwordx4 v[164:165], off
	s_waitcnt vmcnt(8)
	s_waitcnt lgkmcnt(0)
	s_barrier
; #define PG8_STAGE(bufoff, gbase, voff) do { _Pragma("unroll") for (int _i = 0; _i < 2; ++_i) \
;         __builtin_amdgcn_global_load_lds((const unsigned*)((const char*)(gbase) + (voff)[_i]), (PG8_LAS unsigned*)(lds + (bufoff) + ldsw + _i * 8192), 16, 0, 0); } while (0)
; #define PG8_LDA(dst, b, h) do { _Pragma("unroll") for (int m = 0; m < 4; ++m) _Pragma("unroll") for (int k = 0; k < 2; ++k) dst[m][k] = *(const PG8_LAS bf16x8*)(lds + PG8_SA(b, h) + aoff + m * 2048 + k * 1024); } while (0)
; #define PG8_MMA(ai, bj, At, Bt) do { __builtin_amdgcn_s_setprio(1); _Pragma("unroll") for (int m = 0; m < 4; ++m) _Pragma("unroll") for (int n = 0; n < 2; ++n) _Pragma("unroll") for (int k = 0; k < 2; ++k) \
;         acc[ai][bj][m][n] = __builtin_amdgcn_mfma_f32_16x16x32_bf16(Bt[n][k], At[m][k], acc[ai][bj][m][n], 0, 0, 0); __builtin_amdgcn_s_setprio(0); } while (0)
; #define PG8_WAIT_V(n) asm volatile("s_waitcnt vmcnt(" #n ")" ::: "memory")
; #define PG8_WAIT_L(n) asm volatile("s_waitcnt lgkmcnt(" #n ")" ::: "memory")
; #define PG8_BAR __builtin_amdgcn_s_barrier()
; #define PG8_SCHED __builtin_amdgcn_sched_barrier(0)
;     ...
;             PG8_WAIT_V(8); PG8_WAIT_L(0); PG8_BAR; PG8_MMA(0, 0, At, B0); PG8_MMA(0, 1, At, B1); PG8_BAR; PG8_SCHED;
;             PG8_LDA(At, 0, 1); PG8_STAGE(PG8_SB(0, 0), b2, voffB); PG8_STAGE(PG8_SB(0, 1), b2 + hstepB, voffB); PG8_STAGE(PG8_SA(0, 0), a2, voffA);
;             PG8_WAIT_V(8); PG8_WAIT_L(0); PG8_BAR; PG8_MMA(1, 0, At, B0); PG8_MMA(1, 1, At, B1); PG8_BAR; PG8_SCHED;
	s_waitcnt lgkmcnt(0)
	v_mfma_f32_16x16x32_bf16 v[126:129], v[144:147], v[192:195], v[126:129]
	v_mfma_f32_16x16x32_bf16 v[122:125], v[154:157], v[192:195], v[122:125]
	v_mfma_f32_16x16x32_bf16 v[110:113], v[144:147], v[200:203], v[110:113]
	v_mfma_f32_16x16x32_bf16 v[106:109], v[154:157], v[200:203], v[106:109]
	v_mfma_f32_16x16x32_bf16 v[94:97], v[144:147], v[208:211], v[94:97]
	v_mfma_f32_16x16x32_bf16 v[90:93], v[154:157], v[208:211], v[90:93]
	v_mfma_f32_16x16x32_bf16 v[78:81], v[144:147], v[216:219], v[78:81]
	v_mfma_f32_16x16x32_bf16 v[74:77], v[154:157], v[216:219], v[74:77]
	v_mfma_f32_16x16x32_bf16 v[126:129], v[148:151], v[196:199], v[126:129]
	v_mfma_f32_16x16x32_bf16 v[122:125], v[160:163], v[196:199], v[122:125]
	v_mfma_f32_16x16x32_bf16 v[110:113], v[148:151], v[204:207], v[110:113]
	v_mfma_f32_16x16x32_bf16 v[106:109], v[160:163], v[204:207], v[106:109]
	v_mfma_f32_16x16x32_bf16 v[94:97], v[148:151], v[212:215], v[94:97]
	v_mfma_f32_16x16x32_bf16 v[90:93], v[160:163], v[212:215], v[90:93]
	v_mfma_f32_16x16x32_bf16 v[78:81], v[148:151], v[220:223], v[78:81]
	v_mfma_f32_16x16x32_bf16 v[74:77], v[160:163], v[220:223], v[74:77]
	v_mfma_f32_16x16x32_bf16 v[118:121], v[172:175], v[192:195], v[118:121]
	v_mfma_f32_16x16x32_bf16 v[114:117], v[184:187], v[192:195], v[114:117]
	v_mfma_f32_16x16x32_bf16 v[102:105], v[172:175], v[200:203], v[102:105]
	v_mfma_f32_16x16x32_bf16 v[98:101], v[184:187], v[200:203], v[98:101]
	v_mfma_f32_16x16x32_bf16 v[86:89], v[172:175], v[208:211], v[86:89]
	v_mfma_f32_16x16x32_bf16 v[82:85], v[184:187], v[208:211], v[82:85]
	v_mfma_f32_16x16x32_bf16 v[70:73], v[172:175], v[216:219], v[70:73]
	v_mfma_f32_16x16x32_bf16 v[66:69], v[184:187], v[216:219], v[66:69]
	v_mfma_f32_16x16x32_bf16 v[118:121], v[180:183], v[196:199], v[118:121]
	v_mfma_f32_16x16x32_bf16 v[114:117], v[188:191], v[196:199], v[114:117]
	v_mfma_f32_16x16x32_bf16 v[102:105], v[180:183], v[204:207], v[102:105]
	v_mfma_f32_16x16x32_bf16 v[98:101], v[188:191], v[204:207], v[98:101]
	v_mfma_f32_16x16x32_bf16 v[86:89], v[180:183], v[212:215], v[86:89]
	v_mfma_f32_16x16x32_bf16 v[82:85], v[188:191], v[212:215], v[82:85]
	v_mfma_f32_16x16x32_bf16 v[70:73], v[180:183], v[220:223], v[70:73]
	v_mfma_f32_16x16x32_bf16 v[66:69], v[188:191], v[220:223], v[66:69]
	s_barrier
	s_add_i32 s27, s27, s0
	v_lshl_add_u64 v[164:165], s[34:35], 0, v[134:135]
	s_mov_b32 m0, s27
	ds_read_b128 v[192:195], v179 offset:16384
	ds_read_b128 v[196:199], v179 offset:17408
	ds_read_b128 v[200:203], v179 offset:18432
	ds_read_b128 v[204:207], v179 offset:19456
	ds_read_b128 v[208:211], v179 offset:20480
	ds_read_b128 v[212:215], v179 offset:21504
	ds_read_b128 v[216:219], v179 offset:22528
	ds_read_b128 v[220:223], v179 offset:23552
	global_load_lds_dwordx4 v[164:165], off
	s_add_i32 m0, s27, 0x2000
	v_lshl_add_u64 v[168:169], s[34:35], 0, v[130:131]
	s_add_u32 s34, s34, s42
	s_addc_u32 s35, s35, s43
	s_add_i32 s25, s25, s0
	global_load_lds_dwordx4 v[168:169], off
	v_lshl_add_u64 v[170:171], s[34:35], 0, v[134:135]
	s_mov_b32 m0, s25
	v_lshl_add_u64 v[176:177], s[34:35], 0, v[130:131]
	global_load_lds_dwordx4 v[170:171], off
	s_add_i32 m0, s25, 0x2000
	v_lshl_add_u64 v[224:225], s[8:9], 0, v[136:137]
	global_load_lds_dwordx4 v[176:177], off
	s_mov_b32 m0, s2
	v_lshl_add_u64 v[226:227], s[8:9], 0, v[132:133]
	global_load_lds_dwordx4 v[224:225], off
	s_mov_b32 m0, s3
	s_nop 0
	global_load_lds_dwordx4 v[226:227], off
	s_waitcnt vmcnt(8)
	s_waitcnt lgkmcnt(0)
	s_barrier
	s_waitcnt lgkmcnt(0)
	v_mfma_f32_16x16x32_bf16 v[62:65], v[144:147], v[192:195], v[62:65]
	v_mfma_f32_16x16x32_bf16 v[58:61], v[154:157], v[192:195], v[58:61]
	v_mfma_f32_16x16x32_bf16 v[46:49], v[144:147], v[200:203], v[46:49]
	v_mfma_f32_16x16x32_bf16 v[42:45], v[154:157], v[200:203], v[42:45]
	v_mfma_f32_16x16x32_bf16 v[30:33], v[144:147], v[208:211], v[30:33]
	v_mfma_f32_16x16x32_bf16 v[26:29], v[154:157], v[208:211], v[26:29]
	v_mfma_f32_16x16x32_bf16 v[14:17], v[144:147], v[216:219], v[14:17]
	v_mfma_f32_16x16x32_bf16 v[10:13], v[154:157], v[216:219], v[10:13]
	v_mfma_f32_16x16x32_bf16 v[62:65], v[148:151], v[196:199], v[62:65]
	v_mfma_f32_16x16x32_bf16 v[58:61], v[160:163], v[196:199], v[58:61]
	v_mfma_f32_16x16x32_bf16 v[46:49], v[148:151], v[204:207], v[46:49]
	v_mfma_f32_16x16x32_bf16 v[42:45], v[160:163], v[204:207], v[42:45]
	v_mfma_f32_16x16x32_bf16 v[30:33], v[148:151], v[212:215], v[30:33]
	v_mfma_f32_16x16x32_bf16 v[26:29], v[160:163], v[212:215], v[26:29]
	v_mfma_f32_16x16x32_bf16 v[14:17], v[148:151], v[220:223], v[14:17]
	v_mfma_f32_16x16x32_bf16 v[10:13], v[160:163], v[220:223], v[10:13]
	v_mfma_f32_16x16x32_bf16 v[54:57], v[172:175], v[192:195], v[54:57]
	v_mfma_f32_16x16x32_bf16 v[50:53], v[184:187], v[192:195], v[50:53]
	v_mfma_f32_16x16x32_bf16 v[38:41], v[172:175], v[200:203], v[38:41]
	v_mfma_f32_16x16x32_bf16 v[34:37], v[184:187], v[200:203], v[34:37]
	v_mfma_f32_16x16x32_bf16 v[22:25], v[172:175], v[208:211], v[22:25]
	v_mfma_f32_16x16x32_bf16 v[18:21], v[184:187], v[208:211], v[18:21]
	v_mfma_f32_16x16x32_bf16 v[6:9], v[172:175], v[216:219], v[6:9]
	v_mfma_f32_16x16x32_bf16 v[2:5], v[184:187], v[216:219], v[2:5]
	v_mfma_f32_16x16x32_bf16 v[54:57], v[180:183], v[196:199], v[54:57]
	v_mfma_f32_16x16x32_bf16 v[50:53], v[188:191], v[196:199], v[50:53]
	v_mfma_f32_16x16x32_bf16 v[38:41], v[180:183], v[204:207], v[38:41]
	v_mfma_f32_16x16x32_bf16 v[34:37], v[188:191], v[204:207], v[34:37]
	v_mfma_f32_16x16x32_bf16 v[22:25], v[180:183], v[212:215], v[22:25]
	v_mfma_f32_16x16x32_bf16 v[18:21], v[188:191], v[212:215], v[18:21]
	v_mfma_f32_16x16x32_bf16 v[6:9], v[180:183], v[220:223], v[6:9]
	v_mfma_f32_16x16x32_bf16 v[2:5], v[188:191], v[220:223], v[2:5]
	s_barrier
; #define PG8_STAGE(bufoff, gbase, voff) do { _Pragma("unroll") for (int _i = 0; _i < 2; ++_i) \
;         __builtin_amdgcn_global_load_lds((const unsigned*)((const char*)(gbase) + (voff)[_i]), (PG8_LAS unsigned*)(lds + (bufoff) + ldsw + _i * 8192), 16, 0, 0); } while (0)
; #define PG8_LDA(dst, b, h) do { _Pragma("unroll") for (int m = 0; m < 4; ++m) _Pragma("unroll") for (int k = 0; k < 2; ++k) dst[m][k] = *(const PG8_LAS bf16x8*)(lds + PG8_SA(b, h) + aoff + m * 2048 + k * 1024); } while (0)
; #define PG8_LDB(dst, b, h) do { _Pragma("unroll") for (int n = 0; n < 2; ++n) _Pragma("unroll") for (int k = 0; k < 2; ++k) dst[n][k] = *(const PG8_LAS bf16x8*)(lds + PG8_SB(b, h) + boff + n * 2048 + k * 1024); } while (0)
; #define PG8_MMA(ai, bj, At, Bt) do { __builtin_amdgcn_s_setprio(1); _Pragma("unroll") for (int m = 0; m < 4; ++m) _Pragma("unroll") for (int n = 0; n < 2; ++n) _Pragma("unroll") for (int k = 0; k < 2; ++k) \
;         acc[ai][bj][m][n] = __builtin_amdgcn_mfma_f32_16x16x32_bf16(Bt[n][k], At[m][k], acc[ai][bj][m][n], 0, 0, 0); __builtin_amdgcn_s_setprio(0); } while (0)
; #define PG8_WAIT_V(n) asm volatile("s_waitcnt vmcnt(" #n ")" ::: "memory")
; #define PG8_WAIT_L(n) asm volatile("s_waitcnt lgkmcnt(" #n ")" ::: "memory")
; #define PG8_BAR __builtin_amdgcn_s_barrier()
; #define PG8_SCHED __builtin_amdgcn_sched_barrier(0)
;     ...
;             PG8_LDB(B0, 1, 0); PG8_LDB(B1, 1, 1); PG8_SCHED; PG8_LDA(At, 1, 0); PG8_STAGE(PG8_SA(0, 1), a2 + hstepA, voffA);
;             PG8_WAIT_V(8); PG8_WAIT_L(0); PG8_BAR; PG8_MMA(0, 0, At, B0); PG8_MMA(0, 1, At, B1); PG8_BAR; PG8_SCHED;
;             PG8_LDA(At, 1, 1); PG8_STAGE(PG8_SB(1, 0), b3, voffB); PG8_STAGE(PG8_SB(1, 1), b3 + hstepB, voffB); PG8_STAGE(PG8_SA(1, 0), a3, voffA);
;             PG8_WAIT_V(8); PG8_WAIT_L(0); PG8_BAR; PG8_MMA(1, 0, At, B0); PG8_MMA(1, 1, At, B1); PG8_BAR; PG8_SCHED;
	s_add_i32 s25, 0, 0x18000
	v_add_u32_e32 v152, s25, v159
	s_add_i32 s27, 0, 0x1c000
	ds_read_b128 v[144:147], v152
	ds_read_b128 v[148:151], v152 offset:1024
	ds_read_b128 v[154:157], v152 offset:2048
	ds_read_b128 v[160:163], v152 offset:3072
	v_add_u32_e32 v152, s27, v159
	ds_read_b128 v[172:175], v152
	ds_read_b128 v[180:183], v152 offset:1024
	ds_read_b128 v[184:187], v152 offset:2048
	ds_read_b128 v[188:191], v152 offset:3072
	s_add_u32 s8, s8, 0x40000
	s_addc_u32 s9, s9, 0
	s_mov_b32 m0, s12
	v_lshl_add_u64 v[228:229], s[8:9], 0, v[136:137]
	ds_read_b128 v[192:195], v179 offset:32768
	ds_read_b128 v[196:199], v179 offset:33792
	ds_read_b128 v[200:203], v179 offset:34816
	ds_read_b128 v[204:207], v179 offset:35840
	ds_read_b128 v[208:211], v179 offset:36864
	ds_read_b128 v[212:215], v179 offset:37888
	ds_read_b128 v[216:219], v179 offset:38912
	ds_read_b128 v[220:223], v179 offset:39936
	global_load_lds_dwordx4 v[228:229], off
	v_lshl_add_u64 v[228:229], s[8:9], 0, v[132:133]
	s_mov_b32 m0, s13
	s_nop 0
	global_load_lds_dwordx4 v[228:229], off
	s_waitcnt vmcnt(8)
	s_waitcnt lgkmcnt(0)
	s_barrier
	s_waitcnt lgkmcnt(0)
	v_mfma_f32_16x16x32_bf16 v[126:129], v[144:147], v[192:195], v[126:129]
	v_mfma_f32_16x16x32_bf16 v[122:125], v[154:157], v[192:195], v[122:125]
	v_mfma_f32_16x16x32_bf16 v[110:113], v[144:147], v[200:203], v[110:113]
	v_mfma_f32_16x16x32_bf16 v[106:109], v[154:157], v[200:203], v[106:109]
	v_mfma_f32_16x16x32_bf16 v[94:97], v[144:147], v[208:211], v[94:97]
	v_mfma_f32_16x16x32_bf16 v[90:93], v[154:157], v[208:211], v[90:93]
	v_mfma_f32_16x16x32_bf16 v[78:81], v[144:147], v[216:219], v[78:81]
	v_mfma_f32_16x16x32_bf16 v[74:77], v[154:157], v[216:219], v[74:77]
	v_mfma_f32_16x16x32_bf16 v[126:129], v[148:151], v[196:199], v[126:129]
	v_mfma_f32_16x16x32_bf16 v[122:125], v[160:163], v[196:199], v[122:125]
	v_mfma_f32_16x16x32_bf16 v[110:113], v[148:151], v[204:207], v[110:113]
	v_mfma_f32_16x16x32_bf16 v[106:109], v[160:163], v[204:207], v[106:109]
	v_mfma_f32_16x16x32_bf16 v[94:97], v[148:151], v[212:215], v[94:97]
	v_mfma_f32_16x16x32_bf16 v[90:93], v[160:163], v[212:215], v[90:93]
	v_mfma_f32_16x16x32_bf16 v[78:81], v[148:151], v[220:223], v[78:81]
	v_mfma_f32_16x16x32_bf16 v[74:77], v[160:163], v[220:223], v[74:77]
	v_mfma_f32_16x16x32_bf16 v[118:121], v[172:175], v[192:195], v[118:121]
	v_mfma_f32_16x16x32_bf16 v[114:117], v[184:187], v[192:195], v[114:117]
	v_mfma_f32_16x16x32_bf16 v[102:105], v[172:175], v[200:203], v[102:105]
	v_mfma_f32_16x16x32_bf16 v[98:101], v[184:187], v[200:203], v[98:101]
	v_mfma_f32_16x16x32_bf16 v[86:89], v[172:175], v[208:211], v[86:89]
	v_mfma_f32_16x16x32_bf16 v[82:85], v[184:187], v[208:211], v[82:85]
	v_mfma_f32_16x16x32_bf16 v[70:73], v[172:175], v[216:219], v[70:73]
	v_mfma_f32_16x16x32_bf16 v[66:69], v[184:187], v[216:219], v[66:69]
	v_mfma_f32_16x16x32_bf16 v[118:121], v[180:183], v[196:199], v[118:121]
	v_mfma_f32_16x16x32_bf16 v[114:117], v[188:191], v[196:199], v[114:117]
	v_mfma_f32_16x16x32_bf16 v[102:105], v[180:183], v[204:207], v[102:105]
	v_mfma_f32_16x16x32_bf16 v[98:101], v[188:191], v[204:207], v[98:101]
	v_mfma_f32_16x16x32_bf16 v[86:89], v[180:183], v[212:215], v[86:89]
	v_mfma_f32_16x16x32_bf16 v[82:85], v[188:191], v[212:215], v[82:85]
	v_mfma_f32_16x16x32_bf16 v[70:73], v[180:183], v[220:223], v[70:73]
	v_mfma_f32_16x16x32_bf16 v[66:69], v[188:191], v[220:223], v[66:69]
	s_barrier
	s_add_i32 s8, s25, s0
	v_lshl_add_u64 v[164:165], v[164:165], 0, s[62:63]
	s_mov_b32 m0, s8
	ds_read_b128 v[192:195], v179 offset:49152
	ds_read_b128 v[196:199], v179 offset:50176
	ds_read_b128 v[200:203], v179 offset:51200
	ds_read_b128 v[204:207], v179 offset:52224
	ds_read_b128 v[208:211], v179 offset:53248
	ds_read_b128 v[212:215], v179 offset:54272
	ds_read_b128 v[216:219], v179 offset:55296
	ds_read_b128 v[220:223], v179 offset:56320
	global_load_lds_dwordx4 v[164:165], off
	v_lshl_add_u64 v[164:165], v[168:169], 0, s[62:63]
	s_add_i32 m0, s8, 0x2000
	s_add_i32 s8, s27, s0
	global_load_lds_dwordx4 v[164:165], off
	v_lshl_add_u64 v[164:165], v[170:171], 0, s[62:63]
	s_mov_b32 m0, s8
	s_nop 0
	global_load_lds_dwordx4 v[164:165], off
	v_lshl_add_u64 v[164:165], v[176:177], 0, s[62:63]
	s_add_i32 m0, s8, 0x2000
	s_nop 0
	global_load_lds_dwordx4 v[164:165], off
	v_lshl_add_u64 v[164:165], v[224:225], 0, s[62:63]
	s_mov_b32 m0, s16
	s_nop 0
	global_load_lds_dwordx4 v[164:165], off
	v_lshl_add_u64 v[164:165], v[226:227], 0, s[62:63]
	s_mov_b32 m0, s17
	s_nop 0
	global_load_lds_dwordx4 v[164:165], off
	s_waitcnt vmcnt(8)
	s_waitcnt lgkmcnt(0)
	s_barrier
	s_waitcnt lgkmcnt(0)
	v_mfma_f32_16x16x32_bf16 v[62:65], v[144:147], v[192:195], v[62:65]
	v_mfma_f32_16x16x32_bf16 v[58:61], v[154:157], v[192:195], v[58:61]
	v_mfma_f32_16x16x32_bf16 v[46:49], v[144:147], v[200:203], v[46:49]
	v_mfma_f32_16x16x32_bf16 v[42:45], v[154:157], v[200:203], v[42:45]
	v_mfma_f32_16x16x32_bf16 v[30:33], v[144:147], v[208:211], v[30:33]
	v_mfma_f32_16x16x32_bf16 v[26:29], v[154:157], v[208:211], v[26:29]
	v_mfma_f32_16x16x32_bf16 v[14:17], v[144:147], v[216:219], v[14:17]
	v_mfma_f32_16x16x32_bf16 v[10:13], v[154:157], v[216:219], v[10:13]
	v_mfma_f32_16x16x32_bf16 v[62:65], v[148:151], v[196:199], v[62:65]
	v_mfma_f32_16x16x32_bf16 v[58:61], v[160:163], v[196:199], v[58:61]
	v_mfma_f32_16x16x32_bf16 v[46:49], v[148:151], v[204:207], v[46:49]
	v_mfma_f32_16x16x32_bf16 v[42:45], v[160:163], v[204:207], v[42:45]
	v_mfma_f32_16x16x32_bf16 v[30:33], v[148:151], v[212:215], v[30:33]
	v_mfma_f32_16x16x32_bf16 v[26:29], v[160:163], v[212:215], v[26:29]
	v_mfma_f32_16x16x32_bf16 v[14:17], v[148:151], v[220:223], v[14:17]
	v_mfma_f32_16x16x32_bf16 v[10:13], v[160:163], v[220:223], v[10:13]
	v_mfma_f32_16x16x32_bf16 v[54:57], v[172:175], v[192:195], v[54:57]
	v_mfma_f32_16x16x32_bf16 v[50:53], v[184:187], v[192:195], v[50:53]
	v_mfma_f32_16x16x32_bf16 v[38:41], v[172:175], v[200:203], v[38:41]
	v_mfma_f32_16x16x32_bf16 v[34:37], v[184:187], v[200:203], v[34:37]
	v_mfma_f32_16x16x32_bf16 v[22:25], v[172:175], v[208:211], v[22:25]
	v_mfma_f32_16x16x32_bf16 v[18:21], v[184:187], v[208:211], v[18:21]
	v_mfma_f32_16x16x32_bf16 v[6:9], v[172:175], v[216:219], v[6:9]
	v_mfma_f32_16x16x32_bf16 v[2:5], v[184:187], v[216:219], v[2:5]
	v_mfma_f32_16x16x32_bf16 v[54:57], v[180:183], v[196:199], v[54:57]
	v_mfma_f32_16x16x32_bf16 v[50:53], v[188:191], v[196:199], v[50:53]
	v_mfma_f32_16x16x32_bf16 v[38:41], v[180:183], v[204:207], v[38:41]
	v_mfma_f32_16x16x32_bf16 v[34:37], v[188:191], v[204:207], v[34:37]
	v_mfma_f32_16x16x32_bf16 v[22:25], v[180:183], v[212:215], v[22:25]
	v_mfma_f32_16x16x32_bf16 v[18:21], v[188:191], v[212:215], v[18:21]
	v_mfma_f32_16x16x32_bf16 v[6:9], v[180:183], v[220:223], v[6:9]
	v_mfma_f32_16x16x32_bf16 v[2:5], v[188:191], v[220:223], v[2:5]
	s_barrier
	s_add_u32 s22, s22, 0x100
	s_addc_u32 s23, s23, 0
	s_add_u32 s6, s6, 0x100
	s_addc_u32 s7, s7, 0
	s_cmp_ge_i32 s24, s14
	s_mov_b32 s8, s24
	s_cbranch_scc0 .LBB0_129

; #define PG8_STAGE(bufoff, gbase, voff) do { _Pragma("unroll") for (int _i = 0; _i < 2; ++_i) \
;         __builtin_amdgcn_global_load_lds((const unsigned*)((const char*)(gbase) + (voff)[_i]), (PG8_LAS unsigned*)(lds + (bufoff) + ldsw + _i * 8192), 16, 0, 0); } while (0)
; #define PG8_LDA(dst, b, h) do { _Pragma("unroll") for (int m = 0; m < 4; ++m) _Pragma("unroll") for (int k = 0; k < 2; ++k) dst[m][k] = *(const PG8_LAS bf16x8*)(lds + PG8_SA(b, h) + aoff + m * 2048 + k * 1024); } while (0)
; #define PG8_LDB(dst, b, h) do { _Pragma("unroll") for (int n = 0; n < 2; ++n) _Pragma("unroll") for (int k = 0; k < 2; ++k) dst[n][k] = *(const PG8_LAS bf16x8*)(lds + PG8_SB(b, h) + boff + n * 2048 + k * 1024); } while (0)
; #define PG8_MMA(ai, bj, At, Bt) do { __builtin_amdgcn_s_setprio(1); _Pragma("unroll") for (int m = 0; m < 4; ++m) _Pragma("unroll") for (int n = 0; n < 2; ++n) _Pragma("unroll") for (int k = 0; k < 2; ++k) \
;         acc[ai][bj][m][n] = __builtin_amdgcn_mfma_f32_16x16x32_bf16(Bt[n][k], At[m][k], acc[ai][bj][m][n], 0, 0, 0); __builtin_amdgcn_s_setprio(0); } while (0)
; #define PG8_WAIT_V(n) asm volatile("s_waitcnt vmcnt(" #n ")" ::: "memory")
; #define PG8_WAIT_L(n) asm volatile("s_waitcnt lgkmcnt(" #n ")" ::: "memory")
; #define PG8_BAR __builtin_amdgcn_s_barrier()
; #define PG8_SCHED __builtin_amdgcn_sched_barrier(0)
;     ...
;         for (int t = 0; t < nt; t += 2) {
;             const bool last = (t == nt - 2);
;             const char* a1 = cA + (size_t)(t + 1) * kstep;
;             const char* a2 = last ? nA : cA + (size_t)(t + 2) * kstep; const char* b2 = last ? nB : cB + (size_t)(t + 2) * kstep;
;             const char* a3 = a2 + kstep; const char* b3 = b2 + kstep;
;             if (last && has_next) S.a_ready(nxt);
;             if constexpr (SP2) {
;             PG8_LDB(B0, 0, 0); PG8_LDB(B1, 0, 1); PG8_SCHED; PG8_LDA(At, 0, 0); PG8_STAGE(PG8_SA(1, 1), a1 + hstepA, voffA);
;             PG8_WAIT_V(8); PG8_WAIT_L(0); PG8_BAR; PG8_MMA(0, 0, At, B0); PG8_MMA(0, 1, At, B1); PG8_BAR; PG8_SCHED;
;             PG8_LDA(At, 0, 1); PG8_STAGE(PG8_SB(0, 0), b2, voffB); PG8_STAGE(PG8_SB(0, 1), b2 + hstepB, voffB); PG8_STAGE(PG8_SA(0, 0), a2, voffA);
.LBB0_286:
	v_readlane_b32 s10, v255, 5
	v_readlane_b32 s11, v255, 6
	s_andn2_b64 vcc, exec, s[10:11]
	s_cbranch_vccnz .LBB0_289
	s_add_u32 s10, s6, 0x100
	s_addc_u32 s11, s7, 0
	s_add_u32 s6, s8, 0x80
	s_addc_u32 s7, s9, 0
	s_mov_b32 s8, 0
	s_add_i32 s12, s8, 2
	s_add_u32 s13, s6, 0x80
	s_addc_u32 s9, s7, 0
	s_add_i32 s16, 0, 0x10000
	s_cmp_eq_u32 s69, s8
	s_cselect_b32 s9, s41, s9
	s_cselect_b32 s8, s40, s13
	s_cselect_b32 s15, s5, s11
	s_cselect_b32 s14, s4, s10
	s_add_i32 s13, 0, 0x14000
	v_add_u32_e32 v142, s16, v249
	v_add_u32_e32 v158, s13, v249
	ds_read_b128 v[130:133], v142
	ds_read_b128 v[134:137], v142 offset:1024
	ds_read_b128 v[138:141], v142 offset:2048
	ds_read_b128 v[142:145], v142 offset:3072
	ds_read_b128 v[146:149], v158
	ds_read_b128 v[150:153], v158 offset:1024
	ds_read_b128 v[154:157], v158 offset:2048
	ds_read_b128 v[158:161], v158 offset:3072
	v_lshl_add_u64 v[212:213], s[6:7], 0, v[182:183]
	s_add_i32 m0, s27, 0xc000
	ds_read_b128 v[162:165], v251
	ds_read_b128 v[184:187], v251 offset:1024
	ds_read_b128 v[188:191], v251 offset:2048
	ds_read_b128 v[192:195], v251 offset:3072
	ds_read_b128 v[196:199], v251 offset:4096
	ds_read_b128 v[200:203], v251 offset:5120
	ds_read_b128 v[204:207], v251 offset:6144
	ds_read_b128 v[208:211], v251 offset:7168
	global_load_lds_dwordx4 v[212:213], off
	v_lshl_add_u64 v[212:213], s[6:7], 0, v[180:181]
	s_add_i32 m0, s27, 0xe000
	s_nop 0
	global_load_lds_dwordx4 v[212:213], off
	s_waitcnt vmcnt(8)
	s_waitcnt lgkmcnt(0)
	s_barrier
	s_waitcnt lgkmcnt(0)
	v_mfma_f32_16x16x32_bf16 v[122:125], v[130:133], v[162:165], 0
	v_mfma_f32_16x16x32_bf16 v[118:121], v[138:141], v[162:165], 0
	v_mfma_f32_16x16x32_bf16 v[110:113], v[130:133], v[188:191], 0
	v_mfma_f32_16x16x32_bf16 v[102:105], v[138:141], v[188:191], 0
	v_mfma_f32_16x16x32_bf16 v[94:97], v[130:133], v[196:199], 0
	v_mfma_f32_16x16x32_bf16 v[86:89], v[138:141], v[196:199], 0
	v_mfma_f32_16x16x32_bf16 v[78:81], v[130:133], v[204:207], 0
	v_mfma_f32_16x16x32_bf16 v[70:73], v[138:141], v[204:207], 0
	v_mfma_f32_16x16x32_bf16 v[122:125], v[134:137], v[184:187], v[122:125]
	v_mfma_f32_16x16x32_bf16 v[118:121], v[142:145], v[184:187], v[118:121]
	v_mfma_f32_16x16x32_bf16 v[110:113], v[134:137], v[192:195], v[110:113]
	v_mfma_f32_16x16x32_bf16 v[102:105], v[142:145], v[192:195], v[102:105]
	v_mfma_f32_16x16x32_bf16 v[94:97], v[134:137], v[200:203], v[94:97]
	v_mfma_f32_16x16x32_bf16 v[86:89], v[142:145], v[200:203], v[86:89]
	v_mfma_f32_16x16x32_bf16 v[78:81], v[134:137], v[208:211], v[78:81]
	v_mfma_f32_16x16x32_bf16 v[70:73], v[142:145], v[208:211], v[70:73]
	v_mfma_f32_16x16x32_bf16 v[126:129], v[146:149], v[162:165], 0
	v_mfma_f32_16x16x32_bf16 v[114:117], v[154:157], v[162:165], 0
	v_mfma_f32_16x16x32_bf16 v[106:109], v[146:149], v[188:191], 0
	v_mfma_f32_16x16x32_bf16 v[98:101], v[154:157], v[188:191], 0
	v_mfma_f32_16x16x32_bf16 v[90:93], v[146:149], v[196:199], 0
	v_mfma_f32_16x16x32_bf16 v[82:85], v[154:157], v[196:199], 0
	v_mfma_f32_16x16x32_bf16 v[74:77], v[146:149], v[204:207], 0
	v_mfma_f32_16x16x32_bf16 v[66:69], v[154:157], v[204:207], 0
	v_mfma_f32_16x16x32_bf16 v[126:129], v[150:153], v[184:187], v[126:129]
	v_mfma_f32_16x16x32_bf16 v[114:117], v[158:161], v[184:187], v[114:117]
	v_mfma_f32_16x16x32_bf16 v[106:109], v[150:153], v[192:195], v[106:109]
	v_mfma_f32_16x16x32_bf16 v[98:101], v[158:161], v[192:195], v[98:101]
	v_mfma_f32_16x16x32_bf16 v[90:93], v[150:153], v[200:203], v[90:93]
	v_mfma_f32_16x16x32_bf16 v[82:85], v[158:161], v[200:203], v[82:85]
	v_mfma_f32_16x16x32_bf16 v[74:77], v[150:153], v[208:211], v[74:77]
	v_mfma_f32_16x16x32_bf16 v[66:69], v[158:161], v[208:211], v[66:69]
	s_barrier
	s_add_i32 s16, s16, s0
	v_lshl_add_u64 v[212:213], s[14:15], 0, v[166:167]
	s_mov_b32 m0, s16
	ds_read_b128 v[162:165], v251 offset:16384
	ds_read_b128 v[184:187], v251 offset:17408
	ds_read_b128 v[188:191], v251 offset:18432
	ds_read_b128 v[192:195], v251 offset:19456
	ds_read_b128 v[196:199], v251 offset:20480
	ds_read_b128 v[200:203], v251 offset:21504
	ds_read_b128 v[204:207], v251 offset:22528
	ds_read_b128 v[208:211], v251 offset:23552
	global_load_lds_dwordx4 v[212:213], off
	s_add_i32 m0, s16, 0x2000
	v_lshl_add_u64 v[214:215], s[14:15], 0, v[172:173]
	s_add_u32 s14, s14, s58
	s_addc_u32 s15, s15, s59
	s_add_i32 s13, s13, s0
	global_load_lds_dwordx4 v[214:215], off
	v_lshl_add_u64 v[216:217], s[14:15], 0, v[166:167]
	s_mov_b32 m0, s13
	v_lshl_add_u64 v[218:219], s[14:15], 0, v[172:173]
	global_load_lds_dwordx4 v[216:217], off
	s_add_i32 m0, s13, 0x2000
	v_lshl_add_u64 v[220:221], s[8:9], 0, v[176:177]
	global_load_lds_dwordx4 v[218:219], off
	s_mov_b32 m0, s27
	v_lshl_add_u64 v[222:223], s[8:9], 0, v[174:175]
	global_load_lds_dwordx4 v[220:221], off
	s_mov_b32 m0, s31
	s_nop 0
	global_load_lds_dwordx4 v[222:223], off
	s_waitcnt vmcnt(8)
	s_waitcnt lgkmcnt(0)
	s_barrier
; #define PG8_STAGE(bufoff, gbase, voff) do { _Pragma("unroll") for (int _i = 0; _i < 2; ++_i) \
;         __builtin_amdgcn_global_load_lds((const unsigned*)((const char*)(gbase) + (voff)[_i]), (PG8_LAS unsigned*)(lds + (bufoff) + ldsw + _i * 8192), 16, 0, 0); } while (0)
; #define PG8_LDA(dst, b, h) do { _Pragma("unroll") for (int m = 0; m < 4; ++m) _Pragma("unroll") for (int k = 0; k < 2; ++k) dst[m][k] = *(const PG8_LAS bf16x8*)(lds + PG8_SA(b, h) + aoff + m * 2048 + k * 1024); } while (0)
; #define PG8_LDB(dst, b, h) do { _Pragma("unroll") for (int n = 0; n < 2; ++n) _Pragma("unroll") for (int k = 0; k < 2; ++k) dst[n][k] = *(const PG8_LAS bf16x8*)(lds + PG8_SB(b, h) + boff + n * 2048 + k * 1024); } while (0)
; #define PG8_MMA(ai, bj, At, Bt) do { __builtin_amdgcn_s_setprio(1); _Pragma("unroll") for (int m = 0; m < 4; ++m) _Pragma("unroll") for (int n = 0; n < 2; ++n) _Pragma("unroll") for (int k = 0; k < 2; ++k) \
;         acc[ai][bj][m][n] = __builtin_amdgcn_mfma_f32_16x16x32_bf16(Bt[n][k], At[m][k], acc[ai][bj][m][n], 0, 0, 0); __builtin_amdgcn_s_setprio(0); } while (0)
; #define PG8_WAIT_V(n) asm volatile("s_waitcnt vmcnt(" #n ")" ::: "memory")
; #define PG8_WAIT_L(n) asm volatile("s_waitcnt lgkmcnt(" #n ")" ::: "memory")
; #define PG8_BAR __builtin_amdgcn_s_barrier()
; #define PG8_SCHED __builtin_amdgcn_sched_barrier(0)
;     ...
;             PG8_WAIT_V(8); PG8_WAIT_L(0); PG8_BAR; PG8_MMA(1, 0, At, B0); PG8_MMA(1, 1, At, B1); PG8_BAR; PG8_SCHED;
;             PG8_LDB(B0, 1, 0); PG8_LDB(B1, 1, 1); PG8_SCHED; PG8_LDA(At, 1, 0); PG8_STAGE(PG8_SA(0, 1), a2 + hstepA, voffA);
;             PG8_WAIT_V(8); PG8_WAIT_L(0); PG8_BAR; PG8_MMA(0, 0, At, B0); PG8_MMA(0, 1, At, B1); PG8_BAR; PG8_SCHED;
	s_waitcnt lgkmcnt(0)
	v_mfma_f32_16x16x32_bf16 v[62:65], v[130:133], v[162:165], 0
	v_mfma_f32_16x16x32_bf16 v[54:57], v[138:141], v[162:165], 0
	v_mfma_f32_16x16x32_bf16 v[46:49], v[130:133], v[188:191], 0
	v_mfma_f32_16x16x32_bf16 v[38:41], v[138:141], v[188:191], 0
	v_mfma_f32_16x16x32_bf16 v[30:33], v[130:133], v[196:199], 0
	v_mfma_f32_16x16x32_bf16 v[22:25], v[138:141], v[196:199], 0
	v_mfma_f32_16x16x32_bf16 v[14:17], v[130:133], v[204:207], 0
	v_mfma_f32_16x16x32_bf16 v[6:9], v[138:141], v[204:207], 0
	v_mfma_f32_16x16x32_bf16 v[62:65], v[134:137], v[184:187], v[62:65]
	v_mfma_f32_16x16x32_bf16 v[54:57], v[142:145], v[184:187], v[54:57]
	v_mfma_f32_16x16x32_bf16 v[46:49], v[134:137], v[192:195], v[46:49]
	v_mfma_f32_16x16x32_bf16 v[38:41], v[142:145], v[192:195], v[38:41]
	v_mfma_f32_16x16x32_bf16 v[30:33], v[134:137], v[200:203], v[30:33]
	v_mfma_f32_16x16x32_bf16 v[22:25], v[142:145], v[200:203], v[22:25]
	v_mfma_f32_16x16x32_bf16 v[14:17], v[134:137], v[208:211], v[14:17]
	v_mfma_f32_16x16x32_bf16 v[6:9], v[142:145], v[208:211], v[6:9]
	v_mfma_f32_16x16x32_bf16 v[58:61], v[146:149], v[162:165], 0
	v_mfma_f32_16x16x32_bf16 v[50:53], v[154:157], v[162:165], 0
	v_mfma_f32_16x16x32_bf16 v[42:45], v[146:149], v[188:191], 0
	v_mfma_f32_16x16x32_bf16 v[34:37], v[154:157], v[188:191], 0
	v_mfma_f32_16x16x32_bf16 v[26:29], v[146:149], v[196:199], 0
	v_mfma_f32_16x16x32_bf16 v[18:21], v[154:157], v[196:199], 0
	v_mfma_f32_16x16x32_bf16 v[10:13], v[146:149], v[204:207], 0
	v_mfma_f32_16x16x32_bf16 v[2:5], v[154:157], v[204:207], 0
	v_mfma_f32_16x16x32_bf16 v[58:61], v[150:153], v[184:187], v[58:61]
	v_mfma_f32_16x16x32_bf16 v[50:53], v[158:161], v[184:187], v[50:53]
	v_mfma_f32_16x16x32_bf16 v[42:45], v[150:153], v[192:195], v[42:45]
	v_mfma_f32_16x16x32_bf16 v[34:37], v[158:161], v[192:195], v[34:37]
	v_mfma_f32_16x16x32_bf16 v[26:29], v[150:153], v[200:203], v[26:29]
	v_mfma_f32_16x16x32_bf16 v[18:21], v[158:161], v[200:203], v[18:21]
	v_mfma_f32_16x16x32_bf16 v[10:13], v[150:153], v[208:211], v[10:13]
	v_mfma_f32_16x16x32_bf16 v[2:5], v[158:161], v[208:211], v[2:5]
	s_barrier
	s_add_i32 s13, 0, 0x18000
	s_add_i32 s14, 0, 0x1c000
	v_add_u32_e32 v142, s13, v249
	v_add_u32_e32 v158, s14, v249
	ds_read_b128 v[130:133], v142
	ds_read_b128 v[134:137], v142 offset:1024
	ds_read_b128 v[138:141], v142 offset:2048
	ds_read_b128 v[142:145], v142 offset:3072
	ds_read_b128 v[146:149], v158
	ds_read_b128 v[150:153], v158 offset:1024
	ds_read_b128 v[154:157], v158 offset:2048
	ds_read_b128 v[158:161], v158 offset:3072
	s_add_u32 s8, s8, s58
	s_addc_u32 s9, s9, s59
	s_mov_b32 m0, s47
	v_lshl_add_u64 v[224:225], s[8:9], 0, v[176:177]
	ds_read_b128 v[162:165], v251 offset:32768
	ds_read_b128 v[184:187], v251 offset:33792
	ds_read_b128 v[188:191], v251 offset:34816
	ds_read_b128 v[192:195], v251 offset:35840
	ds_read_b128 v[196:199], v251 offset:36864
	ds_read_b128 v[200:203], v251 offset:37888
	ds_read_b128 v[204:207], v251 offset:38912
	ds_read_b128 v[208:211], v251 offset:39936
	global_load_lds_dwordx4 v[224:225], off
	v_lshl_add_u64 v[224:225], s[8:9], 0, v[174:175]
	s_mov_b32 m0, s49
	s_nop 0
	global_load_lds_dwordx4 v[224:225], off
	s_waitcnt vmcnt(8)
	s_waitcnt lgkmcnt(0)
	s_barrier
	s_waitcnt lgkmcnt(0)
	v_mfma_f32_16x16x32_bf16 v[122:125], v[130:133], v[162:165], v[122:125]
	v_mfma_f32_16x16x32_bf16 v[118:121], v[138:141], v[162:165], v[118:121]
	v_mfma_f32_16x16x32_bf16 v[110:113], v[130:133], v[188:191], v[110:113]
	v_mfma_f32_16x16x32_bf16 v[102:105], v[138:141], v[188:191], v[102:105]
	v_mfma_f32_16x16x32_bf16 v[94:97], v[130:133], v[196:199], v[94:97]
	v_mfma_f32_16x16x32_bf16 v[86:89], v[138:141], v[196:199], v[86:89]
	v_mfma_f32_16x16x32_bf16 v[78:81], v[130:133], v[204:207], v[78:81]
	v_mfma_f32_16x16x32_bf16 v[70:73], v[138:141], v[204:207], v[70:73]
	v_mfma_f32_16x16x32_bf16 v[122:125], v[134:137], v[184:187], v[122:125]
	v_mfma_f32_16x16x32_bf16 v[118:121], v[142:145], v[184:187], v[118:121]
	v_mfma_f32_16x16x32_bf16 v[110:113], v[134:137], v[192:195], v[110:113]
	v_mfma_f32_16x16x32_bf16 v[102:105], v[142:145], v[192:195], v[102:105]
	v_mfma_f32_16x16x32_bf16 v[94:97], v[134:137], v[200:203], v[94:97]
	v_mfma_f32_16x16x32_bf16 v[86:89], v[142:145], v[200:203], v[86:89]
	v_mfma_f32_16x16x32_bf16 v[78:81], v[134:137], v[208:211], v[78:81]
	v_mfma_f32_16x16x32_bf16 v[70:73], v[142:145], v[208:211], v[70:73]
	v_mfma_f32_16x16x32_bf16 v[126:129], v[146:149], v[162:165], v[126:129]
	v_mfma_f32_16x16x32_bf16 v[114:117], v[154:157], v[162:165], v[114:117]
	v_mfma_f32_16x16x32_bf16 v[106:109], v[146:149], v[188:191], v[106:109]
	v_mfma_f32_16x16x32_bf16 v[98:101], v[154:157], v[188:191], v[98:101]
	v_mfma_f32_16x16x32_bf16 v[90:93], v[146:149], v[196:199], v[90:93]
	v_mfma_f32_16x16x32_bf16 v[82:85], v[154:157], v[196:199], v[82:85]
	v_mfma_f32_16x16x32_bf16 v[74:77], v[146:149], v[204:207], v[74:77]
	v_mfma_f32_16x16x32_bf16 v[66:69], v[154:157], v[204:207], v[66:69]
	v_mfma_f32_16x16x32_bf16 v[126:129], v[150:153], v[184:187], v[126:129]
	v_mfma_f32_16x16x32_bf16 v[114:117], v[158:161], v[184:187], v[114:117]
	v_mfma_f32_16x16x32_bf16 v[106:109], v[150:153], v[192:195], v[106:109]
	v_mfma_f32_16x16x32_bf16 v[98:101], v[158:161], v[192:195], v[98:101]
	v_mfma_f32_16x16x32_bf16 v[90:93], v[150:153], v[200:203], v[90:93]
	v_mfma_f32_16x16x32_bf16 v[82:85], v[158:161], v[200:203], v[82:85]
	v_mfma_f32_16x16x32_bf16 v[74:77], v[150:153], v[208:211], v[74:77]
	v_mfma_f32_16x16x32_bf16 v[66:69], v[158:161], v[208:211], v[66:69]
	s_barrier
; #define PG8_STAGE(bufoff, gbase, voff) do { _Pragma("unroll") for (int _i = 0; _i < 2; ++_i) \
;         __builtin_amdgcn_global_load_lds((const unsigned*)((const char*)(gbase) + (voff)[_i]), (PG8_LAS unsigned*)(lds + (bufoff) + ldsw + _i * 8192), 16, 0, 0); } while (0)
; #define PG8_LDA(dst, b, h) do { _Pragma("unroll") for (int m = 0; m < 4; ++m) _Pragma("unroll") for (int k = 0; k < 2; ++k) dst[m][k] = *(const PG8_LAS bf16x8*)(lds + PG8_SA(b, h) + aoff + m * 2048 + k * 1024); } while (0)
; #define PG8_LDB(dst, b, h) do { _Pragma("unroll") for (int n = 0; n < 2; ++n) _Pragma("unroll") for (int k = 0; k < 2; ++k) dst[n][k] = *(const PG8_LAS bf16x8*)(lds + PG8_SB(b, h) + boff + n * 2048 + k * 1024); } while (0)
; #define PG8_MMA(ai, bj, At, Bt) do { __builtin_amdgcn_s_setprio(1); _Pragma("unroll") for (int m = 0; m < 4; ++m) _Pragma("unroll") for (int n = 0; n < 2; ++n) _Pragma("unroll") for (int k = 0; k < 2; ++k) \
;         acc[ai][bj][m][n] = __builtin_amdgcn_mfma_f32_16x16x32_bf16(Bt[n][k], At[m][k], acc[ai][bj][m][n], 0, 0, 0); __builtin_amdgcn_s_setprio(0); } while (0)
; #define PG8_WAIT_V(n) asm volatile("s_waitcnt vmcnt(" #n ")" ::: "memory")
; #define PG8_WAIT_L(n) asm volatile("s_waitcnt lgkmcnt(" #n ")" ::: "memory")
; #define PG8_BAR __builtin_amdgcn_s_barrier()
; #define PG8_SCHED __builtin_amdgcn_sched_barrier(0)
;     ...
;         for (int t = 0; t < nt; t += 2) {
;             const bool last = (t == nt - 2);
;             const char* a1 = cA + (size_t)(t + 1) * kstep;
;             const char* a2 = last ? nA : cA + (size_t)(t + 2) * kstep; const char* b2 = last ? nB : cB + (size_t)(t + 2) * kstep;
;             const char* a3 = a2 + kstep; const char* b3 = b2 + kstep;
;             if (last && has_next) S.a_ready(nxt);
;             if constexpr (SP2) {
;             PG8_LDB(B0, 0, 0); PG8_LDB(B1, 0, 1); PG8_SCHED; PG8_LDA(At, 0, 0); PG8_STAGE(PG8_SA(1, 1), a1 + hstepA, voffA);
;             PG8_WAIT_V(8); PG8_WAIT_L(0); PG8_BAR; PG8_MMA(0, 0, At, B0); PG8_MMA(0, 1, At, B1); PG8_BAR; PG8_SCHED;
;     ...
;             PG8_LDA(At, 1, 1); PG8_STAGE(PG8_SB(1, 0), b3, voffB); PG8_STAGE(PG8_SB(1, 1), b3 + hstepB, voffB); PG8_STAGE(PG8_SA(1, 0), a3, voffA);
;             PG8_WAIT_V(8); PG8_WAIT_L(0); PG8_BAR; PG8_MMA(1, 0, At, B0); PG8_MMA(1, 1, At, B1); PG8_BAR; PG8_SCHED;
	s_add_i32 s8, s13, s0
	v_lshl_add_u64 v[212:213], v[212:213], 0, s[62:63]
	s_mov_b32 m0, s8
	ds_read_b128 v[162:165], v251 offset:49152
	ds_read_b128 v[184:187], v251 offset:50176
	ds_read_b128 v[188:191], v251 offset:51200
	ds_read_b128 v[192:195], v251 offset:52224
	ds_read_b128 v[196:199], v251 offset:53248
	ds_read_b128 v[200:203], v251 offset:54272
	ds_read_b128 v[204:207], v251 offset:55296
	ds_read_b128 v[208:211], v251 offset:56320
	global_load_lds_dwordx4 v[212:213], off
	v_lshl_add_u64 v[212:213], v[214:215], 0, s[62:63]
	s_add_i32 m0, s8, 0x2000
	s_add_i32 s8, s14, s0
	global_load_lds_dwordx4 v[212:213], off
	v_lshl_add_u64 v[212:213], v[216:217], 0, s[62:63]
	s_mov_b32 m0, s8
	s_nop 0
	global_load_lds_dwordx4 v[212:213], off
	v_lshl_add_u64 v[212:213], v[218:219], 0, s[62:63]
	s_add_i32 m0, s8, 0x2000
	s_nop 0
	global_load_lds_dwordx4 v[212:213], off
	v_lshl_add_u64 v[212:213], v[220:221], 0, s[62:63]
	s_mov_b32 m0, s51
	s_nop 0
	global_load_lds_dwordx4 v[212:213], off
	v_lshl_add_u64 v[212:213], v[222:223], 0, s[62:63]
	s_mov_b32 m0, s53
	s_nop 0
	global_load_lds_dwordx4 v[212:213], off
	s_waitcnt vmcnt(8)
	s_waitcnt lgkmcnt(0)
	s_barrier
	s_waitcnt lgkmcnt(0)
	v_mfma_f32_16x16x32_bf16 v[62:65], v[130:133], v[162:165], v[62:65]
	v_mfma_f32_16x16x32_bf16 v[54:57], v[138:141], v[162:165], v[54:57]
	v_mfma_f32_16x16x32_bf16 v[46:49], v[130:133], v[188:191], v[46:49]
	v_mfma_f32_16x16x32_bf16 v[38:41], v[138:141], v[188:191], v[38:41]
	v_mfma_f32_16x16x32_bf16 v[30:33], v[130:133], v[196:199], v[30:33]
	v_mfma_f32_16x16x32_bf16 v[22:25], v[138:141], v[196:199], v[22:25]
	v_mfma_f32_16x16x32_bf16 v[14:17], v[130:133], v[204:207], v[14:17]
	v_mfma_f32_16x16x32_bf16 v[6:9], v[138:141], v[204:207], v[6:9]
	v_mfma_f32_16x16x32_bf16 v[62:65], v[134:137], v[184:187], v[62:65]
	v_mfma_f32_16x16x32_bf16 v[54:57], v[142:145], v[184:187], v[54:57]
	v_mfma_f32_16x16x32_bf16 v[46:49], v[134:137], v[192:195], v[46:49]
	v_mfma_f32_16x16x32_bf16 v[38:41], v[142:145], v[192:195], v[38:41]
	v_mfma_f32_16x16x32_bf16 v[30:33], v[134:137], v[200:203], v[30:33]
	v_mfma_f32_16x16x32_bf16 v[22:25], v[142:145], v[200:203], v[22:25]
	v_mfma_f32_16x16x32_bf16 v[14:17], v[134:137], v[208:211], v[14:17]
	v_mfma_f32_16x16x32_bf16 v[6:9], v[142:145], v[208:211], v[6:9]
	v_mfma_f32_16x16x32_bf16 v[58:61], v[146:149], v[162:165], v[58:61]
	v_mfma_f32_16x16x32_bf16 v[50:53], v[154:157], v[162:165], v[50:53]
	v_mfma_f32_16x16x32_bf16 v[42:45], v[146:149], v[188:191], v[42:45]
	v_mfma_f32_16x16x32_bf16 v[34:37], v[154:157], v[188:191], v[34:37]
	v_mfma_f32_16x16x32_bf16 v[26:29], v[146:149], v[196:199], v[26:29]
	v_mfma_f32_16x16x32_bf16 v[18:21], v[154:157], v[196:199], v[18:21]
	v_mfma_f32_16x16x32_bf16 v[10:13], v[146:149], v[204:207], v[10:13]
	v_mfma_f32_16x16x32_bf16 v[2:5], v[154:157], v[204:207], v[2:5]
	v_mfma_f32_16x16x32_bf16 v[58:61], v[150:153], v[184:187], v[58:61]
	v_mfma_f32_16x16x32_bf16 v[50:53], v[158:161], v[184:187], v[50:53]
	v_mfma_f32_16x16x32_bf16 v[42:45], v[150:153], v[192:195], v[42:45]
	v_mfma_f32_16x16x32_bf16 v[34:37], v[158:161], v[192:195], v[34:37]
	v_mfma_f32_16x16x32_bf16 v[26:29], v[150:153], v[200:203], v[26:29]
	v_mfma_f32_16x16x32_bf16 v[18:21], v[158:161], v[200:203], v[18:21]
	v_mfma_f32_16x16x32_bf16 v[10:13], v[150:153], v[208:211], v[10:13]
	v_mfma_f32_16x16x32_bf16 v[2:5], v[158:161], v[208:211], v[2:5]
	s_barrier
	s_add_u32 s10, s10, 0x100
	s_addc_u32 s11, s11, 0
	s_add_u32 s6, s6, 0x100
	s_addc_u32 s7, s7, 0
	s_cmp_ge_i32 s12, s55
	s_mov_b32 s8, s12
	s_cbranch_scc1 .LBB0_289
.LBB0_288:
	s_add_i32 s12, s8, 2
	s_add_u32 s13, s6, 0x80
	s_addc_u32 s9, s7, 0
	s_add_i32 s16, 0, 0x10000
	s_cmp_eq_u32 s69, s8
	s_cselect_b32 s9, s41, s9
	s_cselect_b32 s8, s40, s13
	s_cselect_b32 s15, s5, s11
	s_cselect_b32 s14, s4, s10
	s_add_i32 s13, 0, 0x14000
	v_add_u32_e32 v142, s16, v249
	v_add_u32_e32 v158, s13, v249
	ds_read_b128 v[130:133], v142
	ds_read_b128 v[134:137], v142 offset:1024
	ds_read_b128 v[138:141], v142 offset:2048
	ds_read_b128 v[142:145], v142 offset:3072
	ds_read_b128 v[146:149], v158
	ds_read_b128 v[150:153], v158 offset:1024
	ds_read_b128 v[154:157], v158 offset:2048
	ds_read_b128 v[158:161], v158 offset:3072
	v_lshl_add_u64 v[212:213], s[6:7], 0, v[182:183]
	s_add_i32 m0, s27, 0xc000
	ds_read_b128 v[162:165], v251
	ds_read_b128 v[184:187], v251 offset:1024
	ds_read_b128 v[188:191], v251 offset:2048
	ds_read_b128 v[192:195], v251 offset:3072
	ds_read_b128 v[196:199], v251 offset:4096
	ds_read_b128 v[200:203], v251 offset:5120
	ds_read_b128 v[204:207], v251 offset:6144
	ds_read_b128 v[208:211], v251 offset:7168
	global_load_lds_dwordx4 v[212:213], off
	v_lshl_add_u64 v[212:213], s[6:7], 0, v[180:181]
	s_add_i32 m0, s27, 0xe000
	s_nop 0
	global_load_lds_dwordx4 v[212:213], off
	s_waitcnt vmcnt(8)
	s_waitcnt lgkmcnt(0)
	s_barrier
; #define PG8_STAGE(bufoff, gbase, voff) do { _Pragma("unroll") for (int _i = 0; _i < 2; ++_i) \
;         __builtin_amdgcn_global_load_lds((const unsigned*)((const char*)(gbase) + (voff)[_i]), (PG8_LAS unsigned*)(lds + (bufoff) + ldsw + _i * 8192), 16, 0, 0); } while (0)
; #define PG8_LDA(dst, b, h) do { _Pragma("unroll") for (int m = 0; m < 4; ++m) _Pragma("unroll") for (int k = 0; k < 2; ++k) dst[m][k] = *(const PG8_LAS bf16x8*)(lds + PG8_SA(b, h) + aoff + m * 2048 + k * 1024); } while (0)
; #define PG8_MMA(ai, bj, At, Bt) do { __builtin_amdgcn_s_setprio(1); _Pragma("unroll") for (int m = 0; m < 4; ++m) _Pragma("unroll") for (int n = 0; n < 2; ++n) _Pragma("unroll") for (int k = 0; k < 2; ++k) \
;         acc[ai][bj][m][n] = __builtin_amdgcn_mfma_f32_16x16x32_bf16(Bt[n][k], At[m][k], acc[ai][bj][m][n], 0, 0, 0); __builtin_amdgcn_s_setprio(0); } while (0)
; #define PG8_WAIT_V(n) asm volatile("s_waitcnt vmcnt(" #n ")" ::: "memory")
; #define PG8_WAIT_L(n) asm volatile("s_waitcnt lgkmcnt(" #n ")" ::: "memory")
; #define PG8_BAR __builtin_amdgcn_s_barrier()
; #define PG8_SCHED __builtin_amdgcn_sched_barrier(0)
;     ...
;             PG8_WAIT_V(8); PG8_WAIT_L(0); PG8_BAR; PG8_MMA(0, 0, At, B0); PG8_MMA(0, 1, At, B1); PG8_BAR; PG8_SCHED;
;             PG8_LDA(At, 0, 1); PG8_STAGE(PG8_SB(0, 0), b2, voffB); PG8_STAGE(PG8_SB(0, 1), b2 + hstepB, voffB); PG8_STAGE(PG8_SA(0, 0), a2, voffA);
;             PG8_WAIT_V(8); PG8_WAIT_L(0); PG8_BAR; PG8_MMA(1, 0, At, B0); PG8_MMA(1, 1, At, B1); PG8_BAR; PG8_SCHED;
	s_waitcnt lgkmcnt(0)
	v_mfma_f32_16x16x32_bf16 v[122:125], v[130:133], v[162:165], v[122:125]
	v_mfma_f32_16x16x32_bf16 v[118:121], v[138:141], v[162:165], v[118:121]
	v_mfma_f32_16x16x32_bf16 v[110:113], v[130:133], v[188:191], v[110:113]
	v_mfma_f32_16x16x32_bf16 v[102:105], v[138:141], v[188:191], v[102:105]
	v_mfma_f32_16x16x32_bf16 v[94:97], v[130:133], v[196:199], v[94:97]
	v_mfma_f32_16x16x32_bf16 v[86:89], v[138:141], v[196:199], v[86:89]
	v_mfma_f32_16x16x32_bf16 v[78:81], v[130:133], v[204:207], v[78:81]
	v_mfma_f32_16x16x32_bf16 v[70:73], v[138:141], v[204:207], v[70:73]
	v_mfma_f32_16x16x32_bf16 v[122:125], v[134:137], v[184:187], v[122:125]
	v_mfma_f32_16x16x32_bf16 v[118:121], v[142:145], v[184:187], v[118:121]
	v_mfma_f32_16x16x32_bf16 v[110:113], v[134:137], v[192:195], v[110:113]
	v_mfma_f32_16x16x32_bf16 v[102:105], v[142:145], v[192:195], v[102:105]
	v_mfma_f32_16x16x32_bf16 v[94:97], v[134:137], v[200:203], v[94:97]
	v_mfma_f32_16x16x32_bf16 v[86:89], v[142:145], v[200:203], v[86:89]
	v_mfma_f32_16x16x32_bf16 v[78:81], v[134:137], v[208:211], v[78:81]
	v_mfma_f32_16x16x32_bf16 v[70:73], v[142:145], v[208:211], v[70:73]
	v_mfma_f32_16x16x32_bf16 v[126:129], v[146:149], v[162:165], v[126:129]
	v_mfma_f32_16x16x32_bf16 v[114:117], v[154:157], v[162:165], v[114:117]
	v_mfma_f32_16x16x32_bf16 v[106:109], v[146:149], v[188:191], v[106:109]
	v_mfma_f32_16x16x32_bf16 v[98:101], v[154:157], v[188:191], v[98:101]
	v_mfma_f32_16x16x32_bf16 v[90:93], v[146:149], v[196:199], v[90:93]
	v_mfma_f32_16x16x32_bf16 v[82:85], v[154:157], v[196:199], v[82:85]
	v_mfma_f32_16x16x32_bf16 v[74:77], v[146:149], v[204:207], v[74:77]
	v_mfma_f32_16x16x32_bf16 v[66:69], v[154:157], v[204:207], v[66:69]
	v_mfma_f32_16x16x32_bf16 v[126:129], v[150:153], v[184:187], v[126:129]
	v_mfma_f32_16x16x32_bf16 v[114:117], v[158:161], v[184:187], v[114:117]
	v_mfma_f32_16x16x32_bf16 v[106:109], v[150:153], v[192:195], v[106:109]
	v_mfma_f32_16x16x32_bf16 v[98:101], v[158:161], v[192:195], v[98:101]
	v_mfma_f32_16x16x32_bf16 v[90:93], v[150:153], v[200:203], v[90:93]
	v_mfma_f32_16x16x32_bf16 v[82:85], v[158:161], v[200:203], v[82:85]
	v_mfma_f32_16x16x32_bf16 v[74:77], v[150:153], v[208:211], v[74:77]
	v_mfma_f32_16x16x32_bf16 v[66:69], v[158:161], v[208:211], v[66:69]
	s_barrier
	s_add_i32 s16, s16, s0
	v_lshl_add_u64 v[212:213], s[14:15], 0, v[166:167]
	s_mov_b32 m0, s16
	ds_read_b128 v[162:165], v251 offset:16384
	ds_read_b128 v[184:187], v251 offset:17408
	ds_read_b128 v[188:191], v251 offset:18432
	ds_read_b128 v[192:195], v251 offset:19456
	ds_read_b128 v[196:199], v251 offset:20480
	ds_read_b128 v[200:203], v251 offset:21504
	ds_read_b128 v[204:207], v251 offset:22528
	ds_read_b128 v[208:211], v251 offset:23552
	global_load_lds_dwordx4 v[212:213], off
	s_add_i32 m0, s16, 0x2000
	v_lshl_add_u64 v[214:215], s[14:15], 0, v[172:173]
	s_add_u32 s14, s14, s58
	s_addc_u32 s15, s15, s59
	s_add_i32 s13, s13, s0
	global_load_lds_dwordx4 v[214:215], off
	v_lshl_add_u64 v[216:217], s[14:15], 0, v[166:167]
	s_mov_b32 m0, s13
	v_lshl_add_u64 v[218:219], s[14:15], 0, v[172:173]
	global_load_lds_dwordx4 v[216:217], off
	s_add_i32 m0, s13, 0x2000
	v_lshl_add_u64 v[220:221], s[8:9], 0, v[176:177]
	global_load_lds_dwordx4 v[218:219], off
	s_mov_b32 m0, s27
	v_lshl_add_u64 v[222:223], s[8:9], 0, v[174:175]
	global_load_lds_dwordx4 v[220:221], off
	s_mov_b32 m0, s31
	s_nop 0
	global_load_lds_dwordx4 v[222:223], off
	s_waitcnt vmcnt(8)
	s_waitcnt lgkmcnt(0)
	s_barrier
	s_waitcnt lgkmcnt(0)
	v_mfma_f32_16x16x32_bf16 v[62:65], v[130:133], v[162:165], v[62:65]
	v_mfma_f32_16x16x32_bf16 v[54:57], v[138:141], v[162:165], v[54:57]
	v_mfma_f32_16x16x32_bf16 v[46:49], v[130:133], v[188:191], v[46:49]
	v_mfma_f32_16x16x32_bf16 v[38:41], v[138:141], v[188:191], v[38:41]
	v_mfma_f32_16x16x32_bf16 v[30:33], v[130:133], v[196:199], v[30:33]
	v_mfma_f32_16x16x32_bf16 v[22:25], v[138:141], v[196:199], v[22:25]
	v_mfma_f32_16x16x32_bf16 v[14:17], v[130:133], v[204:207], v[14:17]
	v_mfma_f32_16x16x32_bf16 v[6:9], v[138:141], v[204:207], v[6:9]
	v_mfma_f32_16x16x32_bf16 v[62:65], v[134:137], v[184:187], v[62:65]
	v_mfma_f32_16x16x32_bf16 v[54:57], v[142:145], v[184:187], v[54:57]
	v_mfma_f32_16x16x32_bf16 v[46:49], v[134:137], v[192:195], v[46:49]
	v_mfma_f32_16x16x32_bf16 v[38:41], v[142:145], v[192:195], v[38:41]
	v_mfma_f32_16x16x32_bf16 v[30:33], v[134:137], v[200:203], v[30:33]
	v_mfma_f32_16x16x32_bf16 v[22:25], v[142:145], v[200:203], v[22:25]
	v_mfma_f32_16x16x32_bf16 v[14:17], v[134:137], v[208:211], v[14:17]
	v_mfma_f32_16x16x32_bf16 v[6:9], v[142:145], v[208:211], v[6:9]
	v_mfma_f32_16x16x32_bf16 v[58:61], v[146:149], v[162:165], v[58:61]
	v_mfma_f32_16x16x32_bf16 v[50:53], v[154:157], v[162:165], v[50:53]
	v_mfma_f32_16x16x32_bf16 v[42:45], v[146:149], v[188:191], v[42:45]
	v_mfma_f32_16x16x32_bf16 v[34:37], v[154:157], v[188:191], v[34:37]
	v_mfma_f32_16x16x32_bf16 v[26:29], v[146:149], v[196:199], v[26:29]
	v_mfma_f32_16x16x32_bf16 v[18:21], v[154:157], v[196:199], v[18:21]
	v_mfma_f32_16x16x32_bf16 v[10:13], v[146:149], v[204:207], v[10:13]
	v_mfma_f32_16x16x32_bf16 v[2:5], v[154:157], v[204:207], v[2:5]
	v_mfma_f32_16x16x32_bf16 v[58:61], v[150:153], v[184:187], v[58:61]
	v_mfma_f32_16x16x32_bf16 v[50:53], v[158:161], v[184:187], v[50:53]
	v_mfma_f32_16x16x32_bf16 v[42:45], v[150:153], v[192:195], v[42:45]
	v_mfma_f32_16x16x32_bf16 v[34:37], v[158:161], v[192:195], v[34:37]
	v_mfma_f32_16x16x32_bf16 v[26:29], v[150:153], v[200:203], v[26:29]
	v_mfma_f32_16x16x32_bf16 v[18:21], v[158:161], v[200:203], v[18:21]
	v_mfma_f32_16x16x32_bf16 v[10:13], v[150:153], v[208:211], v[10:13]
	v_mfma_f32_16x16x32_bf16 v[2:5], v[158:161], v[208:211], v[2:5]
	s_barrier
; #define PG8_STAGE(bufoff, gbase, voff) do { _Pragma("unroll") for (int _i = 0; _i < 2; ++_i) \
;         __builtin_amdgcn_global_load_lds((const unsigned*)((const char*)(gbase) + (voff)[_i]), (PG8_LAS unsigned*)(lds + (bufoff) + ldsw + _i * 8192), 16, 0, 0); } while (0)
; #define PG8_LDA(dst, b, h) do { _Pragma("unroll") for (int m = 0; m < 4; ++m) _Pragma("unroll") for (int k = 0; k < 2; ++k) dst[m][k] = *(const PG8_LAS bf16x8*)(lds + PG8_SA(b, h) + aoff + m * 2048 + k * 1024); } while (0)
; #define PG8_LDB(dst, b, h) do { _Pragma("unroll") for (int n = 0; n < 2; ++n) _Pragma("unroll") for (int k = 0; k < 2; ++k) dst[n][k] = *(const PG8_LAS bf16x8*)(lds + PG8_SB(b, h) + boff + n * 2048 + k * 1024); } while (0)
; #define PG8_MMA(ai, bj, At, Bt) do { __builtin_amdgcn_s_setprio(1); _Pragma("unroll") for (int m = 0; m < 4; ++m) _Pragma("unroll") for (int n = 0; n < 2; ++n) _Pragma("unroll") for (int k = 0; k < 2; ++k) \
;         acc[ai][bj][m][n] = __builtin_amdgcn_mfma_f32_16x16x32_bf16(Bt[n][k], At[m][k], acc[ai][bj][m][n], 0, 0, 0); __builtin_amdgcn_s_setprio(0); } while (0)
; #define PG8_WAIT_V(n) asm volatile("s_waitcnt vmcnt(" #n ")" ::: "memory")
; #define PG8_WAIT_L(n) asm volatile("s_waitcnt lgkmcnt(" #n ")" ::: "memory")
; #define PG8_BAR __builtin_amdgcn_s_barrier()
; #define PG8_SCHED __builtin_amdgcn_sched_barrier(0)
;     ...
;             PG8_LDB(B0, 1, 0); PG8_LDB(B1, 1, 1); PG8_SCHED; PG8_LDA(At, 1, 0); PG8_STAGE(PG8_SA(0, 1), a2 + hstepA, voffA);
;             PG8_WAIT_V(8); PG8_WAIT_L(0); PG8_BAR; PG8_MMA(0, 0, At, B0); PG8_MMA(0, 1, At, B1); PG8_BAR; PG8_SCHED;
;             PG8_LDA(At, 1, 1); PG8_STAGE(PG8_SB(1, 0), b3, voffB); PG8_STAGE(PG8_SB(1, 1), b3 + hstepB, voffB); PG8_STAGE(PG8_SA(1, 0), a3, voffA);
;             PG8_WAIT_V(8); PG8_WAIT_L(0); PG8_BAR; PG8_MMA(1, 0, At, B0); PG8_MMA(1, 1, At, B1); PG8_BAR; PG8_SCHED;
	s_add_i32 s13, 0, 0x18000
	s_add_i32 s14, 0, 0x1c000
	v_add_u32_e32 v142, s13, v249
	v_add_u32_e32 v158, s14, v249
	ds_read_b128 v[130:133], v142
	ds_read_b128 v[134:137], v142 offset:1024
	ds_read_b128 v[138:141], v142 offset:2048
	ds_read_b128 v[142:145], v142 offset:3072
	ds_read_b128 v[146:149], v158
	ds_read_b128 v[150:153], v158 offset:1024
	ds_read_b128 v[154:157], v158 offset:2048
	ds_read_b128 v[158:161], v158 offset:3072
	s_add_u32 s8, s8, s58
	s_addc_u32 s9, s9, s59
	s_mov_b32 m0, s47
	v_lshl_add_u64 v[224:225], s[8:9], 0, v[176:177]
	ds_read_b128 v[162:165], v251 offset:32768
	ds_read_b128 v[184:187], v251 offset:33792
	ds_read_b128 v[188:191], v251 offset:34816
	ds_read_b128 v[192:195], v251 offset:35840
	ds_read_b128 v[196:199], v251 offset:36864
	ds_read_b128 v[200:203], v251 offset:37888
	ds_read_b128 v[204:207], v251 offset:38912
	ds_read_b128 v[208:211], v251 offset:39936
	global_load_lds_dwordx4 v[224:225], off
	v_lshl_add_u64 v[224:225], s[8:9], 0, v[174:175]
	s_mov_b32 m0, s49
	s_nop 0
	global_load_lds_dwordx4 v[224:225], off
	s_waitcnt vmcnt(8)
	s_waitcnt lgkmcnt(0)
	s_barrier
	s_waitcnt lgkmcnt(0)
	v_mfma_f32_16x16x32_bf16 v[122:125], v[130:133], v[162:165], v[122:125]
	v_mfma_f32_16x16x32_bf16 v[118:121], v[138:141], v[162:165], v[118:121]
	v_mfma_f32_16x16x32_bf16 v[110:113], v[130:133], v[188:191], v[110:113]
	v_mfma_f32_16x16x32_bf16 v[102:105], v[138:141], v[188:191], v[102:105]
	v_mfma_f32_16x16x32_bf16 v[94:97], v[130:133], v[196:199], v[94:97]
	v_mfma_f32_16x16x32_bf16 v[86:89], v[138:141], v[196:199], v[86:89]
	v_mfma_f32_16x16x32_bf16 v[78:81], v[130:133], v[204:207], v[78:81]
	v_mfma_f32_16x16x32_bf16 v[70:73], v[138:141], v[204:207], v[70:73]
	v_mfma_f32_16x16x32_bf16 v[122:125], v[134:137], v[184:187], v[122:125]
	v_mfma_f32_16x16x32_bf16 v[118:121], v[142:145], v[184:187], v[118:121]
	v_mfma_f32_16x16x32_bf16 v[110:113], v[134:137], v[192:195], v[110:113]
	v_mfma_f32_16x16x32_bf16 v[102:105], v[142:145], v[192:195], v[102:105]
	v_mfma_f32_16x16x32_bf16 v[94:97], v[134:137], v[200:203], v[94:97]
	v_mfma_f32_16x16x32_bf16 v[86:89], v[142:145], v[200:203], v[86:89]
	v_mfma_f32_16x16x32_bf16 v[78:81], v[134:137], v[208:211], v[78:81]
	v_mfma_f32_16x16x32_bf16 v[70:73], v[142:145], v[208:211], v[70:73]
	v_mfma_f32_16x16x32_bf16 v[126:129], v[146:149], v[162:165], v[126:129]
	v_mfma_f32_16x16x32_bf16 v[114:117], v[154:157], v[162:165], v[114:117]
	v_mfma_f32_16x16x32_bf16 v[106:109], v[146:149], v[188:191], v[106:109]
	v_mfma_f32_16x16x32_bf16 v[98:101], v[154:157], v[188:191], v[98:101]
	v_mfma_f32_16x16x32_bf16 v[90:93], v[146:149], v[196:199], v[90:93]
	v_mfma_f32_16x16x32_bf16 v[82:85], v[154:157], v[196:199], v[82:85]
	v_mfma_f32_16x16x32_bf16 v[74:77], v[146:149], v[204:207], v[74:77]
	v_mfma_f32_16x16x32_bf16 v[66:69], v[154:157], v[204:207], v[66:69]
	v_mfma_f32_16x16x32_bf16 v[126:129], v[150:153], v[184:187], v[126:129]
	v_mfma_f32_16x16x32_bf16 v[114:117], v[158:161], v[184:187], v[114:117]
	v_mfma_f32_16x16x32_bf16 v[106:109], v[150:153], v[192:195], v[106:109]
	v_mfma_f32_16x16x32_bf16 v[98:101], v[158:161], v[192:195], v[98:101]
	v_mfma_f32_16x16x32_bf16 v[90:93], v[150:153], v[200:203], v[90:93]
	v_mfma_f32_16x16x32_bf16 v[82:85], v[158:161], v[200:203], v[82:85]
	v_mfma_f32_16x16x32_bf16 v[74:77], v[150:153], v[208:211], v[74:77]
	v_mfma_f32_16x16x32_bf16 v[66:69], v[158:161], v[208:211], v[66:69]
	s_barrier
	s_add_i32 s8, s13, s0
	v_lshl_add_u64 v[212:213], v[212:213], 0, s[62:63]
	s_mov_b32 m0, s8
	ds_read_b128 v[162:165], v251 offset:49152
	ds_read_b128 v[184:187], v251 offset:50176
	ds_read_b128 v[188:191], v251 offset:51200
	ds_read_b128 v[192:195], v251 offset:52224
	ds_read_b128 v[196:199], v251 offset:53248
	ds_read_b128 v[200:203], v251 offset:54272
	ds_read_b128 v[204:207], v251 offset:55296
	ds_read_b128 v[208:211], v251 offset:56320
	global_load_lds_dwordx4 v[212:213], off
	v_lshl_add_u64 v[212:213], v[214:215], 0, s[62:63]
	s_add_i32 m0, s8, 0x2000
	s_add_i32 s8, s14, s0
	global_load_lds_dwordx4 v[212:213], off
	v_lshl_add_u64 v[212:213], v[216:217], 0, s[62:63]
	s_mov_b32 m0, s8
	s_nop 0
	global_load_lds_dwordx4 v[212:213], off
	v_lshl_add_u64 v[212:213], v[218:219], 0, s[62:63]
	s_add_i32 m0, s8, 0x2000
	s_nop 0
	global_load_lds_dwordx4 v[212:213], off
	v_lshl_add_u64 v[212:213], v[220:221], 0, s[62:63]
	s_mov_b32 m0, s51
	s_nop 0
	global_load_lds_dwordx4 v[212:213], off
	v_lshl_add_u64 v[212:213], v[222:223], 0, s[62:63]
	s_mov_b32 m0, s53
	s_nop 0
	global_load_lds_dwordx4 v[212:213], off
	s_waitcnt vmcnt(8)
	s_waitcnt lgkmcnt(0)
	s_barrier
	s_waitcnt lgkmcnt(0)
	v_mfma_f32_16x16x32_bf16 v[62:65], v[130:133], v[162:165], v[62:65]
	v_mfma_f32_16x16x32_bf16 v[54:57], v[138:141], v[162:165], v[54:57]
	v_mfma_f32_16x16x32_bf16 v[46:49], v[130:133], v[188:191], v[46:49]
	v_mfma_f32_16x16x32_bf16 v[38:41], v[138:141], v[188:191], v[38:41]
	v_mfma_f32_16x16x32_bf16 v[30:33], v[130:133], v[196:199], v[30:33]
	v_mfma_f32_16x16x32_bf16 v[22:25], v[138:141], v[196:199], v[22:25]
	v_mfma_f32_16x16x32_bf16 v[14:17], v[130:133], v[204:207], v[14:17]
	v_mfma_f32_16x16x32_bf16 v[6:9], v[138:141], v[204:207], v[6:9]
	v_mfma_f32_16x16x32_bf16 v[62:65], v[134:137], v[184:187], v[62:65]
	v_mfma_f32_16x16x32_bf16 v[54:57], v[142:145], v[184:187], v[54:57]
	v_mfma_f32_16x16x32_bf16 v[46:49], v[134:137], v[192:195], v[46:49]
	v_mfma_f32_16x16x32_bf16 v[38:41], v[142:145], v[192:195], v[38:41]
	v_mfma_f32_16x16x32_bf16 v[30:33], v[134:137], v[200:203], v[30:33]
	v_mfma_f32_16x16x32_bf16 v[22:25], v[142:145], v[200:203], v[22:25]
	v_mfma_f32_16x16x32_bf16 v[14:17], v[134:137], v[208:211], v[14:17]
	v_mfma_f32_16x16x32_bf16 v[6:9], v[142:145], v[208:211], v[6:9]
	v_mfma_f32_16x16x32_bf16 v[58:61], v[146:149], v[162:165], v[58:61]
	v_mfma_f32_16x16x32_bf16 v[50:53], v[154:157], v[162:165], v[50:53]
	v_mfma_f32_16x16x32_bf16 v[42:45], v[146:149], v[188:191], v[42:45]
	v_mfma_f32_16x16x32_bf16 v[34:37], v[154:157], v[188:191], v[34:37]
	v_mfma_f32_16x16x32_bf16 v[26:29], v[146:149], v[196:199], v[26:29]
	v_mfma_f32_16x16x32_bf16 v[18:21], v[154:157], v[196:199], v[18:21]
	v_mfma_f32_16x16x32_bf16 v[10:13], v[146:149], v[204:207], v[10:13]
	v_mfma_f32_16x16x32_bf16 v[2:5], v[154:157], v[204:207], v[2:5]
	v_mfma_f32_16x16x32_bf16 v[58:61], v[150:153], v[184:187], v[58:61]
	v_mfma_f32_16x16x32_bf16 v[50:53], v[158:161], v[184:187], v[50:53]
	v_mfma_f32_16x16x32_bf16 v[42:45], v[150:153], v[192:195], v[42:45]
	v_mfma_f32_16x16x32_bf16 v[34:37], v[158:161], v[192:195], v[34:37]
	v_mfma_f32_16x16x32_bf16 v[26:29], v[150:153], v[200:203], v[26:29]
	v_mfma_f32_16x16x32_bf16 v[18:21], v[158:161], v[200:203], v[18:21]
	v_mfma_f32_16x16x32_bf16 v[10:13], v[150:153], v[208:211], v[10:13]
	v_mfma_f32_16x16x32_bf16 v[2:5], v[158:161], v[208:211], v[2:5]
	s_barrier
	s_add_u32 s10, s10, 0x100
	s_addc_u32 s11, s11, 0
	s_add_u32 s6, s6, 0x100
	s_addc_u32 s7, s7, 0
	s_cmp_ge_i32 s12, s55
	s_mov_b32 s8, s12
	s_cbranch_scc0 .LBB0_288

; #define PG8_STAGE(bufoff, gbase, voff) do { _Pragma("unroll") for (int _i = 0; _i < 2; ++_i) \
;         __builtin_amdgcn_global_load_lds((const unsigned*)((const char*)(gbase) + (voff)[_i]), (PG8_LAS unsigned*)(lds + (bufoff) + ldsw + _i * 8192), 16, 0, 0); } while (0)
; #define PG8_LDA(dst, b, h) do { _Pragma("unroll") for (int m = 0; m < 4; ++m) _Pragma("unroll") for (int k = 0; k < 2; ++k) dst[m][k] = *(const PG8_LAS bf16x8*)(lds + PG8_SA(b, h) + aoff + m * 2048 + k * 1024); } while (0)
; #define PG8_LDB(dst, b, h) do { _Pragma("unroll") for (int n = 0; n < 2; ++n) _Pragma("unroll") for (int k = 0; k < 2; ++k) dst[n][k] = *(const PG8_LAS bf16x8*)(lds + PG8_SB(b, h) + boff + n * 2048 + k * 1024); } while (0)
; #define PG8_MMA(ai, bj, At, Bt) do { __builtin_amdgcn_s_setprio(1); _Pragma("unroll") for (int m = 0; m < 4; ++m) _Pragma("unroll") for (int n = 0; n < 2; ++n) _Pragma("unroll") for (int k = 0; k < 2; ++k) \
;         acc[ai][bj][m][n] = __builtin_amdgcn_mfma_f32_16x16x32_bf16(Bt[n][k], At[m][k], acc[ai][bj][m][n], 0, 0, 0); __builtin_amdgcn_s_setprio(0); } while (0)
; #define PG8_WAIT_V(n) asm volatile("s_waitcnt vmcnt(" #n ")" ::: "memory")
; #define PG8_WAIT_L(n) asm volatile("s_waitcnt lgkmcnt(" #n ")" ::: "memory")
; #define PG8_BAR __builtin_amdgcn_s_barrier()
; #define PG8_SCHED __builtin_amdgcn_sched_barrier(0)
;     ...
;         for (int t = 0; t < nt; t += 2) {
;             const bool last = (t == nt - 2);
;             const char* a1 = cA + (size_t)(t + 1) * kstep;
;             const char* a2 = last ? nA : cA + (size_t)(t + 2) * kstep; const char* b2 = last ? nB : cB + (size_t)(t + 2) * kstep;
;             const char* a3 = a2 + kstep; const char* b3 = b2 + kstep;
;             if (last && has_next) S.a_ready(nxt);
;             if constexpr (SP2) {
;             PG8_LDB(B0, 0, 0); PG8_LDB(B1, 0, 1); PG8_SCHED; PG8_LDA(At, 0, 0); PG8_STAGE(PG8_SA(1, 1), a1 + hstepA, voffA);
;             PG8_WAIT_V(8); PG8_WAIT_L(0); PG8_BAR; PG8_MMA(0, 0, At, B0); PG8_MMA(0, 1, At, B1); PG8_BAR; PG8_SCHED;
;             PG8_LDA(At, 0, 1); PG8_STAGE(PG8_SB(0, 0), b2, voffB); PG8_STAGE(PG8_SB(0, 1), b2 + hstepB, voffB); PG8_STAGE(PG8_SA(0, 0), a2, voffA);
.LBB0_518:
	s_andn2_b64 vcc, exec, s[88:89]
	s_waitcnt lgkmcnt(0)
	s_cbranch_vccnz .LBB0_521
	s_add_u32 s10, s6, 0x100
	s_addc_u32 s11, s7, 0
	s_add_u32 s6, s8, 0x80
	s_addc_u32 s7, s9, 0
	s_mov_b32 s8, 0
	s_add_i32 s25, s8, 2
	s_add_u32 s27, s6, 0x80
	s_addc_u32 s9, s7, 0
	s_add_i32 s31, 0, 0x10000
	s_cmp_eq_u32 s19, s8
	s_cselect_b32 s9, s43, s9
	s_cselect_b32 s8, s42, s27
	s_cselect_b32 s35, s93, s11
	s_cselect_b32 s34, s92, s10
	s_add_i32 s27, 0, 0x14000
	v_add_u32_e32 v148, s31, v229
	v_add_u32_e32 v164, s27, v229
	ds_read_b128 v[136:139], v148
	ds_read_b128 v[140:143], v148 offset:1024
	ds_read_b128 v[144:147], v148 offset:2048
	ds_read_b128 v[148:151], v148 offset:3072
	ds_read_b128 v[152:155], v164
	ds_read_b128 v[156:159], v164 offset:1024
	ds_read_b128 v[160:163], v164 offset:2048
	ds_read_b128 v[172:175], v164 offset:3072
	v_lshl_add_u64 v[164:165], s[6:7], 0, v[134:135]
	s_add_i32 m0, s2, 0xc000
	ds_read_b128 v[176:179], v231
	ds_read_b128 v[180:183], v231 offset:1024
	ds_read_b128 v[184:187], v231 offset:2048
	ds_read_b128 v[188:191], v231 offset:3072
	ds_read_b128 v[192:195], v231 offset:4096
	ds_read_b128 v[196:199], v231 offset:5120
	ds_read_b128 v[200:203], v231 offset:6144
	ds_read_b128 v[204:207], v231 offset:7168
	global_load_lds_dwordx4 v[164:165], off
	v_lshl_add_u64 v[164:165], s[6:7], 0, v[132:133]
	s_add_i32 m0, s2, 0xe000
	s_nop 0
	global_load_lds_dwordx4 v[164:165], off
	s_waitcnt vmcnt(8)
	s_waitcnt lgkmcnt(0)
	s_barrier
	s_waitcnt lgkmcnt(0)
	v_mfma_f32_16x16x32_bf16 v[126:129], v[136:139], v[176:179], 0
	v_mfma_f32_16x16x32_bf16 v[122:125], v[144:147], v[176:179], 0
	v_mfma_f32_16x16x32_bf16 v[110:113], v[136:139], v[184:187], 0
	v_mfma_f32_16x16x32_bf16 v[106:109], v[144:147], v[184:187], 0
	v_mfma_f32_16x16x32_bf16 v[94:97], v[136:139], v[192:195], 0
	v_mfma_f32_16x16x32_bf16 v[90:93], v[144:147], v[192:195], 0
	v_mfma_f32_16x16x32_bf16 v[78:81], v[136:139], v[200:203], 0
	v_mfma_f32_16x16x32_bf16 v[74:77], v[144:147], v[200:203], 0
	v_mfma_f32_16x16x32_bf16 v[126:129], v[140:143], v[180:183], v[126:129]
	v_mfma_f32_16x16x32_bf16 v[122:125], v[148:151], v[180:183], v[122:125]
	v_mfma_f32_16x16x32_bf16 v[110:113], v[140:143], v[188:191], v[110:113]
	v_mfma_f32_16x16x32_bf16 v[106:109], v[148:151], v[188:191], v[106:109]
	v_mfma_f32_16x16x32_bf16 v[94:97], v[140:143], v[196:199], v[94:97]
	v_mfma_f32_16x16x32_bf16 v[90:93], v[148:151], v[196:199], v[90:93]
	v_mfma_f32_16x16x32_bf16 v[78:81], v[140:143], v[204:207], v[78:81]
	v_mfma_f32_16x16x32_bf16 v[74:77], v[148:151], v[204:207], v[74:77]
	v_mfma_f32_16x16x32_bf16 v[118:121], v[152:155], v[176:179], 0
	v_mfma_f32_16x16x32_bf16 v[114:117], v[160:163], v[176:179], 0
	v_mfma_f32_16x16x32_bf16 v[102:105], v[152:155], v[184:187], 0
	v_mfma_f32_16x16x32_bf16 v[98:101], v[160:163], v[184:187], 0
	v_mfma_f32_16x16x32_bf16 v[86:89], v[152:155], v[192:195], 0
	v_mfma_f32_16x16x32_bf16 v[82:85], v[160:163], v[192:195], 0
	v_mfma_f32_16x16x32_bf16 v[70:73], v[152:155], v[200:203], 0
	v_mfma_f32_16x16x32_bf16 v[66:69], v[160:163], v[200:203], 0
	v_mfma_f32_16x16x32_bf16 v[118:121], v[156:159], v[180:183], v[118:121]
	v_mfma_f32_16x16x32_bf16 v[114:117], v[172:175], v[180:183], v[114:117]
	v_mfma_f32_16x16x32_bf16 v[102:105], v[156:159], v[188:191], v[102:105]
	v_mfma_f32_16x16x32_bf16 v[98:101], v[172:175], v[188:191], v[98:101]
	v_mfma_f32_16x16x32_bf16 v[86:89], v[156:159], v[196:199], v[86:89]
	v_mfma_f32_16x16x32_bf16 v[82:85], v[172:175], v[196:199], v[82:85]
	v_mfma_f32_16x16x32_bf16 v[70:73], v[156:159], v[204:207], v[70:73]
	v_mfma_f32_16x16x32_bf16 v[66:69], v[172:175], v[204:207], v[66:69]
	s_barrier
	s_add_i32 s31, s31, s0
	v_lshl_add_u64 v[164:165], s[34:35], 0, v[166:167]
	s_mov_b32 m0, s31
	ds_read_b128 v[176:179], v231 offset:16384
	ds_read_b128 v[180:183], v231 offset:17408
	ds_read_b128 v[184:187], v231 offset:18432
	ds_read_b128 v[188:191], v231 offset:19456
	ds_read_b128 v[192:195], v231 offset:20480
	ds_read_b128 v[196:199], v231 offset:21504
	ds_read_b128 v[200:203], v231 offset:22528
	ds_read_b128 v[204:207], v231 offset:23552
	global_load_lds_dwordx4 v[164:165], off
	s_add_i32 m0, s31, 0x2000
	v_lshl_add_u64 v[168:169], s[34:35], 0, v[130:131]
	s_add_u32 s34, s34, s60
	s_addc_u32 s35, s35, s61
	s_add_i32 s27, s27, s0
	global_load_lds_dwordx4 v[168:169], off
	v_lshl_add_u64 v[170:171], s[34:35], 0, v[166:167]
	s_mov_b32 m0, s27
	v_lshl_add_u64 v[208:209], s[34:35], 0, v[130:131]
	global_load_lds_dwordx4 v[170:171], off
	s_add_i32 m0, s27, 0x2000
	v_lshl_add_u64 v[210:211], s[8:9], 0, v[166:167]
	global_load_lds_dwordx4 v[208:209], off
	s_mov_b32 m0, s2
	v_lshl_add_u64 v[212:213], s[8:9], 0, v[130:131]
	global_load_lds_dwordx4 v[210:211], off
	s_mov_b32 m0, s3
	s_nop 0
	global_load_lds_dwordx4 v[212:213], off
	s_waitcnt vmcnt(8)
	s_waitcnt lgkmcnt(0)
	s_barrier
; #define PG8_STAGE(bufoff, gbase, voff) do { _Pragma("unroll") for (int _i = 0; _i < 2; ++_i) \
;         __builtin_amdgcn_global_load_lds((const unsigned*)((const char*)(gbase) + (voff)[_i]), (PG8_LAS unsigned*)(lds + (bufoff) + ldsw + _i * 8192), 16, 0, 0); } while (0)
; #define PG8_LDA(dst, b, h) do { _Pragma("unroll") for (int m = 0; m < 4; ++m) _Pragma("unroll") for (int k = 0; k < 2; ++k) dst[m][k] = *(const PG8_LAS bf16x8*)(lds + PG8_SA(b, h) + aoff + m * 2048 + k * 1024); } while (0)
; #define PG8_LDB(dst, b, h) do { _Pragma("unroll") for (int n = 0; n < 2; ++n) _Pragma("unroll") for (int k = 0; k < 2; ++k) dst[n][k] = *(const PG8_LAS bf16x8*)(lds + PG8_SB(b, h) + boff + n * 2048 + k * 1024); } while (0)
; #define PG8_MMA(ai, bj, At, Bt) do { __builtin_amdgcn_s_setprio(1); _Pragma("unroll") for (int m = 0; m < 4; ++m) _Pragma("unroll") for (int n = 0; n < 2; ++n) _Pragma("unroll") for (int k = 0; k < 2; ++k) \
;         acc[ai][bj][m][n] = __builtin_amdgcn_mfma_f32_16x16x32_bf16(Bt[n][k], At[m][k], acc[ai][bj][m][n], 0, 0, 0); __builtin_amdgcn_s_setprio(0); } while (0)
; #define PG8_WAIT_V(n) asm volatile("s_waitcnt vmcnt(" #n ")" ::: "memory")
; #define PG8_WAIT_L(n) asm volatile("s_waitcnt lgkmcnt(" #n ")" ::: "memory")
; #define PG8_BAR __builtin_amdgcn_s_barrier()
; #define PG8_SCHED __builtin_amdgcn_sched_barrier(0)
;     ...
;             PG8_WAIT_V(8); PG8_WAIT_L(0); PG8_BAR; PG8_MMA(1, 0, At, B0); PG8_MMA(1, 1, At, B1); PG8_BAR; PG8_SCHED;
;             PG8_LDB(B0, 1, 0); PG8_LDB(B1, 1, 1); PG8_SCHED; PG8_LDA(At, 1, 0); PG8_STAGE(PG8_SA(0, 1), a2 + hstepA, voffA);
;             PG8_WAIT_V(8); PG8_WAIT_L(0); PG8_BAR; PG8_MMA(0, 0, At, B0); PG8_MMA(0, 1, At, B1); PG8_BAR; PG8_SCHED;
	s_waitcnt lgkmcnt(0)
	v_mfma_f32_16x16x32_bf16 v[62:65], v[136:139], v[176:179], 0
	v_mfma_f32_16x16x32_bf16 v[58:61], v[144:147], v[176:179], 0
	v_mfma_f32_16x16x32_bf16 v[46:49], v[136:139], v[184:187], 0
	v_mfma_f32_16x16x32_bf16 v[42:45], v[144:147], v[184:187], 0
	v_mfma_f32_16x16x32_bf16 v[30:33], v[136:139], v[192:195], 0
	v_mfma_f32_16x16x32_bf16 v[26:29], v[144:147], v[192:195], 0
	v_mfma_f32_16x16x32_bf16 v[14:17], v[136:139], v[200:203], 0
	v_mfma_f32_16x16x32_bf16 v[10:13], v[144:147], v[200:203], 0
	v_mfma_f32_16x16x32_bf16 v[62:65], v[140:143], v[180:183], v[62:65]
	v_mfma_f32_16x16x32_bf16 v[58:61], v[148:151], v[180:183], v[58:61]
	v_mfma_f32_16x16x32_bf16 v[46:49], v[140:143], v[188:191], v[46:49]
	v_mfma_f32_16x16x32_bf16 v[42:45], v[148:151], v[188:191], v[42:45]
	v_mfma_f32_16x16x32_bf16 v[30:33], v[140:143], v[196:199], v[30:33]
	v_mfma_f32_16x16x32_bf16 v[26:29], v[148:151], v[196:199], v[26:29]
	v_mfma_f32_16x16x32_bf16 v[14:17], v[140:143], v[204:207], v[14:17]
	v_mfma_f32_16x16x32_bf16 v[10:13], v[148:151], v[204:207], v[10:13]
	v_mfma_f32_16x16x32_bf16 v[54:57], v[152:155], v[176:179], 0
	v_mfma_f32_16x16x32_bf16 v[50:53], v[160:163], v[176:179], 0
	v_mfma_f32_16x16x32_bf16 v[38:41], v[152:155], v[184:187], 0
	v_mfma_f32_16x16x32_bf16 v[34:37], v[160:163], v[184:187], 0
	v_mfma_f32_16x16x32_bf16 v[22:25], v[152:155], v[192:195], 0
	v_mfma_f32_16x16x32_bf16 v[18:21], v[160:163], v[192:195], 0
	v_mfma_f32_16x16x32_bf16 v[6:9], v[152:155], v[200:203], 0
	v_mfma_f32_16x16x32_bf16 v[2:5], v[160:163], v[200:203], 0
	v_mfma_f32_16x16x32_bf16 v[54:57], v[156:159], v[180:183], v[54:57]
	v_mfma_f32_16x16x32_bf16 v[50:53], v[172:175], v[180:183], v[50:53]
	v_mfma_f32_16x16x32_bf16 v[38:41], v[156:159], v[188:191], v[38:41]
	v_mfma_f32_16x16x32_bf16 v[34:37], v[172:175], v[188:191], v[34:37]
	v_mfma_f32_16x16x32_bf16 v[22:25], v[156:159], v[196:199], v[22:25]
	v_mfma_f32_16x16x32_bf16 v[18:21], v[172:175], v[196:199], v[18:21]
	v_mfma_f32_16x16x32_bf16 v[6:9], v[156:159], v[204:207], v[6:9]
	v_mfma_f32_16x16x32_bf16 v[2:5], v[172:175], v[204:207], v[2:5]
	s_barrier
	s_add_i32 s27, 0, 0x18000
	s_add_i32 s31, 0, 0x1c000
	v_add_u32_e32 v148, s27, v229
	v_add_u32_e32 v172, s31, v229
	ds_read_b128 v[136:139], v148
	ds_read_b128 v[140:143], v148 offset:1024
	ds_read_b128 v[144:147], v148 offset:2048
	ds_read_b128 v[148:151], v148 offset:3072
	ds_read_b128 v[152:155], v172
	ds_read_b128 v[156:159], v172 offset:1024
	ds_read_b128 v[160:163], v172 offset:2048
	ds_read_b128 v[172:175], v172 offset:3072
	s_add_u32 s8, s8, s60
	s_addc_u32 s9, s9, s61
	s_mov_b32 m0, s14
	v_lshl_add_u64 v[214:215], s[8:9], 0, v[166:167]
	ds_read_b128 v[176:179], v231 offset:32768
	ds_read_b128 v[180:183], v231 offset:33792
	ds_read_b128 v[184:187], v231 offset:34816
	ds_read_b128 v[188:191], v231 offset:35840
	ds_read_b128 v[192:195], v231 offset:36864
	ds_read_b128 v[196:199], v231 offset:37888
	ds_read_b128 v[200:203], v231 offset:38912
	ds_read_b128 v[204:207], v231 offset:39936
	global_load_lds_dwordx4 v[214:215], off
	v_lshl_add_u64 v[214:215], s[8:9], 0, v[130:131]
	s_mov_b32 m0, s15
	s_nop 0
	global_load_lds_dwordx4 v[214:215], off
	s_waitcnt vmcnt(8)
	s_waitcnt lgkmcnt(0)
	s_barrier
	s_waitcnt lgkmcnt(0)
	v_mfma_f32_16x16x32_bf16 v[126:129], v[136:139], v[176:179], v[126:129]
	v_mfma_f32_16x16x32_bf16 v[122:125], v[144:147], v[176:179], v[122:125]
	v_mfma_f32_16x16x32_bf16 v[110:113], v[136:139], v[184:187], v[110:113]
	v_mfma_f32_16x16x32_bf16 v[106:109], v[144:147], v[184:187], v[106:109]
	v_mfma_f32_16x16x32_bf16 v[94:97], v[136:139], v[192:195], v[94:97]
	v_mfma_f32_16x16x32_bf16 v[90:93], v[144:147], v[192:195], v[90:93]
	v_mfma_f32_16x16x32_bf16 v[78:81], v[136:139], v[200:203], v[78:81]
	v_mfma_f32_16x16x32_bf16 v[74:77], v[144:147], v[200:203], v[74:77]
	v_mfma_f32_16x16x32_bf16 v[126:129], v[140:143], v[180:183], v[126:129]
	v_mfma_f32_16x16x32_bf16 v[122:125], v[148:151], v[180:183], v[122:125]
	v_mfma_f32_16x16x32_bf16 v[110:113], v[140:143], v[188:191], v[110:113]
	v_mfma_f32_16x16x32_bf16 v[106:109], v[148:151], v[188:191], v[106:109]
	v_mfma_f32_16x16x32_bf16 v[94:97], v[140:143], v[196:199], v[94:97]
	v_mfma_f32_16x16x32_bf16 v[90:93], v[148:151], v[196:199], v[90:93]
	v_mfma_f32_16x16x32_bf16 v[78:81], v[140:143], v[204:207], v[78:81]
	v_mfma_f32_16x16x32_bf16 v[74:77], v[148:151], v[204:207], v[74:77]
	v_mfma_f32_16x16x32_bf16 v[118:121], v[152:155], v[176:179], v[118:121]
	v_mfma_f32_16x16x32_bf16 v[114:117], v[160:163], v[176:179], v[114:117]
	v_mfma_f32_16x16x32_bf16 v[102:105], v[152:155], v[184:187], v[102:105]
	v_mfma_f32_16x16x32_bf16 v[98:101], v[160:163], v[184:187], v[98:101]
	v_mfma_f32_16x16x32_bf16 v[86:89], v[152:155], v[192:195], v[86:89]
	v_mfma_f32_16x16x32_bf16 v[82:85], v[160:163], v[192:195], v[82:85]
	v_mfma_f32_16x16x32_bf16 v[70:73], v[152:155], v[200:203], v[70:73]
	v_mfma_f32_16x16x32_bf16 v[66:69], v[160:163], v[200:203], v[66:69]
	v_mfma_f32_16x16x32_bf16 v[118:121], v[156:159], v[180:183], v[118:121]
	v_mfma_f32_16x16x32_bf16 v[114:117], v[172:175], v[180:183], v[114:117]
	v_mfma_f32_16x16x32_bf16 v[102:105], v[156:159], v[188:191], v[102:105]
	v_mfma_f32_16x16x32_bf16 v[98:101], v[172:175], v[188:191], v[98:101]
	v_mfma_f32_16x16x32_bf16 v[86:89], v[156:159], v[196:199], v[86:89]
	v_mfma_f32_16x16x32_bf16 v[82:85], v[172:175], v[196:199], v[82:85]
	v_mfma_f32_16x16x32_bf16 v[70:73], v[156:159], v[204:207], v[70:73]
	v_mfma_f32_16x16x32_bf16 v[66:69], v[172:175], v[204:207], v[66:69]
	s_barrier
; #define PG8_STAGE(bufoff, gbase, voff) do { _Pragma("unroll") for (int _i = 0; _i < 2; ++_i) \
;         __builtin_amdgcn_global_load_lds((const unsigned*)((const char*)(gbase) + (voff)[_i]), (PG8_LAS unsigned*)(lds + (bufoff) + ldsw + _i * 8192), 16, 0, 0); } while (0)
; #define PG8_LDA(dst, b, h) do { _Pragma("unroll") for (int m = 0; m < 4; ++m) _Pragma("unroll") for (int k = 0; k < 2; ++k) dst[m][k] = *(const PG8_LAS bf16x8*)(lds + PG8_SA(b, h) + aoff + m * 2048 + k * 1024); } while (0)
; #define PG8_LDB(dst, b, h) do { _Pragma("unroll") for (int n = 0; n < 2; ++n) _Pragma("unroll") for (int k = 0; k < 2; ++k) dst[n][k] = *(const PG8_LAS bf16x8*)(lds + PG8_SB(b, h) + boff + n * 2048 + k * 1024); } while (0)
; #define PG8_MMA(ai, bj, At, Bt) do { __builtin_amdgcn_s_setprio(1); _Pragma("unroll") for (int m = 0; m < 4; ++m) _Pragma("unroll") for (int n = 0; n < 2; ++n) _Pragma("unroll") for (int k = 0; k < 2; ++k) \
;         acc[ai][bj][m][n] = __builtin_amdgcn_mfma_f32_16x16x32_bf16(Bt[n][k], At[m][k], acc[ai][bj][m][n], 0, 0, 0); __builtin_amdgcn_s_setprio(0); } while (0)
; #define PG8_WAIT_V(n) asm volatile("s_waitcnt vmcnt(" #n ")" ::: "memory")
; #define PG8_WAIT_L(n) asm volatile("s_waitcnt lgkmcnt(" #n ")" ::: "memory")
; #define PG8_BAR __builtin_amdgcn_s_barrier()
; #define PG8_SCHED __builtin_amdgcn_sched_barrier(0)
;     ...
;         for (int t = 0; t < nt; t += 2) {
;             const bool last = (t == nt - 2);
;             const char* a1 = cA + (size_t)(t + 1) * kstep;
;             const char* a2 = last ? nA : cA + (size_t)(t + 2) * kstep; const char* b2 = last ? nB : cB + (size_t)(t + 2) * kstep;
;             const char* a3 = a2 + kstep; const char* b3 = b2 + kstep;
;             if (last && has_next) S.a_ready(nxt);
;             if constexpr (SP2) {
;             PG8_LDB(B0, 0, 0); PG8_LDB(B1, 0, 1); PG8_SCHED; PG8_LDA(At, 0, 0); PG8_STAGE(PG8_SA(1, 1), a1 + hstepA, voffA);
;             PG8_WAIT_V(8); PG8_WAIT_L(0); PG8_BAR; PG8_MMA(0, 0, At, B0); PG8_MMA(0, 1, At, B1); PG8_BAR; PG8_SCHED;
;     ...
;             PG8_LDA(At, 1, 1); PG8_STAGE(PG8_SB(1, 0), b3, voffB); PG8_STAGE(PG8_SB(1, 1), b3 + hstepB, voffB); PG8_STAGE(PG8_SA(1, 0), a3, voffA);
;             PG8_WAIT_V(8); PG8_WAIT_L(0); PG8_BAR; PG8_MMA(1, 0, At, B0); PG8_MMA(1, 1, At, B1); PG8_BAR; PG8_SCHED;
	s_add_i32 s8, s27, s0
	v_lshl_add_u64 v[164:165], v[164:165], 0, s[62:63]
	s_mov_b32 m0, s8
	ds_read_b128 v[176:179], v231 offset:49152
	ds_read_b128 v[180:183], v231 offset:50176
	ds_read_b128 v[184:187], v231 offset:51200
	ds_read_b128 v[188:191], v231 offset:52224
	ds_read_b128 v[192:195], v231 offset:53248
	ds_read_b128 v[196:199], v231 offset:54272
	ds_read_b128 v[200:203], v231 offset:55296
	ds_read_b128 v[204:207], v231 offset:56320
	global_load_lds_dwordx4 v[164:165], off
	v_lshl_add_u64 v[164:165], v[168:169], 0, s[62:63]
	s_add_i32 m0, s8, 0x2000
	s_add_i32 s8, s31, s0
	global_load_lds_dwordx4 v[164:165], off
	v_lshl_add_u64 v[164:165], v[170:171], 0, s[62:63]
	s_mov_b32 m0, s8
	s_nop 0
	global_load_lds_dwordx4 v[164:165], off
	v_lshl_add_u64 v[164:165], v[208:209], 0, s[62:63]
	s_add_i32 m0, s8, 0x2000
	s_nop 0
	global_load_lds_dwordx4 v[164:165], off
	v_lshl_add_u64 v[164:165], v[210:211], 0, s[62:63]
	s_mov_b32 m0, s17
	s_nop 0
	global_load_lds_dwordx4 v[164:165], off
	v_lshl_add_u64 v[164:165], v[212:213], 0, s[62:63]
	s_mov_b32 m0, s18
	s_nop 0
	global_load_lds_dwordx4 v[164:165], off
	s_waitcnt vmcnt(8)
	s_waitcnt lgkmcnt(0)
	s_barrier
	s_waitcnt lgkmcnt(0)
	v_mfma_f32_16x16x32_bf16 v[62:65], v[136:139], v[176:179], v[62:65]
	v_mfma_f32_16x16x32_bf16 v[58:61], v[144:147], v[176:179], v[58:61]
	v_mfma_f32_16x16x32_bf16 v[46:49], v[136:139], v[184:187], v[46:49]
	v_mfma_f32_16x16x32_bf16 v[42:45], v[144:147], v[184:187], v[42:45]
	v_mfma_f32_16x16x32_bf16 v[30:33], v[136:139], v[192:195], v[30:33]
	v_mfma_f32_16x16x32_bf16 v[26:29], v[144:147], v[192:195], v[26:29]
	v_mfma_f32_16x16x32_bf16 v[14:17], v[136:139], v[200:203], v[14:17]
	v_mfma_f32_16x16x32_bf16 v[10:13], v[144:147], v[200:203], v[10:13]
	v_mfma_f32_16x16x32_bf16 v[62:65], v[140:143], v[180:183], v[62:65]
	v_mfma_f32_16x16x32_bf16 v[58:61], v[148:151], v[180:183], v[58:61]
	v_mfma_f32_16x16x32_bf16 v[46:49], v[140:143], v[188:191], v[46:49]
	v_mfma_f32_16x16x32_bf16 v[42:45], v[148:151], v[188:191], v[42:45]
	v_mfma_f32_16x16x32_bf16 v[30:33], v[140:143], v[196:199], v[30:33]
	v_mfma_f32_16x16x32_bf16 v[26:29], v[148:151], v[196:199], v[26:29]
	v_mfma_f32_16x16x32_bf16 v[14:17], v[140:143], v[204:207], v[14:17]
	v_mfma_f32_16x16x32_bf16 v[10:13], v[148:151], v[204:207], v[10:13]
	v_mfma_f32_16x16x32_bf16 v[54:57], v[152:155], v[176:179], v[54:57]
	v_mfma_f32_16x16x32_bf16 v[50:53], v[160:163], v[176:179], v[50:53]
	v_mfma_f32_16x16x32_bf16 v[38:41], v[152:155], v[184:187], v[38:41]
	v_mfma_f32_16x16x32_bf16 v[34:37], v[160:163], v[184:187], v[34:37]
	v_mfma_f32_16x16x32_bf16 v[22:25], v[152:155], v[192:195], v[22:25]
	v_mfma_f32_16x16x32_bf16 v[18:21], v[160:163], v[192:195], v[18:21]
	v_mfma_f32_16x16x32_bf16 v[6:9], v[152:155], v[200:203], v[6:9]
	v_mfma_f32_16x16x32_bf16 v[2:5], v[160:163], v[200:203], v[2:5]
	v_mfma_f32_16x16x32_bf16 v[54:57], v[156:159], v[180:183], v[54:57]
	v_mfma_f32_16x16x32_bf16 v[50:53], v[172:175], v[180:183], v[50:53]
	v_mfma_f32_16x16x32_bf16 v[38:41], v[156:159], v[188:191], v[38:41]
	v_mfma_f32_16x16x32_bf16 v[34:37], v[172:175], v[188:191], v[34:37]
	v_mfma_f32_16x16x32_bf16 v[22:25], v[156:159], v[196:199], v[22:25]
	v_mfma_f32_16x16x32_bf16 v[18:21], v[172:175], v[196:199], v[18:21]
	v_mfma_f32_16x16x32_bf16 v[6:9], v[156:159], v[204:207], v[6:9]
	v_mfma_f32_16x16x32_bf16 v[2:5], v[172:175], v[204:207], v[2:5]
	s_barrier
	s_add_u32 s10, s10, 0x100
	s_addc_u32 s11, s11, 0
	s_add_u32 s6, s6, 0x100
	s_addc_u32 s7, s7, 0
	s_cmp_ge_i32 s25, s13
	s_mov_b32 s8, s25
	s_cbranch_scc1 .LBB0_521
.LBB0_520:
	s_add_i32 s25, s8, 2
	s_add_u32 s27, s6, 0x80
	s_addc_u32 s9, s7, 0
	s_add_i32 s31, 0, 0x10000
	s_cmp_eq_u32 s19, s8
	s_cselect_b32 s9, s43, s9
	s_cselect_b32 s8, s42, s27
	s_cselect_b32 s35, s93, s11
	s_cselect_b32 s34, s92, s10
	s_add_i32 s27, 0, 0x14000
	v_add_u32_e32 v148, s31, v229
	v_add_u32_e32 v164, s27, v229
	ds_read_b128 v[136:139], v148
	ds_read_b128 v[140:143], v148 offset:1024
	ds_read_b128 v[144:147], v148 offset:2048
	ds_read_b128 v[148:151], v148 offset:3072
	ds_read_b128 v[152:155], v164
	ds_read_b128 v[156:159], v164 offset:1024
	ds_read_b128 v[160:163], v164 offset:2048
	ds_read_b128 v[172:175], v164 offset:3072
	v_lshl_add_u64 v[164:165], s[6:7], 0, v[134:135]
	s_add_i32 m0, s2, 0xc000
	ds_read_b128 v[176:179], v231
	ds_read_b128 v[180:183], v231 offset:1024
	ds_read_b128 v[184:187], v231 offset:2048
	ds_read_b128 v[188:191], v231 offset:3072
	ds_read_b128 v[192:195], v231 offset:4096
	ds_read_b128 v[196:199], v231 offset:5120
	ds_read_b128 v[200:203], v231 offset:6144
	ds_read_b128 v[204:207], v231 offset:7168
	global_load_lds_dwordx4 v[164:165], off
	v_lshl_add_u64 v[164:165], s[6:7], 0, v[132:133]
	s_add_i32 m0, s2, 0xe000
	s_nop 0
	global_load_lds_dwordx4 v[164:165], off
	s_waitcnt vmcnt(8)
	s_waitcnt lgkmcnt(0)
	s_barrier
; #define PG8_STAGE(bufoff, gbase, voff) do { _Pragma("unroll") for (int _i = 0; _i < 2; ++_i) \
;         __builtin_amdgcn_global_load_lds((const unsigned*)((const char*)(gbase) + (voff)[_i]), (PG8_LAS unsigned*)(lds + (bufoff) + ldsw + _i * 8192), 16, 0, 0); } while (0)
; #define PG8_LDA(dst, b, h) do { _Pragma("unroll") for (int m = 0; m < 4; ++m) _Pragma("unroll") for (int k = 0; k < 2; ++k) dst[m][k] = *(const PG8_LAS bf16x8*)(lds + PG8_SA(b, h) + aoff + m * 2048 + k * 1024); } while (0)
; #define PG8_MMA(ai, bj, At, Bt) do { __builtin_amdgcn_s_setprio(1); _Pragma("unroll") for (int m = 0; m < 4; ++m) _Pragma("unroll") for (int n = 0; n < 2; ++n) _Pragma("unroll") for (int k = 0; k < 2; ++k) \
;         acc[ai][bj][m][n] = __builtin_amdgcn_mfma_f32_16x16x32_bf16(Bt[n][k], At[m][k], acc[ai][bj][m][n], 0, 0, 0); __builtin_amdgcn_s_setprio(0); } while (0)
; #define PG8_WAIT_V(n) asm volatile("s_waitcnt vmcnt(" #n ")" ::: "memory")
; #define PG8_WAIT_L(n) asm volatile("s_waitcnt lgkmcnt(" #n ")" ::: "memory")
; #define PG8_BAR __builtin_amdgcn_s_barrier()
; #define PG8_SCHED __builtin_amdgcn_sched_barrier(0)
;     ...
;             PG8_WAIT_V(8); PG8_WAIT_L(0); PG8_BAR; PG8_MMA(0, 0, At, B0); PG8_MMA(0, 1, At, B1); PG8_BAR; PG8_SCHED;
;             PG8_LDA(At, 0, 1); PG8_STAGE(PG8_SB(0, 0), b2, voffB); PG8_STAGE(PG8_SB(0, 1), b2 + hstepB, voffB); PG8_STAGE(PG8_SA(0, 0), a2, voffA);
;             PG8_WAIT_V(8); PG8_WAIT_L(0); PG8_BAR; PG8_MMA(1, 0, At, B0); PG8_MMA(1, 1, At, B1); PG8_BAR; PG8_SCHED;
	s_waitcnt lgkmcnt(0)
	v_mfma_f32_16x16x32_bf16 v[126:129], v[136:139], v[176:179], v[126:129]
	v_mfma_f32_16x16x32_bf16 v[122:125], v[144:147], v[176:179], v[122:125]
	v_mfma_f32_16x16x32_bf16 v[110:113], v[136:139], v[184:187], v[110:113]
	v_mfma_f32_16x16x32_bf16 v[106:109], v[144:147], v[184:187], v[106:109]
	v_mfma_f32_16x16x32_bf16 v[94:97], v[136:139], v[192:195], v[94:97]
	v_mfma_f32_16x16x32_bf16 v[90:93], v[144:147], v[192:195], v[90:93]
	v_mfma_f32_16x16x32_bf16 v[78:81], v[136:139], v[200:203], v[78:81]
	v_mfma_f32_16x16x32_bf16 v[74:77], v[144:147], v[200:203], v[74:77]
	v_mfma_f32_16x16x32_bf16 v[126:129], v[140:143], v[180:183], v[126:129]
	v_mfma_f32_16x16x32_bf16 v[122:125], v[148:151], v[180:183], v[122:125]
	v_mfma_f32_16x16x32_bf16 v[110:113], v[140:143], v[188:191], v[110:113]
	v_mfma_f32_16x16x32_bf16 v[106:109], v[148:151], v[188:191], v[106:109]
	v_mfma_f32_16x16x32_bf16 v[94:97], v[140:143], v[196:199], v[94:97]
	v_mfma_f32_16x16x32_bf16 v[90:93], v[148:151], v[196:199], v[90:93]
	v_mfma_f32_16x16x32_bf16 v[78:81], v[140:143], v[204:207], v[78:81]
	v_mfma_f32_16x16x32_bf16 v[74:77], v[148:151], v[204:207], v[74:77]
	v_mfma_f32_16x16x32_bf16 v[118:121], v[152:155], v[176:179], v[118:121]
	v_mfma_f32_16x16x32_bf16 v[114:117], v[160:163], v[176:179], v[114:117]
	v_mfma_f32_16x16x32_bf16 v[102:105], v[152:155], v[184:187], v[102:105]
	v_mfma_f32_16x16x32_bf16 v[98:101], v[160:163], v[184:187], v[98:101]
	v_mfma_f32_16x16x32_bf16 v[86:89], v[152:155], v[192:195], v[86:89]
	v_mfma_f32_16x16x32_bf16 v[82:85], v[160:163], v[192:195], v[82:85]
	v_mfma_f32_16x16x32_bf16 v[70:73], v[152:155], v[200:203], v[70:73]
	v_mfma_f32_16x16x32_bf16 v[66:69], v[160:163], v[200:203], v[66:69]
	v_mfma_f32_16x16x32_bf16 v[118:121], v[156:159], v[180:183], v[118:121]
	v_mfma_f32_16x16x32_bf16 v[114:117], v[172:175], v[180:183], v[114:117]
	v_mfma_f32_16x16x32_bf16 v[102:105], v[156:159], v[188:191], v[102:105]
	v_mfma_f32_16x16x32_bf16 v[98:101], v[172:175], v[188:191], v[98:101]
	v_mfma_f32_16x16x32_bf16 v[86:89], v[156:159], v[196:199], v[86:89]
	v_mfma_f32_16x16x32_bf16 v[82:85], v[172:175], v[196:199], v[82:85]
	v_mfma_f32_16x16x32_bf16 v[70:73], v[156:159], v[204:207], v[70:73]
	v_mfma_f32_16x16x32_bf16 v[66:69], v[172:175], v[204:207], v[66:69]
	s_barrier
	s_add_i32 s31, s31, s0
	v_lshl_add_u64 v[164:165], s[34:35], 0, v[166:167]
	s_mov_b32 m0, s31
	ds_read_b128 v[176:179], v231 offset:16384
	ds_read_b128 v[180:183], v231 offset:17408
	ds_read_b128 v[184:187], v231 offset:18432
	ds_read_b128 v[188:191], v231 offset:19456
	ds_read_b128 v[192:195], v231 offset:20480
	ds_read_b128 v[196:199], v231 offset:21504
	ds_read_b128 v[200:203], v231 offset:22528
	ds_read_b128 v[204:207], v231 offset:23552
	global_load_lds_dwordx4 v[164:165], off
	s_add_i32 m0, s31, 0x2000
	v_lshl_add_u64 v[168:169], s[34:35], 0, v[130:131]
	s_add_u32 s34, s34, s60
	s_addc_u32 s35, s35, s61
	s_add_i32 s27, s27, s0
	global_load_lds_dwordx4 v[168:169], off
	v_lshl_add_u64 v[170:171], s[34:35], 0, v[166:167]
	s_mov_b32 m0, s27
	v_lshl_add_u64 v[208:209], s[34:35], 0, v[130:131]
	global_load_lds_dwordx4 v[170:171], off
	s_add_i32 m0, s27, 0x2000
	v_lshl_add_u64 v[210:211], s[8:9], 0, v[166:167]
	global_load_lds_dwordx4 v[208:209], off
	s_mov_b32 m0, s2
	v_lshl_add_u64 v[212:213], s[8:9], 0, v[130:131]
	global_load_lds_dwordx4 v[210:211], off
	s_mov_b32 m0, s3
	s_nop 0
	global_load_lds_dwordx4 v[212:213], off
	s_waitcnt vmcnt(8)
	s_waitcnt lgkmcnt(0)
	s_barrier
	s_waitcnt lgkmcnt(0)
	v_mfma_f32_16x16x32_bf16 v[62:65], v[136:139], v[176:179], v[62:65]
	v_mfma_f32_16x16x32_bf16 v[58:61], v[144:147], v[176:179], v[58:61]
	v_mfma_f32_16x16x32_bf16 v[46:49], v[136:139], v[184:187], v[46:49]
	v_mfma_f32_16x16x32_bf16 v[42:45], v[144:147], v[184:187], v[42:45]
	v_mfma_f32_16x16x32_bf16 v[30:33], v[136:139], v[192:195], v[30:33]
	v_mfma_f32_16x16x32_bf16 v[26:29], v[144:147], v[192:195], v[26:29]
	v_mfma_f32_16x16x32_bf16 v[14:17], v[136:139], v[200:203], v[14:17]
	v_mfma_f32_16x16x32_bf16 v[10:13], v[144:147], v[200:203], v[10:13]
	v_mfma_f32_16x16x32_bf16 v[62:65], v[140:143], v[180:183], v[62:65]
	v_mfma_f32_16x16x32_bf16 v[58:61], v[148:151], v[180:183], v[58:61]
	v_mfma_f32_16x16x32_bf16 v[46:49], v[140:143], v[188:191], v[46:49]
	v_mfma_f32_16x16x32_bf16 v[42:45], v[148:151], v[188:191], v[42:45]
	v_mfma_f32_16x16x32_bf16 v[30:33], v[140:143], v[196:199], v[30:33]
	v_mfma_f32_16x16x32_bf16 v[26:29], v[148:151], v[196:199], v[26:29]
	v_mfma_f32_16x16x32_bf16 v[14:17], v[140:143], v[204:207], v[14:17]
	v_mfma_f32_16x16x32_bf16 v[10:13], v[148:151], v[204:207], v[10:13]
	v_mfma_f32_16x16x32_bf16 v[54:57], v[152:155], v[176:179], v[54:57]
	v_mfma_f32_16x16x32_bf16 v[50:53], v[160:163], v[176:179], v[50:53]
	v_mfma_f32_16x16x32_bf16 v[38:41], v[152:155], v[184:187], v[38:41]
	v_mfma_f32_16x16x32_bf16 v[34:37], v[160:163], v[184:187], v[34:37]
	v_mfma_f32_16x16x32_bf16 v[22:25], v[152:155], v[192:195], v[22:25]
	v_mfma_f32_16x16x32_bf16 v[18:21], v[160:163], v[192:195], v[18:21]
	v_mfma_f32_16x16x32_bf16 v[6:9], v[152:155], v[200:203], v[6:9]
	v_mfma_f32_16x16x32_bf16 v[2:5], v[160:163], v[200:203], v[2:5]
	v_mfma_f32_16x16x32_bf16 v[54:57], v[156:159], v[180:183], v[54:57]
	v_mfma_f32_16x16x32_bf16 v[50:53], v[172:175], v[180:183], v[50:53]
	v_mfma_f32_16x16x32_bf16 v[38:41], v[156:159], v[188:191], v[38:41]
	v_mfma_f32_16x16x32_bf16 v[34:37], v[172:175], v[188:191], v[34:37]
	v_mfma_f32_16x16x32_bf16 v[22:25], v[156:159], v[196:199], v[22:25]
	v_mfma_f32_16x16x32_bf16 v[18:21], v[172:175], v[196:199], v[18:21]
	v_mfma_f32_16x16x32_bf16 v[6:9], v[156:159], v[204:207], v[6:9]
	v_mfma_f32_16x16x32_bf16 v[2:5], v[172:175], v[204:207], v[2:5]
	s_barrier
; #define PG8_STAGE(bufoff, gbase, voff) do { _Pragma("unroll") for (int _i = 0; _i < 2; ++_i) \
;         __builtin_amdgcn_global_load_lds((const unsigned*)((const char*)(gbase) + (voff)[_i]), (PG8_LAS unsigned*)(lds + (bufoff) + ldsw + _i * 8192), 16, 0, 0); } while (0)
; #define PG8_LDA(dst, b, h) do { _Pragma("unroll") for (int m = 0; m < 4; ++m) _Pragma("unroll") for (int k = 0; k < 2; ++k) dst[m][k] = *(const PG8_LAS bf16x8*)(lds + PG8_SA(b, h) + aoff + m * 2048 + k * 1024); } while (0)
; #define PG8_LDB(dst, b, h) do { _Pragma("unroll") for (int n = 0; n < 2; ++n) _Pragma("unroll") for (int k = 0; k < 2; ++k) dst[n][k] = *(const PG8_LAS bf16x8*)(lds + PG8_SB(b, h) + boff + n * 2048 + k * 1024); } while (0)
; #define PG8_MMA(ai, bj, At, Bt) do { __builtin_amdgcn_s_setprio(1); _Pragma("unroll") for (int m = 0; m < 4; ++m) _Pragma("unroll") for (int n = 0; n < 2; ++n) _Pragma("unroll") for (int k = 0; k < 2; ++k) \
;         acc[ai][bj][m][n] = __builtin_amdgcn_mfma_f32_16x16x32_bf16(Bt[n][k], At[m][k], acc[ai][bj][m][n], 0, 0, 0); __builtin_amdgcn_s_setprio(0); } while (0)
; #define PG8_WAIT_V(n) asm volatile("s_waitcnt vmcnt(" #n ")" ::: "memory")
; #define PG8_WAIT_L(n) asm volatile("s_waitcnt lgkmcnt(" #n ")" ::: "memory")
; #define PG8_BAR __builtin_amdgcn_s_barrier()
; #define PG8_SCHED __builtin_amdgcn_sched_barrier(0)
;     ...
;             PG8_LDB(B0, 1, 0); PG8_LDB(B1, 1, 1); PG8_SCHED; PG8_LDA(At, 1, 0); PG8_STAGE(PG8_SA(0, 1), a2 + hstepA, voffA);
;             PG8_WAIT_V(8); PG8_WAIT_L(0); PG8_BAR; PG8_MMA(0, 0, At, B0); PG8_MMA(0, 1, At, B1); PG8_BAR; PG8_SCHED;
;             PG8_LDA(At, 1, 1); PG8_STAGE(PG8_SB(1, 0), b3, voffB); PG8_STAGE(PG8_SB(1, 1), b3 + hstepB, voffB); PG8_STAGE(PG8_SA(1, 0), a3, voffA);
;             PG8_WAIT_V(8); PG8_WAIT_L(0); PG8_BAR; PG8_MMA(1, 0, At, B0); PG8_MMA(1, 1, At, B1); PG8_BAR; PG8_SCHED;
	s_add_i32 s27, 0, 0x18000
	s_add_i32 s31, 0, 0x1c000
	v_add_u32_e32 v148, s27, v229
	v_add_u32_e32 v172, s31, v229
	ds_read_b128 v[136:139], v148
	ds_read_b128 v[140:143], v148 offset:1024
	ds_read_b128 v[144:147], v148 offset:2048
	ds_read_b128 v[148:151], v148 offset:3072
	ds_read_b128 v[152:155], v172
	ds_read_b128 v[156:159], v172 offset:1024
	ds_read_b128 v[160:163], v172 offset:2048
	ds_read_b128 v[172:175], v172 offset:3072
	s_add_u32 s8, s8, s60
	s_addc_u32 s9, s9, s61
	s_mov_b32 m0, s14
	v_lshl_add_u64 v[214:215], s[8:9], 0, v[166:167]
	ds_read_b128 v[176:179], v231 offset:32768
	ds_read_b128 v[180:183], v231 offset:33792
	ds_read_b128 v[184:187], v231 offset:34816
	ds_read_b128 v[188:191], v231 offset:35840
	ds_read_b128 v[192:195], v231 offset:36864
	ds_read_b128 v[196:199], v231 offset:37888
	ds_read_b128 v[200:203], v231 offset:38912
	ds_read_b128 v[204:207], v231 offset:39936
	global_load_lds_dwordx4 v[214:215], off
	v_lshl_add_u64 v[214:215], s[8:9], 0, v[130:131]
	s_mov_b32 m0, s15
	s_nop 0
	global_load_lds_dwordx4 v[214:215], off
	s_waitcnt vmcnt(8)
	s_waitcnt lgkmcnt(0)
	s_barrier
	s_waitcnt lgkmcnt(0)
	v_mfma_f32_16x16x32_bf16 v[126:129], v[136:139], v[176:179], v[126:129]
	v_mfma_f32_16x16x32_bf16 v[122:125], v[144:147], v[176:179], v[122:125]
	v_mfma_f32_16x16x32_bf16 v[110:113], v[136:139], v[184:187], v[110:113]
	v_mfma_f32_16x16x32_bf16 v[106:109], v[144:147], v[184:187], v[106:109]
	v_mfma_f32_16x16x32_bf16 v[94:97], v[136:139], v[192:195], v[94:97]
	v_mfma_f32_16x16x32_bf16 v[90:93], v[144:147], v[192:195], v[90:93]
	v_mfma_f32_16x16x32_bf16 v[78:81], v[136:139], v[200:203], v[78:81]
	v_mfma_f32_16x16x32_bf16 v[74:77], v[144:147], v[200:203], v[74:77]
	v_mfma_f32_16x16x32_bf16 v[126:129], v[140:143], v[180:183], v[126:129]
	v_mfma_f32_16x16x32_bf16 v[122:125], v[148:151], v[180:183], v[122:125]
	v_mfma_f32_16x16x32_bf16 v[110:113], v[140:143], v[188:191], v[110:113]
	v_mfma_f32_16x16x32_bf16 v[106:109], v[148:151], v[188:191], v[106:109]
	v_mfma_f32_16x16x32_bf16 v[94:97], v[140:143], v[196:199], v[94:97]
	v_mfma_f32_16x16x32_bf16 v[90:93], v[148:151], v[196:199], v[90:93]
	v_mfma_f32_16x16x32_bf16 v[78:81], v[140:143], v[204:207], v[78:81]
	v_mfma_f32_16x16x32_bf16 v[74:77], v[148:151], v[204:207], v[74:77]
	v_mfma_f32_16x16x32_bf16 v[118:121], v[152:155], v[176:179], v[118:121]
	v_mfma_f32_16x16x32_bf16 v[114:117], v[160:163], v[176:179], v[114:117]
	v_mfma_f32_16x16x32_bf16 v[102:105], v[152:155], v[184:187], v[102:105]
	v_mfma_f32_16x16x32_bf16 v[98:101], v[160:163], v[184:187], v[98:101]
	v_mfma_f32_16x16x32_bf16 v[86:89], v[152:155], v[192:195], v[86:89]
	v_mfma_f32_16x16x32_bf16 v[82:85], v[160:163], v[192:195], v[82:85]
	v_mfma_f32_16x16x32_bf16 v[70:73], v[152:155], v[200:203], v[70:73]
	v_mfma_f32_16x16x32_bf16 v[66:69], v[160:163], v[200:203], v[66:69]
	v_mfma_f32_16x16x32_bf16 v[118:121], v[156:159], v[180:183], v[118:121]
	v_mfma_f32_16x16x32_bf16 v[114:117], v[172:175], v[180:183], v[114:117]
	v_mfma_f32_16x16x32_bf16 v[102:105], v[156:159], v[188:191], v[102:105]
	v_mfma_f32_16x16x32_bf16 v[98:101], v[172:175], v[188:191], v[98:101]
	v_mfma_f32_16x16x32_bf16 v[86:89], v[156:159], v[196:199], v[86:89]
	v_mfma_f32_16x16x32_bf16 v[82:85], v[172:175], v[196:199], v[82:85]
	v_mfma_f32_16x16x32_bf16 v[70:73], v[156:159], v[204:207], v[70:73]
	v_mfma_f32_16x16x32_bf16 v[66:69], v[172:175], v[204:207], v[66:69]
	s_barrier
	s_add_i32 s8, s27, s0
	v_lshl_add_u64 v[164:165], v[164:165], 0, s[62:63]
	s_mov_b32 m0, s8
	ds_read_b128 v[176:179], v231 offset:49152
	ds_read_b128 v[180:183], v231 offset:50176
	ds_read_b128 v[184:187], v231 offset:51200
	ds_read_b128 v[188:191], v231 offset:52224
	ds_read_b128 v[192:195], v231 offset:53248
	ds_read_b128 v[196:199], v231 offset:54272
	ds_read_b128 v[200:203], v231 offset:55296
	ds_read_b128 v[204:207], v231 offset:56320
	global_load_lds_dwordx4 v[164:165], off
	v_lshl_add_u64 v[164:165], v[168:169], 0, s[62:63]
	s_add_i32 m0, s8, 0x2000
	s_add_i32 s8, s31, s0
	global_load_lds_dwordx4 v[164:165], off
	v_lshl_add_u64 v[164:165], v[170:171], 0, s[62:63]
	s_mov_b32 m0, s8
	s_nop 0
	global_load_lds_dwordx4 v[164:165], off
	v_lshl_add_u64 v[164:165], v[208:209], 0, s[62:63]
	s_add_i32 m0, s8, 0x2000
	s_nop 0
	global_load_lds_dwordx4 v[164:165], off
	v_lshl_add_u64 v[164:165], v[210:211], 0, s[62:63]
	s_mov_b32 m0, s17
	s_nop 0
	global_load_lds_dwordx4 v[164:165], off
	v_lshl_add_u64 v[164:165], v[212:213], 0, s[62:63]
	s_mov_b32 m0, s18
	s_nop 0
	global_load_lds_dwordx4 v[164:165], off
	s_waitcnt vmcnt(8)
	s_waitcnt lgkmcnt(0)
	s_barrier
	s_waitcnt lgkmcnt(0)
	v_mfma_f32_16x16x32_bf16 v[62:65], v[136:139], v[176:179], v[62:65]
	v_mfma_f32_16x16x32_bf16 v[58:61], v[144:147], v[176:179], v[58:61]
	v_mfma_f32_16x16x32_bf16 v[46:49], v[136:139], v[184:187], v[46:49]
	v_mfma_f32_16x16x32_bf16 v[42:45], v[144:147], v[184:187], v[42:45]
	v_mfma_f32_16x16x32_bf16 v[30:33], v[136:139], v[192:195], v[30:33]
	v_mfma_f32_16x16x32_bf16 v[26:29], v[144:147], v[192:195], v[26:29]
	v_mfma_f32_16x16x32_bf16 v[14:17], v[136:139], v[200:203], v[14:17]
	v_mfma_f32_16x16x32_bf16 v[10:13], v[144:147], v[200:203], v[10:13]
	v_mfma_f32_16x16x32_bf16 v[62:65], v[140:143], v[180:183], v[62:65]
	v_mfma_f32_16x16x32_bf16 v[58:61], v[148:151], v[180:183], v[58:61]
	v_mfma_f32_16x16x32_bf16 v[46:49], v[140:143], v[188:191], v[46:49]
	v_mfma_f32_16x16x32_bf16 v[42:45], v[148:151], v[188:191], v[42:45]
	v_mfma_f32_16x16x32_bf16 v[30:33], v[140:143], v[196:199], v[30:33]
	v_mfma_f32_16x16x32_bf16 v[26:29], v[148:151], v[196:199], v[26:29]
	v_mfma_f32_16x16x32_bf16 v[14:17], v[140:143], v[204:207], v[14:17]
	v_mfma_f32_16x16x32_bf16 v[10:13], v[148:151], v[204:207], v[10:13]
	v_mfma_f32_16x16x32_bf16 v[54:57], v[152:155], v[176:179], v[54:57]
	v_mfma_f32_16x16x32_bf16 v[50:53], v[160:163], v[176:179], v[50:53]
	v_mfma_f32_16x16x32_bf16 v[38:41], v[152:155], v[184:187], v[38:41]
	v_mfma_f32_16x16x32_bf16 v[34:37], v[160:163], v[184:187], v[34:37]
	v_mfma_f32_16x16x32_bf16 v[22:25], v[152:155], v[192:195], v[22:25]
	v_mfma_f32_16x16x32_bf16 v[18:21], v[160:163], v[192:195], v[18:21]
	v_mfma_f32_16x16x32_bf16 v[6:9], v[152:155], v[200:203], v[6:9]
	v_mfma_f32_16x16x32_bf16 v[2:5], v[160:163], v[200:203], v[2:5]
	v_mfma_f32_16x16x32_bf16 v[54:57], v[156:159], v[180:183], v[54:57]
	v_mfma_f32_16x16x32_bf16 v[50:53], v[172:175], v[180:183], v[50:53]
	v_mfma_f32_16x16x32_bf16 v[38:41], v[156:159], v[188:191], v[38:41]
	v_mfma_f32_16x16x32_bf16 v[34:37], v[172:175], v[188:191], v[34:37]
	v_mfma_f32_16x16x32_bf16 v[22:25], v[156:159], v[196:199], v[22:25]
	v_mfma_f32_16x16x32_bf16 v[18:21], v[172:175], v[196:199], v[18:21]
	v_mfma_f32_16x16x32_bf16 v[6:9], v[156:159], v[204:207], v[6:9]
	v_mfma_f32_16x16x32_bf16 v[2:5], v[172:175], v[204:207], v[2:5]
	s_barrier
	s_add_u32 s10, s10, 0x100
	s_addc_u32 s11, s11, 0
	s_add_u32 s6, s6, 0x100
	s_addc_u32 s7, s7, 0
	s_cmp_ge_i32 s25, s13
	s_mov_b32 s8, s25
	s_cbranch_scc0 .LBB0_520

; #define PG8_STAGE(bufoff, gbase, voff) do { _Pragma("unroll") for (int _i = 0; _i < 2; ++_i) \
;         __builtin_amdgcn_global_load_lds((const unsigned*)((const char*)(gbase) + (voff)[_i]), (PG8_LAS unsigned*)(lds + (bufoff) + ldsw + _i * 8192), 16, 0, 0); } while (0)
; #define PG8_LDA(dst, b, h) do { _Pragma("unroll") for (int m = 0; m < 4; ++m) _Pragma("unroll") for (int k = 0; k < 2; ++k) dst[m][k] = *(const PG8_LAS bf16x8*)(lds + PG8_SA(b, h) + aoff + m * 2048 + k * 1024); } while (0)
; #define PG8_LDB(dst, b, h) do { _Pragma("unroll") for (int n = 0; n < 2; ++n) _Pragma("unroll") for (int k = 0; k < 2; ++k) dst[n][k] = *(const PG8_LAS bf16x8*)(lds + PG8_SB(b, h) + boff + n * 2048 + k * 1024); } while (0)
; #define PG8_MMA(ai, bj, At, Bt) do { __builtin_amdgcn_s_setprio(1); _Pragma("unroll") for (int m = 0; m < 4; ++m) _Pragma("unroll") for (int n = 0; n < 2; ++n) _Pragma("unroll") for (int k = 0; k < 2; ++k) \
;         acc[ai][bj][m][n] = __builtin_amdgcn_mfma_f32_16x16x32_bf16(Bt[n][k], At[m][k], acc[ai][bj][m][n], 0, 0, 0); __builtin_amdgcn_s_setprio(0); } while (0)
; #define PG8_WAIT_V(n) asm volatile("s_waitcnt vmcnt(" #n ")" ::: "memory")
; #define PG8_WAIT_L(n) asm volatile("s_waitcnt lgkmcnt(" #n ")" ::: "memory")
; #define PG8_BAR __builtin_amdgcn_s_barrier()
; #define PG8_SCHED __builtin_amdgcn_sched_barrier(0)
;     ...
;         for (int t = 0; t < nt; t += 2) {
;             const bool last = (t == nt - 2);
;             const char* a1 = cA + (size_t)(t + 1) * kstep;
;             const char* a2 = last ? nA : cA + (size_t)(t + 2) * kstep; const char* b2 = last ? nB : cB + (size_t)(t + 2) * kstep;
;             const char* a3 = a2 + kstep; const char* b3 = b2 + kstep;
;             if (last && has_next) S.a_ready(nxt);
;             if constexpr (SP2) {
;             PG8_LDB(B0, 0, 0); PG8_LDB(B1, 0, 1); PG8_SCHED; PG8_LDA(At, 0, 0); PG8_STAGE(PG8_SA(1, 1), a1 + hstepA, voffA);
;             PG8_WAIT_V(8); PG8_WAIT_L(0); PG8_BAR; PG8_MMA(0, 0, At, B0); PG8_MMA(0, 1, At, B1); PG8_BAR; PG8_SCHED;
;             PG8_LDA(At, 0, 1); PG8_STAGE(PG8_SB(0, 0), b2, voffB); PG8_STAGE(PG8_SB(0, 1), b2 + hstepB, voffB); PG8_STAGE(PG8_SA(0, 0), a2, voffA);
.LBB0_611:
	s_andn2_b64 vcc, exec, s[86:87]
	s_cbranch_vccnz .LBB0_614
	s_add_u32 s24, s8, 0x100
	s_addc_u32 s25, s9, 0
	s_add_u32 s6, s10, 0x80
	s_addc_u32 s7, s11, 0
	s_mov_b32 s8, 0
	s_add_i32 s10, s8, 2
	s_add_u32 s11, s6, 0x80
	s_addc_u32 s9, s7, 0
	s_add_i32 s27, 0, 0x10000
	s_cmp_eq_u32 s18, s8
	s_cselect_b32 s9, s41, s9
	s_cselect_b32 s8, s40, s11
	v_add_u32_e32 v140, s27, v151
	s_cselect_b32 s35, s91, s25
	s_cselect_b32 s34, s90, s24
	s_add_i32 s11, 0, 0x14000
	ds_read_b128 v[156:159], v140
	ds_read_b128 v[160:163], v140 offset:1024
	ds_read_b128 v[172:175], v140 offset:2048
	ds_read_b128 v[176:179], v140 offset:3072
	v_add_u32_e32 v140, s11, v151
	ds_read_b128 v[180:183], v140
	ds_read_b128 v[184:187], v140 offset:1024
	ds_read_b128 v[188:191], v140 offset:2048
	ds_read_b128 v[192:195], v140 offset:3072
	v_lshl_add_u64 v[164:165], s[6:7], 0, v[138:139]
	s_add_i32 m0, s3, 0xc000
	ds_read_b128 v[196:199], v154
	ds_read_b128 v[200:203], v154 offset:1024
	ds_read_b128 v[204:207], v154 offset:2048
	ds_read_b128 v[208:211], v154 offset:3072
	ds_read_b128 v[212:215], v154 offset:4096
	ds_read_b128 v[216:219], v154 offset:5120
	ds_read_b128 v[220:223], v154 offset:6144
	ds_read_b128 v[224:227], v154 offset:7168
	global_load_lds_dwordx4 v[164:165], off
	v_lshl_add_u64 v[164:165], s[6:7], 0, v[136:137]
	s_add_i32 m0, s3, 0xe000
	s_nop 0
	global_load_lds_dwordx4 v[164:165], off
	s_waitcnt vmcnt(8)
	s_waitcnt lgkmcnt(0)
	s_barrier
	s_waitcnt lgkmcnt(0)
	v_mfma_f32_16x16x32_bf16 v[126:129], v[156:159], v[196:199], 0
	v_mfma_f32_16x16x32_bf16 v[122:125], v[172:175], v[196:199], 0
	v_mfma_f32_16x16x32_bf16 v[110:113], v[156:159], v[204:207], 0
	v_mfma_f32_16x16x32_bf16 v[106:109], v[172:175], v[204:207], 0
	v_mfma_f32_16x16x32_bf16 v[94:97], v[156:159], v[212:215], 0
	v_mfma_f32_16x16x32_bf16 v[90:93], v[172:175], v[212:215], 0
	v_mfma_f32_16x16x32_bf16 v[78:81], v[156:159], v[220:223], 0
	v_mfma_f32_16x16x32_bf16 v[74:77], v[172:175], v[220:223], 0
	v_mfma_f32_16x16x32_bf16 v[126:129], v[160:163], v[200:203], v[126:129]
	v_mfma_f32_16x16x32_bf16 v[122:125], v[176:179], v[200:203], v[122:125]
	v_mfma_f32_16x16x32_bf16 v[110:113], v[160:163], v[208:211], v[110:113]
	v_mfma_f32_16x16x32_bf16 v[106:109], v[176:179], v[208:211], v[106:109]
	v_mfma_f32_16x16x32_bf16 v[94:97], v[160:163], v[216:219], v[94:97]
	v_mfma_f32_16x16x32_bf16 v[90:93], v[176:179], v[216:219], v[90:93]
	v_mfma_f32_16x16x32_bf16 v[78:81], v[160:163], v[224:227], v[78:81]
	v_mfma_f32_16x16x32_bf16 v[74:77], v[176:179], v[224:227], v[74:77]
	v_mfma_f32_16x16x32_bf16 v[118:121], v[180:183], v[196:199], 0
	v_mfma_f32_16x16x32_bf16 v[114:117], v[188:191], v[196:199], 0
	v_mfma_f32_16x16x32_bf16 v[102:105], v[180:183], v[204:207], 0
	v_mfma_f32_16x16x32_bf16 v[98:101], v[188:191], v[204:207], 0
	v_mfma_f32_16x16x32_bf16 v[86:89], v[180:183], v[212:215], 0
	v_mfma_f32_16x16x32_bf16 v[82:85], v[188:191], v[212:215], 0
	v_mfma_f32_16x16x32_bf16 v[70:73], v[180:183], v[220:223], 0
	v_mfma_f32_16x16x32_bf16 v[66:69], v[188:191], v[220:223], 0
	v_mfma_f32_16x16x32_bf16 v[118:121], v[184:187], v[200:203], v[118:121]
	v_mfma_f32_16x16x32_bf16 v[114:117], v[192:195], v[200:203], v[114:117]
	v_mfma_f32_16x16x32_bf16 v[102:105], v[184:187], v[208:211], v[102:105]
	v_mfma_f32_16x16x32_bf16 v[98:101], v[192:195], v[208:211], v[98:101]
	v_mfma_f32_16x16x32_bf16 v[86:89], v[184:187], v[216:219], v[86:89]
	v_mfma_f32_16x16x32_bf16 v[82:85], v[192:195], v[216:219], v[82:85]
	v_mfma_f32_16x16x32_bf16 v[70:73], v[184:187], v[224:227], v[70:73]
	v_mfma_f32_16x16x32_bf16 v[66:69], v[192:195], v[224:227], v[66:69]
	s_barrier
	s_add_i32 s27, s27, s0
	v_lshl_add_u64 v[164:165], s[34:35], 0, v[166:167]
	s_mov_b32 m0, s27
	ds_read_b128 v[196:199], v154 offset:16384
	ds_read_b128 v[200:203], v154 offset:17408
	ds_read_b128 v[204:207], v154 offset:18432
	ds_read_b128 v[208:211], v154 offset:19456
	ds_read_b128 v[212:215], v154 offset:20480
	ds_read_b128 v[216:219], v154 offset:21504
	ds_read_b128 v[220:223], v154 offset:22528
	ds_read_b128 v[224:227], v154 offset:23552
	global_load_lds_dwordx4 v[164:165], off
	s_add_i32 m0, s27, 0x2000
	v_lshl_add_u64 v[168:169], s[34:35], 0, v[130:131]
	s_add_u32 s34, s34, s58
	s_addc_u32 s35, s35, s59
	s_add_i32 s11, s11, s0
	global_load_lds_dwordx4 v[168:169], off
	v_lshl_add_u64 v[170:171], s[34:35], 0, v[166:167]
	s_mov_b32 m0, s11
	v_lshl_add_u64 v[228:229], s[34:35], 0, v[130:131]
	global_load_lds_dwordx4 v[170:171], off
	s_add_i32 m0, s11, 0x2000
	v_lshl_add_u64 v[230:231], s[8:9], 0, v[134:135]
	global_load_lds_dwordx4 v[228:229], off
	s_mov_b32 m0, s3
	v_lshl_add_u64 v[232:233], s[8:9], 0, v[132:133]
	global_load_lds_dwordx4 v[230:231], off
	s_mov_b32 m0, s12
	s_nop 0
	global_load_lds_dwordx4 v[232:233], off
	s_waitcnt vmcnt(8)
	s_waitcnt lgkmcnt(0)
	s_barrier
; #define PG8_STAGE(bufoff, gbase, voff) do { _Pragma("unroll") for (int _i = 0; _i < 2; ++_i) \
;         __builtin_amdgcn_global_load_lds((const unsigned*)((const char*)(gbase) + (voff)[_i]), (PG8_LAS unsigned*)(lds + (bufoff) + ldsw + _i * 8192), 16, 0, 0); } while (0)
; #define PG8_LDA(dst, b, h) do { _Pragma("unroll") for (int m = 0; m < 4; ++m) _Pragma("unroll") for (int k = 0; k < 2; ++k) dst[m][k] = *(const PG8_LAS bf16x8*)(lds + PG8_SA(b, h) + aoff + m * 2048 + k * 1024); } while (0)
; #define PG8_LDB(dst, b, h) do { _Pragma("unroll") for (int n = 0; n < 2; ++n) _Pragma("unroll") for (int k = 0; k < 2; ++k) dst[n][k] = *(const PG8_LAS bf16x8*)(lds + PG8_SB(b, h) + boff + n * 2048 + k * 1024); } while (0)
; #define PG8_MMA(ai, bj, At, Bt) do { __builtin_amdgcn_s_setprio(1); _Pragma("unroll") for (int m = 0; m < 4; ++m) _Pragma("unroll") for (int n = 0; n < 2; ++n) _Pragma("unroll") for (int k = 0; k < 2; ++k) \
;         acc[ai][bj][m][n] = __builtin_amdgcn_mfma_f32_16x16x32_bf16(Bt[n][k], At[m][k], acc[ai][bj][m][n], 0, 0, 0); __builtin_amdgcn_s_setprio(0); } while (0)
; #define PG8_WAIT_V(n) asm volatile("s_waitcnt vmcnt(" #n ")" ::: "memory")
; #define PG8_WAIT_L(n) asm volatile("s_waitcnt lgkmcnt(" #n ")" ::: "memory")
; #define PG8_BAR __builtin_amdgcn_s_barrier()
; #define PG8_SCHED __builtin_amdgcn_sched_barrier(0)
;     ...
;             PG8_WAIT_V(8); PG8_WAIT_L(0); PG8_BAR; PG8_MMA(1, 0, At, B0); PG8_MMA(1, 1, At, B1); PG8_BAR; PG8_SCHED;
;             PG8_LDB(B0, 1, 0); PG8_LDB(B1, 1, 1); PG8_SCHED; PG8_LDA(At, 1, 0); PG8_STAGE(PG8_SA(0, 1), a2 + hstepA, voffA);
;             PG8_WAIT_V(8); PG8_WAIT_L(0); PG8_BAR; PG8_MMA(0, 0, At, B0); PG8_MMA(0, 1, At, B1); PG8_BAR; PG8_SCHED;
	s_waitcnt lgkmcnt(0)
	v_mfma_f32_16x16x32_bf16 v[62:65], v[156:159], v[196:199], 0
	v_mfma_f32_16x16x32_bf16 v[58:61], v[172:175], v[196:199], 0
	v_mfma_f32_16x16x32_bf16 v[46:49], v[156:159], v[204:207], 0
	v_mfma_f32_16x16x32_bf16 v[42:45], v[172:175], v[204:207], 0
	v_mfma_f32_16x16x32_bf16 v[30:33], v[156:159], v[212:215], 0
	v_mfma_f32_16x16x32_bf16 v[26:29], v[172:175], v[212:215], 0
	v_mfma_f32_16x16x32_bf16 v[14:17], v[156:159], v[220:223], 0
	v_mfma_f32_16x16x32_bf16 v[10:13], v[172:175], v[220:223], 0
	v_mfma_f32_16x16x32_bf16 v[62:65], v[160:163], v[200:203], v[62:65]
	v_mfma_f32_16x16x32_bf16 v[58:61], v[176:179], v[200:203], v[58:61]
	v_mfma_f32_16x16x32_bf16 v[46:49], v[160:163], v[208:211], v[46:49]
	v_mfma_f32_16x16x32_bf16 v[42:45], v[176:179], v[208:211], v[42:45]
	v_mfma_f32_16x16x32_bf16 v[30:33], v[160:163], v[216:219], v[30:33]
	v_mfma_f32_16x16x32_bf16 v[26:29], v[176:179], v[216:219], v[26:29]
	v_mfma_f32_16x16x32_bf16 v[14:17], v[160:163], v[224:227], v[14:17]
	v_mfma_f32_16x16x32_bf16 v[10:13], v[176:179], v[224:227], v[10:13]
	v_mfma_f32_16x16x32_bf16 v[54:57], v[180:183], v[196:199], 0
	v_mfma_f32_16x16x32_bf16 v[50:53], v[188:191], v[196:199], 0
	v_mfma_f32_16x16x32_bf16 v[38:41], v[180:183], v[204:207], 0
	v_mfma_f32_16x16x32_bf16 v[34:37], v[188:191], v[204:207], 0
	v_mfma_f32_16x16x32_bf16 v[22:25], v[180:183], v[212:215], 0
	v_mfma_f32_16x16x32_bf16 v[18:21], v[188:191], v[212:215], 0
	v_mfma_f32_16x16x32_bf16 v[6:9], v[180:183], v[220:223], 0
	v_mfma_f32_16x16x32_bf16 v[2:5], v[188:191], v[220:223], 0
	v_mfma_f32_16x16x32_bf16 v[54:57], v[184:187], v[200:203], v[54:57]
	v_mfma_f32_16x16x32_bf16 v[50:53], v[192:195], v[200:203], v[50:53]
	v_mfma_f32_16x16x32_bf16 v[38:41], v[184:187], v[208:211], v[38:41]
	v_mfma_f32_16x16x32_bf16 v[34:37], v[192:195], v[208:211], v[34:37]
	v_mfma_f32_16x16x32_bf16 v[22:25], v[184:187], v[216:219], v[22:25]
	v_mfma_f32_16x16x32_bf16 v[18:21], v[192:195], v[216:219], v[18:21]
	v_mfma_f32_16x16x32_bf16 v[6:9], v[184:187], v[224:227], v[6:9]
	v_mfma_f32_16x16x32_bf16 v[2:5], v[192:195], v[224:227], v[2:5]
	s_barrier
	s_add_i32 s11, 0, 0x18000
	v_add_u32_e32 v140, s11, v151
	s_add_i32 s27, 0, 0x1c000
	ds_read_b128 v[156:159], v140
	ds_read_b128 v[160:163], v140 offset:1024
	ds_read_b128 v[172:175], v140 offset:2048
	ds_read_b128 v[176:179], v140 offset:3072
	v_add_u32_e32 v140, s27, v151
	ds_read_b128 v[180:183], v140
	ds_read_b128 v[184:187], v140 offset:1024
	ds_read_b128 v[188:191], v140 offset:2048
	ds_read_b128 v[192:195], v140 offset:3072
	s_add_u32 s8, s8, s58
	s_addc_u32 s9, s9, s59
	s_mov_b32 m0, s13
	v_lshl_add_u64 v[234:235], s[8:9], 0, v[134:135]
	ds_read_b128 v[196:199], v154 offset:32768
	ds_read_b128 v[200:203], v154 offset:33792
	ds_read_b128 v[204:207], v154 offset:34816
	ds_read_b128 v[208:211], v154 offset:35840
	ds_read_b128 v[212:215], v154 offset:36864
	ds_read_b128 v[216:219], v154 offset:37888
	ds_read_b128 v[220:223], v154 offset:38912
	ds_read_b128 v[224:227], v154 offset:39936
	global_load_lds_dwordx4 v[234:235], off
	v_lshl_add_u64 v[234:235], s[8:9], 0, v[132:133]
	s_mov_b32 m0, s14
	s_nop 0
	global_load_lds_dwordx4 v[234:235], off
	s_waitcnt vmcnt(8)
	s_waitcnt lgkmcnt(0)
	s_barrier
	s_waitcnt lgkmcnt(0)
	v_mfma_f32_16x16x32_bf16 v[126:129], v[156:159], v[196:199], v[126:129]
	v_mfma_f32_16x16x32_bf16 v[122:125], v[172:175], v[196:199], v[122:125]
	v_mfma_f32_16x16x32_bf16 v[110:113], v[156:159], v[204:207], v[110:113]
	v_mfma_f32_16x16x32_bf16 v[106:109], v[172:175], v[204:207], v[106:109]
	v_mfma_f32_16x16x32_bf16 v[94:97], v[156:159], v[212:215], v[94:97]
	v_mfma_f32_16x16x32_bf16 v[90:93], v[172:175], v[212:215], v[90:93]
	v_mfma_f32_16x16x32_bf16 v[78:81], v[156:159], v[220:223], v[78:81]
	v_mfma_f32_16x16x32_bf16 v[74:77], v[172:175], v[220:223], v[74:77]
	v_mfma_f32_16x16x32_bf16 v[126:129], v[160:163], v[200:203], v[126:129]
	v_mfma_f32_16x16x32_bf16 v[122:125], v[176:179], v[200:203], v[122:125]
	v_mfma_f32_16x16x32_bf16 v[110:113], v[160:163], v[208:211], v[110:113]
	v_mfma_f32_16x16x32_bf16 v[106:109], v[176:179], v[208:211], v[106:109]
	v_mfma_f32_16x16x32_bf16 v[94:97], v[160:163], v[216:219], v[94:97]
	v_mfma_f32_16x16x32_bf16 v[90:93], v[176:179], v[216:219], v[90:93]
	v_mfma_f32_16x16x32_bf16 v[78:81], v[160:163], v[224:227], v[78:81]
	v_mfma_f32_16x16x32_bf16 v[74:77], v[176:179], v[224:227], v[74:77]
	v_mfma_f32_16x16x32_bf16 v[118:121], v[180:183], v[196:199], v[118:121]
	v_mfma_f32_16x16x32_bf16 v[114:117], v[188:191], v[196:199], v[114:117]
	v_mfma_f32_16x16x32_bf16 v[102:105], v[180:183], v[204:207], v[102:105]
	v_mfma_f32_16x16x32_bf16 v[98:101], v[188:191], v[204:207], v[98:101]
	v_mfma_f32_16x16x32_bf16 v[86:89], v[180:183], v[212:215], v[86:89]
	v_mfma_f32_16x16x32_bf16 v[82:85], v[188:191], v[212:215], v[82:85]
	v_mfma_f32_16x16x32_bf16 v[70:73], v[180:183], v[220:223], v[70:73]
	v_mfma_f32_16x16x32_bf16 v[66:69], v[188:191], v[220:223], v[66:69]
	v_mfma_f32_16x16x32_bf16 v[118:121], v[184:187], v[200:203], v[118:121]
	v_mfma_f32_16x16x32_bf16 v[114:117], v[192:195], v[200:203], v[114:117]
	v_mfma_f32_16x16x32_bf16 v[102:105], v[184:187], v[208:211], v[102:105]
	v_mfma_f32_16x16x32_bf16 v[98:101], v[192:195], v[208:211], v[98:101]
	v_mfma_f32_16x16x32_bf16 v[86:89], v[184:187], v[216:219], v[86:89]
	v_mfma_f32_16x16x32_bf16 v[82:85], v[192:195], v[216:219], v[82:85]
	v_mfma_f32_16x16x32_bf16 v[70:73], v[184:187], v[224:227], v[70:73]
	v_mfma_f32_16x16x32_bf16 v[66:69], v[192:195], v[224:227], v[66:69]
	s_barrier
; #define PG8_STAGE(bufoff, gbase, voff) do { _Pragma("unroll") for (int _i = 0; _i < 2; ++_i) \
;         __builtin_amdgcn_global_load_lds((const unsigned*)((const char*)(gbase) + (voff)[_i]), (PG8_LAS unsigned*)(lds + (bufoff) + ldsw + _i * 8192), 16, 0, 0); } while (0)
; #define PG8_LDA(dst, b, h) do { _Pragma("unroll") for (int m = 0; m < 4; ++m) _Pragma("unroll") for (int k = 0; k < 2; ++k) dst[m][k] = *(const PG8_LAS bf16x8*)(lds + PG8_SA(b, h) + aoff + m * 2048 + k * 1024); } while (0)
; #define PG8_LDB(dst, b, h) do { _Pragma("unroll") for (int n = 0; n < 2; ++n) _Pragma("unroll") for (int k = 0; k < 2; ++k) dst[n][k] = *(const PG8_LAS bf16x8*)(lds + PG8_SB(b, h) + boff + n * 2048 + k * 1024); } while (0)
; #define PG8_MMA(ai, bj, At, Bt) do { __builtin_amdgcn_s_setprio(1); _Pragma("unroll") for (int m = 0; m < 4; ++m) _Pragma("unroll") for (int n = 0; n < 2; ++n) _Pragma("unroll") for (int k = 0; k < 2; ++k) \
;         acc[ai][bj][m][n] = __builtin_amdgcn_mfma_f32_16x16x32_bf16(Bt[n][k], At[m][k], acc[ai][bj][m][n], 0, 0, 0); __builtin_amdgcn_s_setprio(0); } while (0)
; #define PG8_WAIT_V(n) asm volatile("s_waitcnt vmcnt(" #n ")" ::: "memory")
; #define PG8_WAIT_L(n) asm volatile("s_waitcnt lgkmcnt(" #n ")" ::: "memory")
; #define PG8_BAR __builtin_amdgcn_s_barrier()
; #define PG8_SCHED __builtin_amdgcn_sched_barrier(0)
;     ...
;         for (int t = 0; t < nt; t += 2) {
;             const bool last = (t == nt - 2);
;             const char* a1 = cA + (size_t)(t + 1) * kstep;
;             const char* a2 = last ? nA : cA + (size_t)(t + 2) * kstep; const char* b2 = last ? nB : cB + (size_t)(t + 2) * kstep;
;             const char* a3 = a2 + kstep; const char* b3 = b2 + kstep;
;             if (last && has_next) S.a_ready(nxt);
;             if constexpr (SP2) {
;             PG8_LDB(B0, 0, 0); PG8_LDB(B1, 0, 1); PG8_SCHED; PG8_LDA(At, 0, 0); PG8_STAGE(PG8_SA(1, 1), a1 + hstepA, voffA);
;             PG8_WAIT_V(8); PG8_WAIT_L(0); PG8_BAR; PG8_MMA(0, 0, At, B0); PG8_MMA(0, 1, At, B1); PG8_BAR; PG8_SCHED;
;     ...
;             PG8_LDA(At, 1, 1); PG8_STAGE(PG8_SB(1, 0), b3, voffB); PG8_STAGE(PG8_SB(1, 1), b3 + hstepB, voffB); PG8_STAGE(PG8_SA(1, 0), a3, voffA);
;             PG8_WAIT_V(8); PG8_WAIT_L(0); PG8_BAR; PG8_MMA(1, 0, At, B0); PG8_MMA(1, 1, At, B1); PG8_BAR; PG8_SCHED;
	s_add_i32 s8, s11, s0
	v_lshl_add_u64 v[164:165], v[164:165], 0, s[62:63]
	s_mov_b32 m0, s8
	ds_read_b128 v[196:199], v154 offset:49152
	ds_read_b128 v[200:203], v154 offset:50176
	ds_read_b128 v[204:207], v154 offset:51200
	ds_read_b128 v[208:211], v154 offset:52224
	ds_read_b128 v[212:215], v154 offset:53248
	ds_read_b128 v[216:219], v154 offset:54272
	ds_read_b128 v[220:223], v154 offset:55296
	ds_read_b128 v[224:227], v154 offset:56320
	global_load_lds_dwordx4 v[164:165], off
	v_lshl_add_u64 v[164:165], v[168:169], 0, s[62:63]
	s_add_i32 m0, s8, 0x2000
	s_add_i32 s8, s27, s0
	global_load_lds_dwordx4 v[164:165], off
	v_lshl_add_u64 v[164:165], v[170:171], 0, s[62:63]
	s_mov_b32 m0, s8
	s_nop 0
	global_load_lds_dwordx4 v[164:165], off
	v_lshl_add_u64 v[164:165], v[228:229], 0, s[62:63]
	s_add_i32 m0, s8, 0x2000
	s_nop 0
	global_load_lds_dwordx4 v[164:165], off
	v_lshl_add_u64 v[164:165], v[230:231], 0, s[62:63]
	s_mov_b32 m0, s16
	s_nop 0
	global_load_lds_dwordx4 v[164:165], off
	v_lshl_add_u64 v[164:165], v[232:233], 0, s[62:63]
	s_mov_b32 m0, s17
	s_nop 0
	global_load_lds_dwordx4 v[164:165], off
	s_waitcnt vmcnt(8)
	s_waitcnt lgkmcnt(0)
	s_barrier
	s_waitcnt lgkmcnt(0)
	v_mfma_f32_16x16x32_bf16 v[62:65], v[156:159], v[196:199], v[62:65]
	v_mfma_f32_16x16x32_bf16 v[58:61], v[172:175], v[196:199], v[58:61]
	v_mfma_f32_16x16x32_bf16 v[46:49], v[156:159], v[204:207], v[46:49]
	v_mfma_f32_16x16x32_bf16 v[42:45], v[172:175], v[204:207], v[42:45]
	v_mfma_f32_16x16x32_bf16 v[30:33], v[156:159], v[212:215], v[30:33]
	v_mfma_f32_16x16x32_bf16 v[26:29], v[172:175], v[212:215], v[26:29]
	v_mfma_f32_16x16x32_bf16 v[14:17], v[156:159], v[220:223], v[14:17]
	v_mfma_f32_16x16x32_bf16 v[10:13], v[172:175], v[220:223], v[10:13]
	v_mfma_f32_16x16x32_bf16 v[62:65], v[160:163], v[200:203], v[62:65]
	v_mfma_f32_16x16x32_bf16 v[58:61], v[176:179], v[200:203], v[58:61]
	v_mfma_f32_16x16x32_bf16 v[46:49], v[160:163], v[208:211], v[46:49]
	v_mfma_f32_16x16x32_bf16 v[42:45], v[176:179], v[208:211], v[42:45]
	v_mfma_f32_16x16x32_bf16 v[30:33], v[160:163], v[216:219], v[30:33]
	v_mfma_f32_16x16x32_bf16 v[26:29], v[176:179], v[216:219], v[26:29]
	v_mfma_f32_16x16x32_bf16 v[14:17], v[160:163], v[224:227], v[14:17]
	v_mfma_f32_16x16x32_bf16 v[10:13], v[176:179], v[224:227], v[10:13]
	v_mfma_f32_16x16x32_bf16 v[54:57], v[180:183], v[196:199], v[54:57]
	v_mfma_f32_16x16x32_bf16 v[50:53], v[188:191], v[196:199], v[50:53]
	v_mfma_f32_16x16x32_bf16 v[38:41], v[180:183], v[204:207], v[38:41]
	v_mfma_f32_16x16x32_bf16 v[34:37], v[188:191], v[204:207], v[34:37]
	v_mfma_f32_16x16x32_bf16 v[22:25], v[180:183], v[212:215], v[22:25]
	v_mfma_f32_16x16x32_bf16 v[18:21], v[188:191], v[212:215], v[18:21]
	v_mfma_f32_16x16x32_bf16 v[6:9], v[180:183], v[220:223], v[6:9]
	v_mfma_f32_16x16x32_bf16 v[2:5], v[188:191], v[220:223], v[2:5]
	v_mfma_f32_16x16x32_bf16 v[54:57], v[184:187], v[200:203], v[54:57]
	v_mfma_f32_16x16x32_bf16 v[50:53], v[192:195], v[200:203], v[50:53]
	v_mfma_f32_16x16x32_bf16 v[38:41], v[184:187], v[208:211], v[38:41]
	v_mfma_f32_16x16x32_bf16 v[34:37], v[192:195], v[208:211], v[34:37]
	v_mfma_f32_16x16x32_bf16 v[22:25], v[184:187], v[216:219], v[22:25]
	v_mfma_f32_16x16x32_bf16 v[18:21], v[192:195], v[216:219], v[18:21]
	v_mfma_f32_16x16x32_bf16 v[6:9], v[184:187], v[224:227], v[6:9]
	v_mfma_f32_16x16x32_bf16 v[2:5], v[192:195], v[224:227], v[2:5]
	s_barrier
	s_add_u32 s24, s24, 0x100
	s_addc_u32 s25, s25, 0
	s_add_u32 s6, s6, 0x100
	s_addc_u32 s7, s7, 0
	s_cmp_ge_i32 s10, s15
	s_mov_b32 s8, s10
	s_cbranch_scc1 .LBB0_614
.LBB0_613:
	s_add_i32 s10, s8, 2
	s_add_u32 s11, s6, 0x80
	s_addc_u32 s9, s7, 0
	s_add_i32 s27, 0, 0x10000
	s_cmp_eq_u32 s18, s8
	s_cselect_b32 s9, s41, s9
	s_cselect_b32 s8, s40, s11
	v_add_u32_e32 v140, s27, v151
	s_cselect_b32 s35, s91, s25
	s_cselect_b32 s34, s90, s24
	s_add_i32 s11, 0, 0x14000
	ds_read_b128 v[156:159], v140
	ds_read_b128 v[160:163], v140 offset:1024
	ds_read_b128 v[172:175], v140 offset:2048
	ds_read_b128 v[176:179], v140 offset:3072
	v_add_u32_e32 v140, s11, v151
	ds_read_b128 v[180:183], v140
	ds_read_b128 v[184:187], v140 offset:1024
	ds_read_b128 v[188:191], v140 offset:2048
	ds_read_b128 v[192:195], v140 offset:3072
	v_lshl_add_u64 v[164:165], s[6:7], 0, v[138:139]
	s_add_i32 m0, s3, 0xc000
	ds_read_b128 v[196:199], v154
	ds_read_b128 v[200:203], v154 offset:1024
	ds_read_b128 v[204:207], v154 offset:2048
	ds_read_b128 v[208:211], v154 offset:3072
	ds_read_b128 v[212:215], v154 offset:4096
	ds_read_b128 v[216:219], v154 offset:5120
	ds_read_b128 v[220:223], v154 offset:6144
	ds_read_b128 v[224:227], v154 offset:7168
	global_load_lds_dwordx4 v[164:165], off
	v_lshl_add_u64 v[164:165], s[6:7], 0, v[136:137]
	s_add_i32 m0, s3, 0xe000
	s_nop 0
	global_load_lds_dwordx4 v[164:165], off
	s_waitcnt vmcnt(8)
	s_waitcnt lgkmcnt(0)
	s_barrier
; #define PG8_STAGE(bufoff, gbase, voff) do { _Pragma("unroll") for (int _i = 0; _i < 2; ++_i) \
;         __builtin_amdgcn_global_load_lds((const unsigned*)((const char*)(gbase) + (voff)[_i]), (PG8_LAS unsigned*)(lds + (bufoff) + ldsw + _i * 8192), 16, 0, 0); } while (0)
; #define PG8_LDA(dst, b, h) do { _Pragma("unroll") for (int m = 0; m < 4; ++m) _Pragma("unroll") for (int k = 0; k < 2; ++k) dst[m][k] = *(const PG8_LAS bf16x8*)(lds + PG8_SA(b, h) + aoff + m * 2048 + k * 1024); } while (0)
; #define PG8_MMA(ai, bj, At, Bt) do { __builtin_amdgcn_s_setprio(1); _Pragma("unroll") for (int m = 0; m < 4; ++m) _Pragma("unroll") for (int n = 0; n < 2; ++n) _Pragma("unroll") for (int k = 0; k < 2; ++k) \
;         acc[ai][bj][m][n] = __builtin_amdgcn_mfma_f32_16x16x32_bf16(Bt[n][k], At[m][k], acc[ai][bj][m][n], 0, 0, 0); __builtin_amdgcn_s_setprio(0); } while (0)
; #define PG8_WAIT_V(n) asm volatile("s_waitcnt vmcnt(" #n ")" ::: "memory")
; #define PG8_WAIT_L(n) asm volatile("s_waitcnt lgkmcnt(" #n ")" ::: "memory")
; #define PG8_BAR __builtin_amdgcn_s_barrier()
; #define PG8_SCHED __builtin_amdgcn_sched_barrier(0)
;     ...
;             PG8_WAIT_V(8); PG8_WAIT_L(0); PG8_BAR; PG8_MMA(0, 0, At, B0); PG8_MMA(0, 1, At, B1); PG8_BAR; PG8_SCHED;
;             PG8_LDA(At, 0, 1); PG8_STAGE(PG8_SB(0, 0), b2, voffB); PG8_STAGE(PG8_SB(0, 1), b2 + hstepB, voffB); PG8_STAGE(PG8_SA(0, 0), a2, voffA);
;             PG8_WAIT_V(8); PG8_WAIT_L(0); PG8_BAR; PG8_MMA(1, 0, At, B0); PG8_MMA(1, 1, At, B1); PG8_BAR; PG8_SCHED;
	s_waitcnt lgkmcnt(0)
	v_mfma_f32_16x16x32_bf16 v[126:129], v[156:159], v[196:199], v[126:129]
	v_mfma_f32_16x16x32_bf16 v[122:125], v[172:175], v[196:199], v[122:125]
	v_mfma_f32_16x16x32_bf16 v[110:113], v[156:159], v[204:207], v[110:113]
	v_mfma_f32_16x16x32_bf16 v[106:109], v[172:175], v[204:207], v[106:109]
	v_mfma_f32_16x16x32_bf16 v[94:97], v[156:159], v[212:215], v[94:97]
	v_mfma_f32_16x16x32_bf16 v[90:93], v[172:175], v[212:215], v[90:93]
	v_mfma_f32_16x16x32_bf16 v[78:81], v[156:159], v[220:223], v[78:81]
	v_mfma_f32_16x16x32_bf16 v[74:77], v[172:175], v[220:223], v[74:77]
	v_mfma_f32_16x16x32_bf16 v[126:129], v[160:163], v[200:203], v[126:129]
	v_mfma_f32_16x16x32_bf16 v[122:125], v[176:179], v[200:203], v[122:125]
	v_mfma_f32_16x16x32_bf16 v[110:113], v[160:163], v[208:211], v[110:113]
	v_mfma_f32_16x16x32_bf16 v[106:109], v[176:179], v[208:211], v[106:109]
	v_mfma_f32_16x16x32_bf16 v[94:97], v[160:163], v[216:219], v[94:97]
	v_mfma_f32_16x16x32_bf16 v[90:93], v[176:179], v[216:219], v[90:93]
	v_mfma_f32_16x16x32_bf16 v[78:81], v[160:163], v[224:227], v[78:81]
	v_mfma_f32_16x16x32_bf16 v[74:77], v[176:179], v[224:227], v[74:77]
	v_mfma_f32_16x16x32_bf16 v[118:121], v[180:183], v[196:199], v[118:121]
	v_mfma_f32_16x16x32_bf16 v[114:117], v[188:191], v[196:199], v[114:117]
	v_mfma_f32_16x16x32_bf16 v[102:105], v[180:183], v[204:207], v[102:105]
	v_mfma_f32_16x16x32_bf16 v[98:101], v[188:191], v[204:207], v[98:101]
	v_mfma_f32_16x16x32_bf16 v[86:89], v[180:183], v[212:215], v[86:89]
	v_mfma_f32_16x16x32_bf16 v[82:85], v[188:191], v[212:215], v[82:85]
	v_mfma_f32_16x16x32_bf16 v[70:73], v[180:183], v[220:223], v[70:73]
	v_mfma_f32_16x16x32_bf16 v[66:69], v[188:191], v[220:223], v[66:69]
	v_mfma_f32_16x16x32_bf16 v[118:121], v[184:187], v[200:203], v[118:121]
	v_mfma_f32_16x16x32_bf16 v[114:117], v[192:195], v[200:203], v[114:117]
	v_mfma_f32_16x16x32_bf16 v[102:105], v[184:187], v[208:211], v[102:105]
	v_mfma_f32_16x16x32_bf16 v[98:101], v[192:195], v[208:211], v[98:101]
	v_mfma_f32_16x16x32_bf16 v[86:89], v[184:187], v[216:219], v[86:89]
	v_mfma_f32_16x16x32_bf16 v[82:85], v[192:195], v[216:219], v[82:85]
	v_mfma_f32_16x16x32_bf16 v[70:73], v[184:187], v[224:227], v[70:73]
	v_mfma_f32_16x16x32_bf16 v[66:69], v[192:195], v[224:227], v[66:69]
	s_barrier
	s_add_i32 s27, s27, s0
	v_lshl_add_u64 v[164:165], s[34:35], 0, v[166:167]
	s_mov_b32 m0, s27
	ds_read_b128 v[196:199], v154 offset:16384
	ds_read_b128 v[200:203], v154 offset:17408
	ds_read_b128 v[204:207], v154 offset:18432
	ds_read_b128 v[208:211], v154 offset:19456
	ds_read_b128 v[212:215], v154 offset:20480
	ds_read_b128 v[216:219], v154 offset:21504
	ds_read_b128 v[220:223], v154 offset:22528
	ds_read_b128 v[224:227], v154 offset:23552
	global_load_lds_dwordx4 v[164:165], off
	s_add_i32 m0, s27, 0x2000
	v_lshl_add_u64 v[168:169], s[34:35], 0, v[130:131]
	s_add_u32 s34, s34, s58
	s_addc_u32 s35, s35, s59
	s_add_i32 s11, s11, s0
	global_load_lds_dwordx4 v[168:169], off
	v_lshl_add_u64 v[170:171], s[34:35], 0, v[166:167]
	s_mov_b32 m0, s11
	v_lshl_add_u64 v[228:229], s[34:35], 0, v[130:131]
	global_load_lds_dwordx4 v[170:171], off
	s_add_i32 m0, s11, 0x2000
	v_lshl_add_u64 v[230:231], s[8:9], 0, v[134:135]
	global_load_lds_dwordx4 v[228:229], off
	s_mov_b32 m0, s3
	v_lshl_add_u64 v[232:233], s[8:9], 0, v[132:133]
	global_load_lds_dwordx4 v[230:231], off
	s_mov_b32 m0, s12
	s_nop 0
	global_load_lds_dwordx4 v[232:233], off
	s_waitcnt vmcnt(8)
	s_waitcnt lgkmcnt(0)
	s_barrier
	s_waitcnt lgkmcnt(0)
	v_mfma_f32_16x16x32_bf16 v[62:65], v[156:159], v[196:199], v[62:65]
	v_mfma_f32_16x16x32_bf16 v[58:61], v[172:175], v[196:199], v[58:61]
	v_mfma_f32_16x16x32_bf16 v[46:49], v[156:159], v[204:207], v[46:49]
	v_mfma_f32_16x16x32_bf16 v[42:45], v[172:175], v[204:207], v[42:45]
	v_mfma_f32_16x16x32_bf16 v[30:33], v[156:159], v[212:215], v[30:33]
	v_mfma_f32_16x16x32_bf16 v[26:29], v[172:175], v[212:215], v[26:29]
	v_mfma_f32_16x16x32_bf16 v[14:17], v[156:159], v[220:223], v[14:17]
	v_mfma_f32_16x16x32_bf16 v[10:13], v[172:175], v[220:223], v[10:13]
	v_mfma_f32_16x16x32_bf16 v[62:65], v[160:163], v[200:203], v[62:65]
	v_mfma_f32_16x16x32_bf16 v[58:61], v[176:179], v[200:203], v[58:61]
	v_mfma_f32_16x16x32_bf16 v[46:49], v[160:163], v[208:211], v[46:49]
	v_mfma_f32_16x16x32_bf16 v[42:45], v[176:179], v[208:211], v[42:45]
	v_mfma_f32_16x16x32_bf16 v[30:33], v[160:163], v[216:219], v[30:33]
	v_mfma_f32_16x16x32_bf16 v[26:29], v[176:179], v[216:219], v[26:29]
	v_mfma_f32_16x16x32_bf16 v[14:17], v[160:163], v[224:227], v[14:17]
	v_mfma_f32_16x16x32_bf16 v[10:13], v[176:179], v[224:227], v[10:13]
	v_mfma_f32_16x16x32_bf16 v[54:57], v[180:183], v[196:199], v[54:57]
	v_mfma_f32_16x16x32_bf16 v[50:53], v[188:191], v[196:199], v[50:53]
	v_mfma_f32_16x16x32_bf16 v[38:41], v[180:183], v[204:207], v[38:41]
	v_mfma_f32_16x16x32_bf16 v[34:37], v[188:191], v[204:207], v[34:37]
	v_mfma_f32_16x16x32_bf16 v[22:25], v[180:183], v[212:215], v[22:25]
	v_mfma_f32_16x16x32_bf16 v[18:21], v[188:191], v[212:215], v[18:21]
	v_mfma_f32_16x16x32_bf16 v[6:9], v[180:183], v[220:223], v[6:9]
	v_mfma_f32_16x16x32_bf16 v[2:5], v[188:191], v[220:223], v[2:5]
	v_mfma_f32_16x16x32_bf16 v[54:57], v[184:187], v[200:203], v[54:57]
	v_mfma_f32_16x16x32_bf16 v[50:53], v[192:195], v[200:203], v[50:53]
	v_mfma_f32_16x16x32_bf16 v[38:41], v[184:187], v[208:211], v[38:41]
	v_mfma_f32_16x16x32_bf16 v[34:37], v[192:195], v[208:211], v[34:37]
	v_mfma_f32_16x16x32_bf16 v[22:25], v[184:187], v[216:219], v[22:25]
	v_mfma_f32_16x16x32_bf16 v[18:21], v[192:195], v[216:219], v[18:21]
	v_mfma_f32_16x16x32_bf16 v[6:9], v[184:187], v[224:227], v[6:9]
	v_mfma_f32_16x16x32_bf16 v[2:5], v[192:195], v[224:227], v[2:5]
	s_barrier
; #define PG8_STAGE(bufoff, gbase, voff) do { _Pragma("unroll") for (int _i = 0; _i < 2; ++_i) \
;         __builtin_amdgcn_global_load_lds((const unsigned*)((const char*)(gbase) + (voff)[_i]), (PG8_LAS unsigned*)(lds + (bufoff) + ldsw + _i * 8192), 16, 0, 0); } while (0)
; #define PG8_LDA(dst, b, h) do { _Pragma("unroll") for (int m = 0; m < 4; ++m) _Pragma("unroll") for (int k = 0; k < 2; ++k) dst[m][k] = *(const PG8_LAS bf16x8*)(lds + PG8_SA(b, h) + aoff + m * 2048 + k * 1024); } while (0)
; #define PG8_LDB(dst, b, h) do { _Pragma("unroll") for (int n = 0; n < 2; ++n) _Pragma("unroll") for (int k = 0; k < 2; ++k) dst[n][k] = *(const PG8_LAS bf16x8*)(lds + PG8_SB(b, h) + boff + n * 2048 + k * 1024); } while (0)
; #define PG8_MMA(ai, bj, At, Bt) do { __builtin_amdgcn_s_setprio(1); _Pragma("unroll") for (int m = 0; m < 4; ++m) _Pragma("unroll") for (int n = 0; n < 2; ++n) _Pragma("unroll") for (int k = 0; k < 2; ++k) \
;         acc[ai][bj][m][n] = __builtin_amdgcn_mfma_f32_16x16x32_bf16(Bt[n][k], At[m][k], acc[ai][bj][m][n], 0, 0, 0); __builtin_amdgcn_s_setprio(0); } while (0)
; #define PG8_WAIT_V(n) asm volatile("s_waitcnt vmcnt(" #n ")" ::: "memory")
; #define PG8_WAIT_L(n) asm volatile("s_waitcnt lgkmcnt(" #n ")" ::: "memory")
; #define PG8_BAR __builtin_amdgcn_s_barrier()
; #define PG8_SCHED __builtin_amdgcn_sched_barrier(0)
;     ...
;             PG8_LDB(B0, 1, 0); PG8_LDB(B1, 1, 1); PG8_SCHED; PG8_LDA(At, 1, 0); PG8_STAGE(PG8_SA(0, 1), a2 + hstepA, voffA);
;             PG8_WAIT_V(8); PG8_WAIT_L(0); PG8_BAR; PG8_MMA(0, 0, At, B0); PG8_MMA(0, 1, At, B1); PG8_BAR; PG8_SCHED;
;             PG8_LDA(At, 1, 1); PG8_STAGE(PG8_SB(1, 0), b3, voffB); PG8_STAGE(PG8_SB(1, 1), b3 + hstepB, voffB); PG8_STAGE(PG8_SA(1, 0), a3, voffA);
;             PG8_WAIT_V(8); PG8_WAIT_L(0); PG8_BAR; PG8_MMA(1, 0, At, B0); PG8_MMA(1, 1, At, B1); PG8_BAR; PG8_SCHED;
	s_add_i32 s11, 0, 0x18000
	v_add_u32_e32 v140, s11, v151
	s_add_i32 s27, 0, 0x1c000
	ds_read_b128 v[156:159], v140
	ds_read_b128 v[160:163], v140 offset:1024
	ds_read_b128 v[172:175], v140 offset:2048
	ds_read_b128 v[176:179], v140 offset:3072
	v_add_u32_e32 v140, s27, v151
	ds_read_b128 v[180:183], v140
	ds_read_b128 v[184:187], v140 offset:1024
	ds_read_b128 v[188:191], v140 offset:2048
	ds_read_b128 v[192:195], v140 offset:3072
	s_add_u32 s8, s8, s58
	s_addc_u32 s9, s9, s59
	s_mov_b32 m0, s13
	v_lshl_add_u64 v[234:235], s[8:9], 0, v[134:135]
	ds_read_b128 v[196:199], v154 offset:32768
	ds_read_b128 v[200:203], v154 offset:33792
	ds_read_b128 v[204:207], v154 offset:34816
	ds_read_b128 v[208:211], v154 offset:35840
	ds_read_b128 v[212:215], v154 offset:36864
	ds_read_b128 v[216:219], v154 offset:37888
	ds_read_b128 v[220:223], v154 offset:38912
	ds_read_b128 v[224:227], v154 offset:39936
	global_load_lds_dwordx4 v[234:235], off
	v_lshl_add_u64 v[234:235], s[8:9], 0, v[132:133]
	s_mov_b32 m0, s14
	s_nop 0
	global_load_lds_dwordx4 v[234:235], off
	s_waitcnt vmcnt(8)
	s_waitcnt lgkmcnt(0)
	s_barrier
	s_waitcnt lgkmcnt(0)
	v_mfma_f32_16x16x32_bf16 v[126:129], v[156:159], v[196:199], v[126:129]
	v_mfma_f32_16x16x32_bf16 v[122:125], v[172:175], v[196:199], v[122:125]
	v_mfma_f32_16x16x32_bf16 v[110:113], v[156:159], v[204:207], v[110:113]
	v_mfma_f32_16x16x32_bf16 v[106:109], v[172:175], v[204:207], v[106:109]
	v_mfma_f32_16x16x32_bf16 v[94:97], v[156:159], v[212:215], v[94:97]
	v_mfma_f32_16x16x32_bf16 v[90:93], v[172:175], v[212:215], v[90:93]
	v_mfma_f32_16x16x32_bf16 v[78:81], v[156:159], v[220:223], v[78:81]
	v_mfma_f32_16x16x32_bf16 v[74:77], v[172:175], v[220:223], v[74:77]
	v_mfma_f32_16x16x32_bf16 v[126:129], v[160:163], v[200:203], v[126:129]
	v_mfma_f32_16x16x32_bf16 v[122:125], v[176:179], v[200:203], v[122:125]
	v_mfma_f32_16x16x32_bf16 v[110:113], v[160:163], v[208:211], v[110:113]
	v_mfma_f32_16x16x32_bf16 v[106:109], v[176:179], v[208:211], v[106:109]
	v_mfma_f32_16x16x32_bf16 v[94:97], v[160:163], v[216:219], v[94:97]
	v_mfma_f32_16x16x32_bf16 v[90:93], v[176:179], v[216:219], v[90:93]
	v_mfma_f32_16x16x32_bf16 v[78:81], v[160:163], v[224:227], v[78:81]
	v_mfma_f32_16x16x32_bf16 v[74:77], v[176:179], v[224:227], v[74:77]
	v_mfma_f32_16x16x32_bf16 v[118:121], v[180:183], v[196:199], v[118:121]
	v_mfma_f32_16x16x32_bf16 v[114:117], v[188:191], v[196:199], v[114:117]
	v_mfma_f32_16x16x32_bf16 v[102:105], v[180:183], v[204:207], v[102:105]
	v_mfma_f32_16x16x32_bf16 v[98:101], v[188:191], v[204:207], v[98:101]
	v_mfma_f32_16x16x32_bf16 v[86:89], v[180:183], v[212:215], v[86:89]
	v_mfma_f32_16x16x32_bf16 v[82:85], v[188:191], v[212:215], v[82:85]
	v_mfma_f32_16x16x32_bf16 v[70:73], v[180:183], v[220:223], v[70:73]
	v_mfma_f32_16x16x32_bf16 v[66:69], v[188:191], v[220:223], v[66:69]
	v_mfma_f32_16x16x32_bf16 v[118:121], v[184:187], v[200:203], v[118:121]
	v_mfma_f32_16x16x32_bf16 v[114:117], v[192:195], v[200:203], v[114:117]
	v_mfma_f32_16x16x32_bf16 v[102:105], v[184:187], v[208:211], v[102:105]
	v_mfma_f32_16x16x32_bf16 v[98:101], v[192:195], v[208:211], v[98:101]
	v_mfma_f32_16x16x32_bf16 v[86:89], v[184:187], v[216:219], v[86:89]
	v_mfma_f32_16x16x32_bf16 v[82:85], v[192:195], v[216:219], v[82:85]
	v_mfma_f32_16x16x32_bf16 v[70:73], v[184:187], v[224:227], v[70:73]
	v_mfma_f32_16x16x32_bf16 v[66:69], v[192:195], v[224:227], v[66:69]
	s_barrier
	s_add_i32 s8, s11, s0
	v_lshl_add_u64 v[164:165], v[164:165], 0, s[62:63]
	s_mov_b32 m0, s8
	ds_read_b128 v[196:199], v154 offset:49152
	ds_read_b128 v[200:203], v154 offset:50176
	ds_read_b128 v[204:207], v154 offset:51200
	ds_read_b128 v[208:211], v154 offset:52224
	ds_read_b128 v[212:215], v154 offset:53248
	ds_read_b128 v[216:219], v154 offset:54272
	ds_read_b128 v[220:223], v154 offset:55296
	ds_read_b128 v[224:227], v154 offset:56320
	global_load_lds_dwordx4 v[164:165], off
	v_lshl_add_u64 v[164:165], v[168:169], 0, s[62:63]
	s_add_i32 m0, s8, 0x2000
	s_add_i32 s8, s27, s0
	global_load_lds_dwordx4 v[164:165], off
	v_lshl_add_u64 v[164:165], v[170:171], 0, s[62:63]
	s_mov_b32 m0, s8
	s_nop 0
	global_load_lds_dwordx4 v[164:165], off
	v_lshl_add_u64 v[164:165], v[228:229], 0, s[62:63]
	s_add_i32 m0, s8, 0x2000
	s_nop 0
	global_load_lds_dwordx4 v[164:165], off
	v_lshl_add_u64 v[164:165], v[230:231], 0, s[62:63]
	s_mov_b32 m0, s16
	s_nop 0
	global_load_lds_dwordx4 v[164:165], off
	v_lshl_add_u64 v[164:165], v[232:233], 0, s[62:63]
	s_mov_b32 m0, s17
	s_nop 0
	global_load_lds_dwordx4 v[164:165], off
	s_waitcnt vmcnt(8)
	s_waitcnt lgkmcnt(0)
	s_barrier
	s_waitcnt lgkmcnt(0)
	v_mfma_f32_16x16x32_bf16 v[62:65], v[156:159], v[196:199], v[62:65]
	v_mfma_f32_16x16x32_bf16 v[58:61], v[172:175], v[196:199], v[58:61]
	v_mfma_f32_16x16x32_bf16 v[46:49], v[156:159], v[204:207], v[46:49]
	v_mfma_f32_16x16x32_bf16 v[42:45], v[172:175], v[204:207], v[42:45]
	v_mfma_f32_16x16x32_bf16 v[30:33], v[156:159], v[212:215], v[30:33]
	v_mfma_f32_16x16x32_bf16 v[26:29], v[172:175], v[212:215], v[26:29]
	v_mfma_f32_16x16x32_bf16 v[14:17], v[156:159], v[220:223], v[14:17]
	v_mfma_f32_16x16x32_bf16 v[10:13], v[172:175], v[220:223], v[10:13]
	v_mfma_f32_16x16x32_bf16 v[62:65], v[160:163], v[200:203], v[62:65]
	v_mfma_f32_16x16x32_bf16 v[58:61], v[176:179], v[200:203], v[58:61]
	v_mfma_f32_16x16x32_bf16 v[46:49], v[160:163], v[208:211], v[46:49]
	v_mfma_f32_16x16x32_bf16 v[42:45], v[176:179], v[208:211], v[42:45]
	v_mfma_f32_16x16x32_bf16 v[30:33], v[160:163], v[216:219], v[30:33]
	v_mfma_f32_16x16x32_bf16 v[26:29], v[176:179], v[216:219], v[26:29]
	v_mfma_f32_16x16x32_bf16 v[14:17], v[160:163], v[224:227], v[14:17]
	v_mfma_f32_16x16x32_bf16 v[10:13], v[176:179], v[224:227], v[10:13]
	v_mfma_f32_16x16x32_bf16 v[54:57], v[180:183], v[196:199], v[54:57]
	v_mfma_f32_16x16x32_bf16 v[50:53], v[188:191], v[196:199], v[50:53]
	v_mfma_f32_16x16x32_bf16 v[38:41], v[180:183], v[204:207], v[38:41]
	v_mfma_f32_16x16x32_bf16 v[34:37], v[188:191], v[204:207], v[34:37]
	v_mfma_f32_16x16x32_bf16 v[22:25], v[180:183], v[212:215], v[22:25]
	v_mfma_f32_16x16x32_bf16 v[18:21], v[188:191], v[212:215], v[18:21]
	v_mfma_f32_16x16x32_bf16 v[6:9], v[180:183], v[220:223], v[6:9]
	v_mfma_f32_16x16x32_bf16 v[2:5], v[188:191], v[220:223], v[2:5]
	v_mfma_f32_16x16x32_bf16 v[54:57], v[184:187], v[200:203], v[54:57]
	v_mfma_f32_16x16x32_bf16 v[50:53], v[192:195], v[200:203], v[50:53]
	v_mfma_f32_16x16x32_bf16 v[38:41], v[184:187], v[208:211], v[38:41]
	v_mfma_f32_16x16x32_bf16 v[34:37], v[192:195], v[208:211], v[34:37]
	v_mfma_f32_16x16x32_bf16 v[22:25], v[184:187], v[216:219], v[22:25]
	v_mfma_f32_16x16x32_bf16 v[18:21], v[192:195], v[216:219], v[18:21]
	v_mfma_f32_16x16x32_bf16 v[6:9], v[184:187], v[224:227], v[6:9]
	v_mfma_f32_16x16x32_bf16 v[2:5], v[192:195], v[224:227], v[2:5]
	s_barrier
	s_add_u32 s24, s24, 0x100
	s_addc_u32 s25, s25, 0
	s_add_u32 s6, s6, 0x100
	s_addc_u32 s7, s7, 0
	s_cmp_ge_i32 s10, s15
	s_mov_b32 s8, s10
	s_cbranch_scc0 .LBB0_613

; #define PG8_STAGE(bufoff, gbase, voff) do { _Pragma("unroll") for (int _i = 0; _i < 2; ++_i) \
;         __builtin_amdgcn_global_load_lds((const unsigned*)((const char*)(gbase) + (voff)[_i]), (PG8_LAS unsigned*)(lds + (bufoff) + ldsw + _i * 8192), 16, 0, 0); } while (0)
; #define PG8_LDA(dst, b, h) do { _Pragma("unroll") for (int m = 0; m < 4; ++m) _Pragma("unroll") for (int k = 0; k < 2; ++k) dst[m][k] = *(const PG8_LAS bf16x8*)(lds + PG8_SA(b, h) + aoff + m * 2048 + k * 1024); } while (0)
; #define PG8_LDB(dst, b, h) do { _Pragma("unroll") for (int n = 0; n < 2; ++n) _Pragma("unroll") for (int k = 0; k < 2; ++k) dst[n][k] = *(const PG8_LAS bf16x8*)(lds + PG8_SB(b, h) + boff + n * 2048 + k * 1024); } while (0)
; #define PG8_MMA(ai, bj, At, Bt) do { __builtin_amdgcn_s_setprio(1); _Pragma("unroll") for (int m = 0; m < 4; ++m) _Pragma("unroll") for (int n = 0; n < 2; ++n) _Pragma("unroll") for (int k = 0; k < 2; ++k) \
;         acc[ai][bj][m][n] = __builtin_amdgcn_mfma_f32_16x16x32_bf16(Bt[n][k], At[m][k], acc[ai][bj][m][n], 0, 0, 0); __builtin_amdgcn_s_setprio(0); } while (0)
; #define PG8_WAIT_V(n) asm volatile("s_waitcnt vmcnt(" #n ")" ::: "memory")
; #define PG8_WAIT_L(n) asm volatile("s_waitcnt lgkmcnt(" #n ")" ::: "memory")
; #define PG8_BAR __builtin_amdgcn_s_barrier()
; #define PG8_SCHED __builtin_amdgcn_sched_barrier(0)
;     ...
;         for (int t = 0; t < nt; t += 2) {
;             const bool last = (t == nt - 2);
;             const char* a1 = cA + (size_t)(t + 1) * kstep;
;             const char* a2 = last ? nA : cA + (size_t)(t + 2) * kstep; const char* b2 = last ? nB : cB + (size_t)(t + 2) * kstep;
;             const char* a3 = a2 + kstep; const char* b3 = b2 + kstep;
;             if (last && has_next) S.a_ready(nxt);
;             if constexpr (SP2) {
;             PG8_LDB(B0, 0, 0); PG8_LDB(B1, 0, 1); PG8_SCHED; PG8_LDA(At, 0, 0); PG8_STAGE(PG8_SA(1, 1), a1 + hstepA, voffA);
;             PG8_WAIT_V(8); PG8_WAIT_L(0); PG8_BAR; PG8_MMA(0, 0, At, B0); PG8_MMA(0, 1, At, B1); PG8_BAR; PG8_SCHED;
;             PG8_LDA(At, 0, 1); PG8_STAGE(PG8_SB(0, 0), b2, voffB); PG8_STAGE(PG8_SB(0, 1), b2 + hstepB, voffB); PG8_STAGE(PG8_SA(0, 0), a2, voffA);
.LBB0_750:
	s_andn2_b64 vcc, exec, s[86:87]
	s_waitcnt lgkmcnt(0)
	s_cbranch_vccnz .LBB0_753
	s_add_u32 s10, s6, 0x100
	s_addc_u32 s11, s7, 0
	s_add_u32 s6, s8, 0x80
	s_addc_u32 s7, s9, 0
	s_mov_b32 s8, 0
	s_add_i32 s25, s8, 2
	s_add_u32 s27, s6, 0x80
	s_addc_u32 s9, s7, 0
	s_add_i32 s31, 0, 0x10000
	s_cmp_eq_u32 s19, s8
	s_cselect_b32 s9, s43, s9
	s_cselect_b32 s8, s42, s27
	s_cselect_b32 s35, s91, s11
	s_cselect_b32 s34, s90, s10
	s_add_i32 s27, 0, 0x14000
	v_add_u32_e32 v148, s31, v229
	v_add_u32_e32 v164, s27, v229
	ds_read_b128 v[136:139], v148
	ds_read_b128 v[140:143], v148 offset:1024
	ds_read_b128 v[144:147], v148 offset:2048
	ds_read_b128 v[148:151], v148 offset:3072
	ds_read_b128 v[152:155], v164
	ds_read_b128 v[156:159], v164 offset:1024
	ds_read_b128 v[160:163], v164 offset:2048
	ds_read_b128 v[172:175], v164 offset:3072
	v_lshl_add_u64 v[164:165], s[6:7], 0, v[134:135]
	s_add_i32 m0, s2, 0xc000
	ds_read_b128 v[176:179], v231
	ds_read_b128 v[180:183], v231 offset:1024
	ds_read_b128 v[184:187], v231 offset:2048
	ds_read_b128 v[188:191], v231 offset:3072
	ds_read_b128 v[192:195], v231 offset:4096
	ds_read_b128 v[196:199], v231 offset:5120
	ds_read_b128 v[200:203], v231 offset:6144
	ds_read_b128 v[204:207], v231 offset:7168
	global_load_lds_dwordx4 v[164:165], off
	v_lshl_add_u64 v[164:165], s[6:7], 0, v[132:133]
	s_add_i32 m0, s2, 0xe000
	s_nop 0
	global_load_lds_dwordx4 v[164:165], off
	s_waitcnt vmcnt(8)
	s_waitcnt lgkmcnt(0)
	s_barrier
	s_waitcnt lgkmcnt(0)
	v_mfma_f32_16x16x32_bf16 v[126:129], v[136:139], v[176:179], 0
	v_mfma_f32_16x16x32_bf16 v[122:125], v[144:147], v[176:179], 0
	v_mfma_f32_16x16x32_bf16 v[110:113], v[136:139], v[184:187], 0
	v_mfma_f32_16x16x32_bf16 v[106:109], v[144:147], v[184:187], 0
	v_mfma_f32_16x16x32_bf16 v[94:97], v[136:139], v[192:195], 0
	v_mfma_f32_16x16x32_bf16 v[90:93], v[144:147], v[192:195], 0
	v_mfma_f32_16x16x32_bf16 v[78:81], v[136:139], v[200:203], 0
	v_mfma_f32_16x16x32_bf16 v[74:77], v[144:147], v[200:203], 0
	v_mfma_f32_16x16x32_bf16 v[126:129], v[140:143], v[180:183], v[126:129]
	v_mfma_f32_16x16x32_bf16 v[122:125], v[148:151], v[180:183], v[122:125]
	v_mfma_f32_16x16x32_bf16 v[110:113], v[140:143], v[188:191], v[110:113]
	v_mfma_f32_16x16x32_bf16 v[106:109], v[148:151], v[188:191], v[106:109]
	v_mfma_f32_16x16x32_bf16 v[94:97], v[140:143], v[196:199], v[94:97]
	v_mfma_f32_16x16x32_bf16 v[90:93], v[148:151], v[196:199], v[90:93]
	v_mfma_f32_16x16x32_bf16 v[78:81], v[140:143], v[204:207], v[78:81]
	v_mfma_f32_16x16x32_bf16 v[74:77], v[148:151], v[204:207], v[74:77]
	v_mfma_f32_16x16x32_bf16 v[118:121], v[152:155], v[176:179], 0
	v_mfma_f32_16x16x32_bf16 v[114:117], v[160:163], v[176:179], 0
	v_mfma_f32_16x16x32_bf16 v[102:105], v[152:155], v[184:187], 0
	v_mfma_f32_16x16x32_bf16 v[98:101], v[160:163], v[184:187], 0
	v_mfma_f32_16x16x32_bf16 v[86:89], v[152:155], v[192:195], 0
	v_mfma_f32_16x16x32_bf16 v[82:85], v[160:163], v[192:195], 0
	v_mfma_f32_16x16x32_bf16 v[70:73], v[152:155], v[200:203], 0
	v_mfma_f32_16x16x32_bf16 v[66:69], v[160:163], v[200:203], 0
	v_mfma_f32_16x16x32_bf16 v[118:121], v[156:159], v[180:183], v[118:121]
	v_mfma_f32_16x16x32_bf16 v[114:117], v[172:175], v[180:183], v[114:117]
	v_mfma_f32_16x16x32_bf16 v[102:105], v[156:159], v[188:191], v[102:105]
	v_mfma_f32_16x16x32_bf16 v[98:101], v[172:175], v[188:191], v[98:101]
	v_mfma_f32_16x16x32_bf16 v[86:89], v[156:159], v[196:199], v[86:89]
	v_mfma_f32_16x16x32_bf16 v[82:85], v[172:175], v[196:199], v[82:85]
	v_mfma_f32_16x16x32_bf16 v[70:73], v[156:159], v[204:207], v[70:73]
	v_mfma_f32_16x16x32_bf16 v[66:69], v[172:175], v[204:207], v[66:69]
	s_barrier
	s_add_i32 s31, s31, s0
	v_lshl_add_u64 v[164:165], s[34:35], 0, v[166:167]
	s_mov_b32 m0, s31
	ds_read_b128 v[176:179], v231 offset:16384
	ds_read_b128 v[180:183], v231 offset:17408
	ds_read_b128 v[184:187], v231 offset:18432
	ds_read_b128 v[188:191], v231 offset:19456
	ds_read_b128 v[192:195], v231 offset:20480
	ds_read_b128 v[196:199], v231 offset:21504
	ds_read_b128 v[200:203], v231 offset:22528
	ds_read_b128 v[204:207], v231 offset:23552
	global_load_lds_dwordx4 v[164:165], off
	s_add_i32 m0, s31, 0x2000
	v_lshl_add_u64 v[168:169], s[34:35], 0, v[130:131]
	s_add_u32 s34, s34, s58
	s_addc_u32 s35, s35, s59
	s_add_i32 s27, s27, s0
	global_load_lds_dwordx4 v[168:169], off
	v_lshl_add_u64 v[170:171], s[34:35], 0, v[166:167]
	s_mov_b32 m0, s27
	v_lshl_add_u64 v[208:209], s[34:35], 0, v[130:131]
	global_load_lds_dwordx4 v[170:171], off
	s_add_i32 m0, s27, 0x2000
	v_lshl_add_u64 v[210:211], s[8:9], 0, v[166:167]
	global_load_lds_dwordx4 v[208:209], off
	s_mov_b32 m0, s2
	v_lshl_add_u64 v[212:213], s[8:9], 0, v[130:131]
	global_load_lds_dwordx4 v[210:211], off
	s_mov_b32 m0, s3
	s_nop 0
	global_load_lds_dwordx4 v[212:213], off
	s_waitcnt vmcnt(8)
	s_waitcnt lgkmcnt(0)
	s_barrier
; #define PG8_STAGE(bufoff, gbase, voff) do { _Pragma("unroll") for (int _i = 0; _i < 2; ++_i) \
;         __builtin_amdgcn_global_load_lds((const unsigned*)((const char*)(gbase) + (voff)[_i]), (PG8_LAS unsigned*)(lds + (bufoff) + ldsw + _i * 8192), 16, 0, 0); } while (0)
; #define PG8_LDA(dst, b, h) do { _Pragma("unroll") for (int m = 0; m < 4; ++m) _Pragma("unroll") for (int k = 0; k < 2; ++k) dst[m][k] = *(const PG8_LAS bf16x8*)(lds + PG8_SA(b, h) + aoff + m * 2048 + k * 1024); } while (0)
; #define PG8_LDB(dst, b, h) do { _Pragma("unroll") for (int n = 0; n < 2; ++n) _Pragma("unroll") for (int k = 0; k < 2; ++k) dst[n][k] = *(const PG8_LAS bf16x8*)(lds + PG8_SB(b, h) + boff + n * 2048 + k * 1024); } while (0)
; #define PG8_MMA(ai, bj, At, Bt) do { __builtin_amdgcn_s_setprio(1); _Pragma("unroll") for (int m = 0; m < 4; ++m) _Pragma("unroll") for (int n = 0; n < 2; ++n) _Pragma("unroll") for (int k = 0; k < 2; ++k) \
;         acc[ai][bj][m][n] = __builtin_amdgcn_mfma_f32_16x16x32_bf16(Bt[n][k], At[m][k], acc[ai][bj][m][n], 0, 0, 0); __builtin_amdgcn_s_setprio(0); } while (0)
; #define PG8_WAIT_V(n) asm volatile("s_waitcnt vmcnt(" #n ")" ::: "memory")
; #define PG8_WAIT_L(n) asm volatile("s_waitcnt lgkmcnt(" #n ")" ::: "memory")
; #define PG8_BAR __builtin_amdgcn_s_barrier()
; #define PG8_SCHED __builtin_amdgcn_sched_barrier(0)
;     ...
;             PG8_WAIT_V(8); PG8_WAIT_L(0); PG8_BAR; PG8_MMA(1, 0, At, B0); PG8_MMA(1, 1, At, B1); PG8_BAR; PG8_SCHED;
;             PG8_LDB(B0, 1, 0); PG8_LDB(B1, 1, 1); PG8_SCHED; PG8_LDA(At, 1, 0); PG8_STAGE(PG8_SA(0, 1), a2 + hstepA, voffA);
;             PG8_WAIT_V(8); PG8_WAIT_L(0); PG8_BAR; PG8_MMA(0, 0, At, B0); PG8_MMA(0, 1, At, B1); PG8_BAR; PG8_SCHED;
	s_waitcnt lgkmcnt(0)
	v_mfma_f32_16x16x32_bf16 v[62:65], v[136:139], v[176:179], 0
	v_mfma_f32_16x16x32_bf16 v[58:61], v[144:147], v[176:179], 0
	v_mfma_f32_16x16x32_bf16 v[46:49], v[136:139], v[184:187], 0
	v_mfma_f32_16x16x32_bf16 v[42:45], v[144:147], v[184:187], 0
	v_mfma_f32_16x16x32_bf16 v[30:33], v[136:139], v[192:195], 0
	v_mfma_f32_16x16x32_bf16 v[26:29], v[144:147], v[192:195], 0
	v_mfma_f32_16x16x32_bf16 v[14:17], v[136:139], v[200:203], 0
	v_mfma_f32_16x16x32_bf16 v[10:13], v[144:147], v[200:203], 0
	v_mfma_f32_16x16x32_bf16 v[62:65], v[140:143], v[180:183], v[62:65]
	v_mfma_f32_16x16x32_bf16 v[58:61], v[148:151], v[180:183], v[58:61]
	v_mfma_f32_16x16x32_bf16 v[46:49], v[140:143], v[188:191], v[46:49]
	v_mfma_f32_16x16x32_bf16 v[42:45], v[148:151], v[188:191], v[42:45]
	v_mfma_f32_16x16x32_bf16 v[30:33], v[140:143], v[196:199], v[30:33]
	v_mfma_f32_16x16x32_bf16 v[26:29], v[148:151], v[196:199], v[26:29]
	v_mfma_f32_16x16x32_bf16 v[14:17], v[140:143], v[204:207], v[14:17]
	v_mfma_f32_16x16x32_bf16 v[10:13], v[148:151], v[204:207], v[10:13]
	v_mfma_f32_16x16x32_bf16 v[54:57], v[152:155], v[176:179], 0
	v_mfma_f32_16x16x32_bf16 v[50:53], v[160:163], v[176:179], 0
	v_mfma_f32_16x16x32_bf16 v[38:41], v[152:155], v[184:187], 0
	v_mfma_f32_16x16x32_bf16 v[34:37], v[160:163], v[184:187], 0
	v_mfma_f32_16x16x32_bf16 v[22:25], v[152:155], v[192:195], 0
	v_mfma_f32_16x16x32_bf16 v[18:21], v[160:163], v[192:195], 0
	v_mfma_f32_16x16x32_bf16 v[6:9], v[152:155], v[200:203], 0
	v_mfma_f32_16x16x32_bf16 v[2:5], v[160:163], v[200:203], 0
	v_mfma_f32_16x16x32_bf16 v[54:57], v[156:159], v[180:183], v[54:57]
	v_mfma_f32_16x16x32_bf16 v[50:53], v[172:175], v[180:183], v[50:53]
	v_mfma_f32_16x16x32_bf16 v[38:41], v[156:159], v[188:191], v[38:41]
	v_mfma_f32_16x16x32_bf16 v[34:37], v[172:175], v[188:191], v[34:37]
	v_mfma_f32_16x16x32_bf16 v[22:25], v[156:159], v[196:199], v[22:25]
	v_mfma_f32_16x16x32_bf16 v[18:21], v[172:175], v[196:199], v[18:21]
	v_mfma_f32_16x16x32_bf16 v[6:9], v[156:159], v[204:207], v[6:9]
	v_mfma_f32_16x16x32_bf16 v[2:5], v[172:175], v[204:207], v[2:5]
	s_barrier
	s_add_i32 s27, 0, 0x18000
	s_add_i32 s31, 0, 0x1c000
	v_add_u32_e32 v148, s27, v229
	v_add_u32_e32 v172, s31, v229
	ds_read_b128 v[136:139], v148
	ds_read_b128 v[140:143], v148 offset:1024
	ds_read_b128 v[144:147], v148 offset:2048
	ds_read_b128 v[148:151], v148 offset:3072
	ds_read_b128 v[152:155], v172
	ds_read_b128 v[156:159], v172 offset:1024
	ds_read_b128 v[160:163], v172 offset:2048
	ds_read_b128 v[172:175], v172 offset:3072
	s_add_u32 s8, s8, s58
	s_addc_u32 s9, s9, s59
	s_mov_b32 m0, s14
	v_lshl_add_u64 v[214:215], s[8:9], 0, v[166:167]
	ds_read_b128 v[176:179], v231 offset:32768
	ds_read_b128 v[180:183], v231 offset:33792
	ds_read_b128 v[184:187], v231 offset:34816
	ds_read_b128 v[188:191], v231 offset:35840
	ds_read_b128 v[192:195], v231 offset:36864
	ds_read_b128 v[196:199], v231 offset:37888
	ds_read_b128 v[200:203], v231 offset:38912
	ds_read_b128 v[204:207], v231 offset:39936
	global_load_lds_dwordx4 v[214:215], off
	v_lshl_add_u64 v[214:215], s[8:9], 0, v[130:131]
	s_mov_b32 m0, s15
	s_nop 0
	global_load_lds_dwordx4 v[214:215], off
	s_waitcnt vmcnt(8)
	s_waitcnt lgkmcnt(0)
	s_barrier
	s_waitcnt lgkmcnt(0)
	v_mfma_f32_16x16x32_bf16 v[126:129], v[136:139], v[176:179], v[126:129]
	v_mfma_f32_16x16x32_bf16 v[122:125], v[144:147], v[176:179], v[122:125]
	v_mfma_f32_16x16x32_bf16 v[110:113], v[136:139], v[184:187], v[110:113]
	v_mfma_f32_16x16x32_bf16 v[106:109], v[144:147], v[184:187], v[106:109]
	v_mfma_f32_16x16x32_bf16 v[94:97], v[136:139], v[192:195], v[94:97]
	v_mfma_f32_16x16x32_bf16 v[90:93], v[144:147], v[192:195], v[90:93]
	v_mfma_f32_16x16x32_bf16 v[78:81], v[136:139], v[200:203], v[78:81]
	v_mfma_f32_16x16x32_bf16 v[74:77], v[144:147], v[200:203], v[74:77]
	v_mfma_f32_16x16x32_bf16 v[126:129], v[140:143], v[180:183], v[126:129]
	v_mfma_f32_16x16x32_bf16 v[122:125], v[148:151], v[180:183], v[122:125]
	v_mfma_f32_16x16x32_bf16 v[110:113], v[140:143], v[188:191], v[110:113]
	v_mfma_f32_16x16x32_bf16 v[106:109], v[148:151], v[188:191], v[106:109]
	v_mfma_f32_16x16x32_bf16 v[94:97], v[140:143], v[196:199], v[94:97]
	v_mfma_f32_16x16x32_bf16 v[90:93], v[148:151], v[196:199], v[90:93]
	v_mfma_f32_16x16x32_bf16 v[78:81], v[140:143], v[204:207], v[78:81]
	v_mfma_f32_16x16x32_bf16 v[74:77], v[148:151], v[204:207], v[74:77]
	v_mfma_f32_16x16x32_bf16 v[118:121], v[152:155], v[176:179], v[118:121]
	v_mfma_f32_16x16x32_bf16 v[114:117], v[160:163], v[176:179], v[114:117]
	v_mfma_f32_16x16x32_bf16 v[102:105], v[152:155], v[184:187], v[102:105]
	v_mfma_f32_16x16x32_bf16 v[98:101], v[160:163], v[184:187], v[98:101]
	v_mfma_f32_16x16x32_bf16 v[86:89], v[152:155], v[192:195], v[86:89]
	v_mfma_f32_16x16x32_bf16 v[82:85], v[160:163], v[192:195], v[82:85]
	v_mfma_f32_16x16x32_bf16 v[70:73], v[152:155], v[200:203], v[70:73]
	v_mfma_f32_16x16x32_bf16 v[66:69], v[160:163], v[200:203], v[66:69]
	v_mfma_f32_16x16x32_bf16 v[118:121], v[156:159], v[180:183], v[118:121]
	v_mfma_f32_16x16x32_bf16 v[114:117], v[172:175], v[180:183], v[114:117]
	v_mfma_f32_16x16x32_bf16 v[102:105], v[156:159], v[188:191], v[102:105]
	v_mfma_f32_16x16x32_bf16 v[98:101], v[172:175], v[188:191], v[98:101]
	v_mfma_f32_16x16x32_bf16 v[86:89], v[156:159], v[196:199], v[86:89]
	v_mfma_f32_16x16x32_bf16 v[82:85], v[172:175], v[196:199], v[82:85]
	v_mfma_f32_16x16x32_bf16 v[70:73], v[156:159], v[204:207], v[70:73]
	v_mfma_f32_16x16x32_bf16 v[66:69], v[172:175], v[204:207], v[66:69]
	s_barrier
; #define PG8_STAGE(bufoff, gbase, voff) do { _Pragma("unroll") for (int _i = 0; _i < 2; ++_i) \
;         __builtin_amdgcn_global_load_lds((const unsigned*)((const char*)(gbase) + (voff)[_i]), (PG8_LAS unsigned*)(lds + (bufoff) + ldsw + _i * 8192), 16, 0, 0); } while (0)
; #define PG8_LDA(dst, b, h) do { _Pragma("unroll") for (int m = 0; m < 4; ++m) _Pragma("unroll") for (int k = 0; k < 2; ++k) dst[m][k] = *(const PG8_LAS bf16x8*)(lds + PG8_SA(b, h) + aoff + m * 2048 + k * 1024); } while (0)
; #define PG8_LDB(dst, b, h) do { _Pragma("unroll") for (int n = 0; n < 2; ++n) _Pragma("unroll") for (int k = 0; k < 2; ++k) dst[n][k] = *(const PG8_LAS bf16x8*)(lds + PG8_SB(b, h) + boff + n * 2048 + k * 1024); } while (0)
; #define PG8_MMA(ai, bj, At, Bt) do { __builtin_amdgcn_s_setprio(1); _Pragma("unroll") for (int m = 0; m < 4; ++m) _Pragma("unroll") for (int n = 0; n < 2; ++n) _Pragma("unroll") for (int k = 0; k < 2; ++k) \
;         acc[ai][bj][m][n] = __builtin_amdgcn_mfma_f32_16x16x32_bf16(Bt[n][k], At[m][k], acc[ai][bj][m][n], 0, 0, 0); __builtin_amdgcn_s_setprio(0); } while (0)
; #define PG8_WAIT_V(n) asm volatile("s_waitcnt vmcnt(" #n ")" ::: "memory")
; #define PG8_WAIT_L(n) asm volatile("s_waitcnt lgkmcnt(" #n ")" ::: "memory")
; #define PG8_BAR __builtin_amdgcn_s_barrier()
; #define PG8_SCHED __builtin_amdgcn_sched_barrier(0)
;     ...
;         for (int t = 0; t < nt; t += 2) {
;             const bool last = (t == nt - 2);
;             const char* a1 = cA + (size_t)(t + 1) * kstep;
;             const char* a2 = last ? nA : cA + (size_t)(t + 2) * kstep; const char* b2 = last ? nB : cB + (size_t)(t + 2) * kstep;
;             const char* a3 = a2 + kstep; const char* b3 = b2 + kstep;
;             if (last && has_next) S.a_ready(nxt);
;             if constexpr (SP2) {
;             PG8_LDB(B0, 0, 0); PG8_LDB(B1, 0, 1); PG8_SCHED; PG8_LDA(At, 0, 0); PG8_STAGE(PG8_SA(1, 1), a1 + hstepA, voffA);
;             PG8_WAIT_V(8); PG8_WAIT_L(0); PG8_BAR; PG8_MMA(0, 0, At, B0); PG8_MMA(0, 1, At, B1); PG8_BAR; PG8_SCHED;
;     ...
;             PG8_LDA(At, 1, 1); PG8_STAGE(PG8_SB(1, 0), b3, voffB); PG8_STAGE(PG8_SB(1, 1), b3 + hstepB, voffB); PG8_STAGE(PG8_SA(1, 0), a3, voffA);
;             PG8_WAIT_V(8); PG8_WAIT_L(0); PG8_BAR; PG8_MMA(1, 0, At, B0); PG8_MMA(1, 1, At, B1); PG8_BAR; PG8_SCHED;
	s_add_i32 s8, s27, s0
	v_lshl_add_u64 v[164:165], v[164:165], 0, s[62:63]
	s_mov_b32 m0, s8
	ds_read_b128 v[176:179], v231 offset:49152
	ds_read_b128 v[180:183], v231 offset:50176
	ds_read_b128 v[184:187], v231 offset:51200
	ds_read_b128 v[188:191], v231 offset:52224
	ds_read_b128 v[192:195], v231 offset:53248
	ds_read_b128 v[196:199], v231 offset:54272
	ds_read_b128 v[200:203], v231 offset:55296
	ds_read_b128 v[204:207], v231 offset:56320
	global_load_lds_dwordx4 v[164:165], off
	v_lshl_add_u64 v[164:165], v[168:169], 0, s[62:63]
	s_add_i32 m0, s8, 0x2000
	s_add_i32 s8, s31, s0
	global_load_lds_dwordx4 v[164:165], off
	v_lshl_add_u64 v[164:165], v[170:171], 0, s[62:63]
	s_mov_b32 m0, s8
	s_nop 0
	global_load_lds_dwordx4 v[164:165], off
	v_lshl_add_u64 v[164:165], v[208:209], 0, s[62:63]
	s_add_i32 m0, s8, 0x2000
	s_nop 0
	global_load_lds_dwordx4 v[164:165], off
	v_lshl_add_u64 v[164:165], v[210:211], 0, s[62:63]
	s_mov_b32 m0, s17
	s_nop 0
	global_load_lds_dwordx4 v[164:165], off
	v_lshl_add_u64 v[164:165], v[212:213], 0, s[62:63]
	s_mov_b32 m0, s18
	s_nop 0
	global_load_lds_dwordx4 v[164:165], off
	s_waitcnt vmcnt(8)
	s_waitcnt lgkmcnt(0)
	s_barrier
	s_waitcnt lgkmcnt(0)
	v_mfma_f32_16x16x32_bf16 v[62:65], v[136:139], v[176:179], v[62:65]
	v_mfma_f32_16x16x32_bf16 v[58:61], v[144:147], v[176:179], v[58:61]
	v_mfma_f32_16x16x32_bf16 v[46:49], v[136:139], v[184:187], v[46:49]
	v_mfma_f32_16x16x32_bf16 v[42:45], v[144:147], v[184:187], v[42:45]
	v_mfma_f32_16x16x32_bf16 v[30:33], v[136:139], v[192:195], v[30:33]
	v_mfma_f32_16x16x32_bf16 v[26:29], v[144:147], v[192:195], v[26:29]
	v_mfma_f32_16x16x32_bf16 v[14:17], v[136:139], v[200:203], v[14:17]
	v_mfma_f32_16x16x32_bf16 v[10:13], v[144:147], v[200:203], v[10:13]
	v_mfma_f32_16x16x32_bf16 v[62:65], v[140:143], v[180:183], v[62:65]
	v_mfma_f32_16x16x32_bf16 v[58:61], v[148:151], v[180:183], v[58:61]
	v_mfma_f32_16x16x32_bf16 v[46:49], v[140:143], v[188:191], v[46:49]
	v_mfma_f32_16x16x32_bf16 v[42:45], v[148:151], v[188:191], v[42:45]
	v_mfma_f32_16x16x32_bf16 v[30:33], v[140:143], v[196:199], v[30:33]
	v_mfma_f32_16x16x32_bf16 v[26:29], v[148:151], v[196:199], v[26:29]
	v_mfma_f32_16x16x32_bf16 v[14:17], v[140:143], v[204:207], v[14:17]
	v_mfma_f32_16x16x32_bf16 v[10:13], v[148:151], v[204:207], v[10:13]
	v_mfma_f32_16x16x32_bf16 v[54:57], v[152:155], v[176:179], v[54:57]
	v_mfma_f32_16x16x32_bf16 v[50:53], v[160:163], v[176:179], v[50:53]
	v_mfma_f32_16x16x32_bf16 v[38:41], v[152:155], v[184:187], v[38:41]
	v_mfma_f32_16x16x32_bf16 v[34:37], v[160:163], v[184:187], v[34:37]
	v_mfma_f32_16x16x32_bf16 v[22:25], v[152:155], v[192:195], v[22:25]
	v_mfma_f32_16x16x32_bf16 v[18:21], v[160:163], v[192:195], v[18:21]
	v_mfma_f32_16x16x32_bf16 v[6:9], v[152:155], v[200:203], v[6:9]
	v_mfma_f32_16x16x32_bf16 v[2:5], v[160:163], v[200:203], v[2:5]
	v_mfma_f32_16x16x32_bf16 v[54:57], v[156:159], v[180:183], v[54:57]
	v_mfma_f32_16x16x32_bf16 v[50:53], v[172:175], v[180:183], v[50:53]
	v_mfma_f32_16x16x32_bf16 v[38:41], v[156:159], v[188:191], v[38:41]
	v_mfma_f32_16x16x32_bf16 v[34:37], v[172:175], v[188:191], v[34:37]
	v_mfma_f32_16x16x32_bf16 v[22:25], v[156:159], v[196:199], v[22:25]
	v_mfma_f32_16x16x32_bf16 v[18:21], v[172:175], v[196:199], v[18:21]
	v_mfma_f32_16x16x32_bf16 v[6:9], v[156:159], v[204:207], v[6:9]
	v_mfma_f32_16x16x32_bf16 v[2:5], v[172:175], v[204:207], v[2:5]
	s_barrier
	s_add_u32 s10, s10, 0x100
	s_addc_u32 s11, s11, 0
	s_add_u32 s6, s6, 0x100
	s_addc_u32 s7, s7, 0
	s_cmp_ge_i32 s25, s13
	s_mov_b32 s8, s25
	s_cbranch_scc1 .LBB0_753
.LBB0_752:
	s_add_i32 s25, s8, 2
	s_add_u32 s27, s6, 0x80
	s_addc_u32 s9, s7, 0
	s_add_i32 s31, 0, 0x10000
	s_cmp_eq_u32 s19, s8
	s_cselect_b32 s9, s43, s9
	s_cselect_b32 s8, s42, s27
	s_cselect_b32 s35, s91, s11
	s_cselect_b32 s34, s90, s10
	s_add_i32 s27, 0, 0x14000
	v_add_u32_e32 v148, s31, v229
	v_add_u32_e32 v164, s27, v229
	ds_read_b128 v[136:139], v148
	ds_read_b128 v[140:143], v148 offset:1024
	ds_read_b128 v[144:147], v148 offset:2048
	ds_read_b128 v[148:151], v148 offset:3072
	ds_read_b128 v[152:155], v164
	ds_read_b128 v[156:159], v164 offset:1024
	ds_read_b128 v[160:163], v164 offset:2048
	ds_read_b128 v[172:175], v164 offset:3072
	v_lshl_add_u64 v[164:165], s[6:7], 0, v[134:135]
	s_add_i32 m0, s2, 0xc000
	ds_read_b128 v[176:179], v231
	ds_read_b128 v[180:183], v231 offset:1024
	ds_read_b128 v[184:187], v231 offset:2048
	ds_read_b128 v[188:191], v231 offset:3072
	ds_read_b128 v[192:195], v231 offset:4096
	ds_read_b128 v[196:199], v231 offset:5120
	ds_read_b128 v[200:203], v231 offset:6144
	ds_read_b128 v[204:207], v231 offset:7168
	global_load_lds_dwordx4 v[164:165], off
	v_lshl_add_u64 v[164:165], s[6:7], 0, v[132:133]
	s_add_i32 m0, s2, 0xe000
	s_nop 0
	global_load_lds_dwordx4 v[164:165], off
	s_waitcnt vmcnt(8)
	s_waitcnt lgkmcnt(0)
	s_barrier
; #define PG8_STAGE(bufoff, gbase, voff) do { _Pragma("unroll") for (int _i = 0; _i < 2; ++_i) \
;         __builtin_amdgcn_global_load_lds((const unsigned*)((const char*)(gbase) + (voff)[_i]), (PG8_LAS unsigned*)(lds + (bufoff) + ldsw + _i * 8192), 16, 0, 0); } while (0)
; #define PG8_LDA(dst, b, h) do { _Pragma("unroll") for (int m = 0; m < 4; ++m) _Pragma("unroll") for (int k = 0; k < 2; ++k) dst[m][k] = *(const PG8_LAS bf16x8*)(lds + PG8_SA(b, h) + aoff + m * 2048 + k * 1024); } while (0)
; #define PG8_LDB(dst, b, h) do { _Pragma("unroll") for (int n = 0; n < 2; ++n) _Pragma("unroll") for (int k = 0; k < 2; ++k) dst[n][k] = *(const PG8_LAS bf16x8*)(lds + PG8_SB(b, h) + boff + n * 2048 + k * 1024); } while (0)
; #define PG8_MMA(ai, bj, At, Bt) do { __builtin_amdgcn_s_setprio(1); _Pragma("unroll") for (int m = 0; m < 4; ++m) _Pragma("unroll") for (int n = 0; n < 2; ++n) _Pragma("unroll") for (int k = 0; k < 2; ++k) \
;         acc[ai][bj][m][n] = __builtin_amdgcn_mfma_f32_16x16x32_bf16(Bt[n][k], At[m][k], acc[ai][bj][m][n], 0, 0, 0); __builtin_amdgcn_s_setprio(0); } while (0)
; #define PG8_WAIT_V(n) asm volatile("s_waitcnt vmcnt(" #n ")" ::: "memory")
; #define PG8_WAIT_L(n) asm volatile("s_waitcnt lgkmcnt(" #n ")" ::: "memory")
; #define PG8_BAR __builtin_amdgcn_s_barrier()
; #define PG8_SCHED __builtin_amdgcn_sched_barrier(0)
;     ...
;             PG8_LDB(B0, 0, 0); PG8_LDB(B1, 0, 1); PG8_SCHED; PG8_LDA(At, 0, 0); PG8_STAGE(PG8_SA(1, 1), a1 + hstepA, voffA);
;             PG8_WAIT_V(8); PG8_WAIT_L(0); PG8_BAR; PG8_MMA(0, 0, At, B0); PG8_MMA(0, 1, At, B1); PG8_BAR; PG8_SCHED;
;             PG8_LDA(At, 0, 1); PG8_STAGE(PG8_SB(0, 0), b2, voffB); PG8_STAGE(PG8_SB(0, 1), b2 + hstepB, voffB); PG8_STAGE(PG8_SA(0, 0), a2, voffA);
;             PG8_WAIT_V(8); PG8_WAIT_L(0); PG8_BAR; PG8_MMA(1, 0, At, B0); PG8_MMA(1, 1, At, B1); PG8_BAR; PG8_SCHED;
	s_waitcnt lgkmcnt(0)
	v_mfma_f32_16x16x32_bf16 v[126:129], v[136:139], v[176:179], v[126:129]
	v_mfma_f32_16x16x32_bf16 v[122:125], v[144:147], v[176:179], v[122:125]
	v_mfma_f32_16x16x32_bf16 v[110:113], v[136:139], v[184:187], v[110:113]
	v_mfma_f32_16x16x32_bf16 v[106:109], v[144:147], v[184:187], v[106:109]
	v_mfma_f32_16x16x32_bf16 v[94:97], v[136:139], v[192:195], v[94:97]
	v_mfma_f32_16x16x32_bf16 v[90:93], v[144:147], v[192:195], v[90:93]
	v_mfma_f32_16x16x32_bf16 v[78:81], v[136:139], v[200:203], v[78:81]
	v_mfma_f32_16x16x32_bf16 v[74:77], v[144:147], v[200:203], v[74:77]
	v_mfma_f32_16x16x32_bf16 v[126:129], v[140:143], v[180:183], v[126:129]
	v_mfma_f32_16x16x32_bf16 v[122:125], v[148:151], v[180:183], v[122:125]
	v_mfma_f32_16x16x32_bf16 v[110:113], v[140:143], v[188:191], v[110:113]
	v_mfma_f32_16x16x32_bf16 v[106:109], v[148:151], v[188:191], v[106:109]
	v_mfma_f32_16x16x32_bf16 v[94:97], v[140:143], v[196:199], v[94:97]
	v_mfma_f32_16x16x32_bf16 v[90:93], v[148:151], v[196:199], v[90:93]
	v_mfma_f32_16x16x32_bf16 v[78:81], v[140:143], v[204:207], v[78:81]
	v_mfma_f32_16x16x32_bf16 v[74:77], v[148:151], v[204:207], v[74:77]
	v_mfma_f32_16x16x32_bf16 v[118:121], v[152:155], v[176:179], v[118:121]
	v_mfma_f32_16x16x32_bf16 v[114:117], v[160:163], v[176:179], v[114:117]
	v_mfma_f32_16x16x32_bf16 v[102:105], v[152:155], v[184:187], v[102:105]
	v_mfma_f32_16x16x32_bf16 v[98:101], v[160:163], v[184:187], v[98:101]
	v_mfma_f32_16x16x32_bf16 v[86:89], v[152:155], v[192:195], v[86:89]
	v_mfma_f32_16x16x32_bf16 v[82:85], v[160:163], v[192:195], v[82:85]
	v_mfma_f32_16x16x32_bf16 v[70:73], v[152:155], v[200:203], v[70:73]
	v_mfma_f32_16x16x32_bf16 v[66:69], v[160:163], v[200:203], v[66:69]
	v_mfma_f32_16x16x32_bf16 v[118:121], v[156:159], v[180:183], v[118:121]
	v_mfma_f32_16x16x32_bf16 v[114:117], v[172:175], v[180:183], v[114:117]
	v_mfma_f32_16x16x32_bf16 v[102:105], v[156:159], v[188:191], v[102:105]
	v_mfma_f32_16x16x32_bf16 v[98:101], v[172:175], v[188:191], v[98:101]
	v_mfma_f32_16x16x32_bf16 v[86:89], v[156:159], v[196:199], v[86:89]
	v_mfma_f32_16x16x32_bf16 v[82:85], v[172:175], v[196:199], v[82:85]
	v_mfma_f32_16x16x32_bf16 v[70:73], v[156:159], v[204:207], v[70:73]
	v_mfma_f32_16x16x32_bf16 v[66:69], v[172:175], v[204:207], v[66:69]
	s_barrier
	s_add_i32 s31, s31, s0
	v_lshl_add_u64 v[164:165], s[34:35], 0, v[166:167]
	s_mov_b32 m0, s31
	ds_read_b128 v[176:179], v231 offset:16384
	ds_read_b128 v[180:183], v231 offset:17408
	ds_read_b128 v[184:187], v231 offset:18432
	ds_read_b128 v[188:191], v231 offset:19456
	ds_read_b128 v[192:195], v231 offset:20480
	ds_read_b128 v[196:199], v231 offset:21504
	ds_read_b128 v[200:203], v231 offset:22528
	ds_read_b128 v[204:207], v231 offset:23552
	global_load_lds_dwordx4 v[164:165], off
	s_add_i32 m0, s31, 0x2000
	v_lshl_add_u64 v[168:169], s[34:35], 0, v[130:131]
	s_add_u32 s34, s34, s58
	s_addc_u32 s35, s35, s59
	s_add_i32 s27, s27, s0
	global_load_lds_dwordx4 v[168:169], off
	v_lshl_add_u64 v[170:171], s[34:35], 0, v[166:167]
	s_mov_b32 m0, s27
	v_lshl_add_u64 v[208:209], s[34:35], 0, v[130:131]
	global_load_lds_dwordx4 v[170:171], off
	s_add_i32 m0, s27, 0x2000
	v_lshl_add_u64 v[210:211], s[8:9], 0, v[166:167]
	global_load_lds_dwordx4 v[208:209], off
	s_mov_b32 m0, s2
	v_lshl_add_u64 v[212:213], s[8:9], 0, v[130:131]
	global_load_lds_dwordx4 v[210:211], off
	s_mov_b32 m0, s3
	s_nop 0
	global_load_lds_dwordx4 v[212:213], off
	s_waitcnt vmcnt(8)
	s_waitcnt lgkmcnt(0)
	s_barrier
	s_waitcnt lgkmcnt(0)
	v_mfma_f32_16x16x32_bf16 v[62:65], v[136:139], v[176:179], v[62:65]
	v_mfma_f32_16x16x32_bf16 v[58:61], v[144:147], v[176:179], v[58:61]
	v_mfma_f32_16x16x32_bf16 v[46:49], v[136:139], v[184:187], v[46:49]
	v_mfma_f32_16x16x32_bf16 v[42:45], v[144:147], v[184:187], v[42:45]
	v_mfma_f32_16x16x32_bf16 v[30:33], v[136:139], v[192:195], v[30:33]
	v_mfma_f32_16x16x32_bf16 v[26:29], v[144:147], v[192:195], v[26:29]
	v_mfma_f32_16x16x32_bf16 v[14:17], v[136:139], v[200:203], v[14:17]
	v_mfma_f32_16x16x32_bf16 v[10:13], v[144:147], v[200:203], v[10:13]
	v_mfma_f32_16x16x32_bf16 v[62:65], v[140:143], v[180:183], v[62:65]
	v_mfma_f32_16x16x32_bf16 v[58:61], v[148:151], v[180:183], v[58:61]
	v_mfma_f32_16x16x32_bf16 v[46:49], v[140:143], v[188:191], v[46:49]
	v_mfma_f32_16x16x32_bf16 v[42:45], v[148:151], v[188:191], v[42:45]
	v_mfma_f32_16x16x32_bf16 v[30:33], v[140:143], v[196:199], v[30:33]
	v_mfma_f32_16x16x32_bf16 v[26:29], v[148:151], v[196:199], v[26:29]
	v_mfma_f32_16x16x32_bf16 v[14:17], v[140:143], v[204:207], v[14:17]
	v_mfma_f32_16x16x32_bf16 v[10:13], v[148:151], v[204:207], v[10:13]
	v_mfma_f32_16x16x32_bf16 v[54:57], v[152:155], v[176:179], v[54:57]
	v_mfma_f32_16x16x32_bf16 v[50:53], v[160:163], v[176:179], v[50:53]
	v_mfma_f32_16x16x32_bf16 v[38:41], v[152:155], v[184:187], v[38:41]
	v_mfma_f32_16x16x32_bf16 v[34:37], v[160:163], v[184:187], v[34:37]
	v_mfma_f32_16x16x32_bf16 v[22:25], v[152:155], v[192:195], v[22:25]
	v_mfma_f32_16x16x32_bf16 v[18:21], v[160:163], v[192:195], v[18:21]
	v_mfma_f32_16x16x32_bf16 v[6:9], v[152:155], v[200:203], v[6:9]
	v_mfma_f32_16x16x32_bf16 v[2:5], v[160:163], v[200:203], v[2:5]
	v_mfma_f32_16x16x32_bf16 v[54:57], v[156:159], v[180:183], v[54:57]
	v_mfma_f32_16x16x32_bf16 v[50:53], v[172:175], v[180:183], v[50:53]
	v_mfma_f32_16x16x32_bf16 v[38:41], v[156:159], v[188:191], v[38:41]
	v_mfma_f32_16x16x32_bf16 v[34:37], v[172:175], v[188:191], v[34:37]
	v_mfma_f32_16x16x32_bf16 v[22:25], v[156:159], v[196:199], v[22:25]
	v_mfma_f32_16x16x32_bf16 v[18:21], v[172:175], v[196:199], v[18:21]
	v_mfma_f32_16x16x32_bf16 v[6:9], v[156:159], v[204:207], v[6:9]
	v_mfma_f32_16x16x32_bf16 v[2:5], v[172:175], v[204:207], v[2:5]
	s_barrier
; #define PG8_STAGE(bufoff, gbase, voff) do { _Pragma("unroll") for (int _i = 0; _i < 2; ++_i) \
;         __builtin_amdgcn_global_load_lds((const unsigned*)((const char*)(gbase) + (voff)[_i]), (PG8_LAS unsigned*)(lds + (bufoff) + ldsw + _i * 8192), 16, 0, 0); } while (0)
; #define PG8_LDA(dst, b, h) do { _Pragma("unroll") for (int m = 0; m < 4; ++m) _Pragma("unroll") for (int k = 0; k < 2; ++k) dst[m][k] = *(const PG8_LAS bf16x8*)(lds + PG8_SA(b, h) + aoff + m * 2048 + k * 1024); } while (0)
; #define PG8_LDB(dst, b, h) do { _Pragma("unroll") for (int n = 0; n < 2; ++n) _Pragma("unroll") for (int k = 0; k < 2; ++k) dst[n][k] = *(const PG8_LAS bf16x8*)(lds + PG8_SB(b, h) + boff + n * 2048 + k * 1024); } while (0)
; #define PG8_MMA(ai, bj, At, Bt) do { __builtin_amdgcn_s_setprio(1); _Pragma("unroll") for (int m = 0; m < 4; ++m) _Pragma("unroll") for (int n = 0; n < 2; ++n) _Pragma("unroll") for (int k = 0; k < 2; ++k) \
;         acc[ai][bj][m][n] = __builtin_amdgcn_mfma_f32_16x16x32_bf16(Bt[n][k], At[m][k], acc[ai][bj][m][n], 0, 0, 0); __builtin_amdgcn_s_setprio(0); } while (0)
; #define PG8_WAIT_V(n) asm volatile("s_waitcnt vmcnt(" #n ")" ::: "memory")
; #define PG8_WAIT_L(n) asm volatile("s_waitcnt lgkmcnt(" #n ")" ::: "memory")
; #define PG8_BAR __builtin_amdgcn_s_barrier()
; #define PG8_SCHED __builtin_amdgcn_sched_barrier(0)
;     ...
;             PG8_LDB(B0, 1, 0); PG8_LDB(B1, 1, 1); PG8_SCHED; PG8_LDA(At, 1, 0); PG8_STAGE(PG8_SA(0, 1), a2 + hstepA, voffA);
;             PG8_WAIT_V(8); PG8_WAIT_L(0); PG8_BAR; PG8_MMA(0, 0, At, B0); PG8_MMA(0, 1, At, B1); PG8_BAR; PG8_SCHED;
;             PG8_LDA(At, 1, 1); PG8_STAGE(PG8_SB(1, 0), b3, voffB); PG8_STAGE(PG8_SB(1, 1), b3 + hstepB, voffB); PG8_STAGE(PG8_SA(1, 0), a3, voffA);
;             PG8_WAIT_V(8); PG8_WAIT_L(0); PG8_BAR; PG8_MMA(1, 0, At, B0); PG8_MMA(1, 1, At, B1); PG8_BAR; PG8_SCHED;
	s_add_i32 s27, 0, 0x18000
	s_add_i32 s31, 0, 0x1c000
	v_add_u32_e32 v148, s27, v229
	v_add_u32_e32 v172, s31, v229
	ds_read_b128 v[136:139], v148
	ds_read_b128 v[140:143], v148 offset:1024
	ds_read_b128 v[144:147], v148 offset:2048
	ds_read_b128 v[148:151], v148 offset:3072
	ds_read_b128 v[152:155], v172
	ds_read_b128 v[156:159], v172 offset:1024
	ds_read_b128 v[160:163], v172 offset:2048
	ds_read_b128 v[172:175], v172 offset:3072
	s_add_u32 s8, s8, s58
	s_addc_u32 s9, s9, s59
	s_mov_b32 m0, s14
	v_lshl_add_u64 v[214:215], s[8:9], 0, v[166:167]
	ds_read_b128 v[176:179], v231 offset:32768
	ds_read_b128 v[180:183], v231 offset:33792
	ds_read_b128 v[184:187], v231 offset:34816
	ds_read_b128 v[188:191], v231 offset:35840
	ds_read_b128 v[192:195], v231 offset:36864
	ds_read_b128 v[196:199], v231 offset:37888
	ds_read_b128 v[200:203], v231 offset:38912
	ds_read_b128 v[204:207], v231 offset:39936
	global_load_lds_dwordx4 v[214:215], off
	v_lshl_add_u64 v[214:215], s[8:9], 0, v[130:131]
	s_mov_b32 m0, s15
	s_nop 0
	global_load_lds_dwordx4 v[214:215], off
	s_waitcnt vmcnt(8)
	s_waitcnt lgkmcnt(0)
	s_barrier
	s_waitcnt lgkmcnt(0)
	v_mfma_f32_16x16x32_bf16 v[126:129], v[136:139], v[176:179], v[126:129]
	v_mfma_f32_16x16x32_bf16 v[122:125], v[144:147], v[176:179], v[122:125]
	v_mfma_f32_16x16x32_bf16 v[110:113], v[136:139], v[184:187], v[110:113]
	v_mfma_f32_16x16x32_bf16 v[106:109], v[144:147], v[184:187], v[106:109]
	v_mfma_f32_16x16x32_bf16 v[94:97], v[136:139], v[192:195], v[94:97]
	v_mfma_f32_16x16x32_bf16 v[90:93], v[144:147], v[192:195], v[90:93]
	v_mfma_f32_16x16x32_bf16 v[78:81], v[136:139], v[200:203], v[78:81]
	v_mfma_f32_16x16x32_bf16 v[74:77], v[144:147], v[200:203], v[74:77]
	v_mfma_f32_16x16x32_bf16 v[126:129], v[140:143], v[180:183], v[126:129]
	v_mfma_f32_16x16x32_bf16 v[122:125], v[148:151], v[180:183], v[122:125]
	v_mfma_f32_16x16x32_bf16 v[110:113], v[140:143], v[188:191], v[110:113]
	v_mfma_f32_16x16x32_bf16 v[106:109], v[148:151], v[188:191], v[106:109]
	v_mfma_f32_16x16x32_bf16 v[94:97], v[140:143], v[196:199], v[94:97]
	v_mfma_f32_16x16x32_bf16 v[90:93], v[148:151], v[196:199], v[90:93]
	v_mfma_f32_16x16x32_bf16 v[78:81], v[140:143], v[204:207], v[78:81]
	v_mfma_f32_16x16x32_bf16 v[74:77], v[148:151], v[204:207], v[74:77]
	v_mfma_f32_16x16x32_bf16 v[118:121], v[152:155], v[176:179], v[118:121]
	v_mfma_f32_16x16x32_bf16 v[114:117], v[160:163], v[176:179], v[114:117]
	v_mfma_f32_16x16x32_bf16 v[102:105], v[152:155], v[184:187], v[102:105]
	v_mfma_f32_16x16x32_bf16 v[98:101], v[160:163], v[184:187], v[98:101]
	v_mfma_f32_16x16x32_bf16 v[86:89], v[152:155], v[192:195], v[86:89]
	v_mfma_f32_16x16x32_bf16 v[82:85], v[160:163], v[192:195], v[82:85]
	v_mfma_f32_16x16x32_bf16 v[70:73], v[152:155], v[200:203], v[70:73]
	v_mfma_f32_16x16x32_bf16 v[66:69], v[160:163], v[200:203], v[66:69]
	v_mfma_f32_16x16x32_bf16 v[118:121], v[156:159], v[180:183], v[118:121]
	v_mfma_f32_16x16x32_bf16 v[114:117], v[172:175], v[180:183], v[114:117]
	v_mfma_f32_16x16x32_bf16 v[102:105], v[156:159], v[188:191], v[102:105]
	v_mfma_f32_16x16x32_bf16 v[98:101], v[172:175], v[188:191], v[98:101]
	v_mfma_f32_16x16x32_bf16 v[86:89], v[156:159], v[196:199], v[86:89]
	v_mfma_f32_16x16x32_bf16 v[82:85], v[172:175], v[196:199], v[82:85]
	v_mfma_f32_16x16x32_bf16 v[70:73], v[156:159], v[204:207], v[70:73]
	v_mfma_f32_16x16x32_bf16 v[66:69], v[172:175], v[204:207], v[66:69]
	s_barrier
	s_add_i32 s8, s27, s0
	v_lshl_add_u64 v[164:165], v[164:165], 0, s[62:63]
	s_mov_b32 m0, s8
	ds_read_b128 v[176:179], v231 offset:49152
	ds_read_b128 v[180:183], v231 offset:50176
	ds_read_b128 v[184:187], v231 offset:51200
	ds_read_b128 v[188:191], v231 offset:52224
	ds_read_b128 v[192:195], v231 offset:53248
	ds_read_b128 v[196:199], v231 offset:54272
	ds_read_b128 v[200:203], v231 offset:55296
	ds_read_b128 v[204:207], v231 offset:56320
	global_load_lds_dwordx4 v[164:165], off
	v_lshl_add_u64 v[164:165], v[168:169], 0, s[62:63]
	s_add_i32 m0, s8, 0x2000
	s_add_i32 s8, s31, s0
	global_load_lds_dwordx4 v[164:165], off
	v_lshl_add_u64 v[164:165], v[170:171], 0, s[62:63]
	s_mov_b32 m0, s8
	s_nop 0
	global_load_lds_dwordx4 v[164:165], off
	v_lshl_add_u64 v[164:165], v[208:209], 0, s[62:63]
	s_add_i32 m0, s8, 0x2000
	s_nop 0
	global_load_lds_dwordx4 v[164:165], off
	v_lshl_add_u64 v[164:165], v[210:211], 0, s[62:63]
	s_mov_b32 m0, s17
	s_nop 0
	global_load_lds_dwordx4 v[164:165], off
	v_lshl_add_u64 v[164:165], v[212:213], 0, s[62:63]
	s_mov_b32 m0, s18
	s_nop 0
	global_load_lds_dwordx4 v[164:165], off
	s_waitcnt vmcnt(8)
	s_waitcnt lgkmcnt(0)
	s_barrier
	s_waitcnt lgkmcnt(0)
	v_mfma_f32_16x16x32_bf16 v[62:65], v[136:139], v[176:179], v[62:65]
	v_mfma_f32_16x16x32_bf16 v[58:61], v[144:147], v[176:179], v[58:61]
	v_mfma_f32_16x16x32_bf16 v[46:49], v[136:139], v[184:187], v[46:49]
	v_mfma_f32_16x16x32_bf16 v[42:45], v[144:147], v[184:187], v[42:45]
	v_mfma_f32_16x16x32_bf16 v[30:33], v[136:139], v[192:195], v[30:33]
	v_mfma_f32_16x16x32_bf16 v[26:29], v[144:147], v[192:195], v[26:29]
	v_mfma_f32_16x16x32_bf16 v[14:17], v[136:139], v[200:203], v[14:17]
	v_mfma_f32_16x16x32_bf16 v[10:13], v[144:147], v[200:203], v[10:13]
	v_mfma_f32_16x16x32_bf16 v[62:65], v[140:143], v[180:183], v[62:65]
	v_mfma_f32_16x16x32_bf16 v[58:61], v[148:151], v[180:183], v[58:61]
	v_mfma_f32_16x16x32_bf16 v[46:49], v[140:143], v[188:191], v[46:49]
	v_mfma_f32_16x16x32_bf16 v[42:45], v[148:151], v[188:191], v[42:45]
	v_mfma_f32_16x16x32_bf16 v[30:33], v[140:143], v[196:199], v[30:33]
	v_mfma_f32_16x16x32_bf16 v[26:29], v[148:151], v[196:199], v[26:29]
	v_mfma_f32_16x16x32_bf16 v[14:17], v[140:143], v[204:207], v[14:17]
	v_mfma_f32_16x16x32_bf16 v[10:13], v[148:151], v[204:207], v[10:13]
	v_mfma_f32_16x16x32_bf16 v[54:57], v[152:155], v[176:179], v[54:57]
	v_mfma_f32_16x16x32_bf16 v[50:53], v[160:163], v[176:179], v[50:53]
	v_mfma_f32_16x16x32_bf16 v[38:41], v[152:155], v[184:187], v[38:41]
	v_mfma_f32_16x16x32_bf16 v[34:37], v[160:163], v[184:187], v[34:37]
	v_mfma_f32_16x16x32_bf16 v[22:25], v[152:155], v[192:195], v[22:25]
	v_mfma_f32_16x16x32_bf16 v[18:21], v[160:163], v[192:195], v[18:21]
	v_mfma_f32_16x16x32_bf16 v[6:9], v[152:155], v[200:203], v[6:9]
	v_mfma_f32_16x16x32_bf16 v[2:5], v[160:163], v[200:203], v[2:5]
	v_mfma_f32_16x16x32_bf16 v[54:57], v[156:159], v[180:183], v[54:57]
	v_mfma_f32_16x16x32_bf16 v[50:53], v[172:175], v[180:183], v[50:53]
	v_mfma_f32_16x16x32_bf16 v[38:41], v[156:159], v[188:191], v[38:41]
	v_mfma_f32_16x16x32_bf16 v[34:37], v[172:175], v[188:191], v[34:37]
	v_mfma_f32_16x16x32_bf16 v[22:25], v[156:159], v[196:199], v[22:25]
	v_mfma_f32_16x16x32_bf16 v[18:21], v[172:175], v[196:199], v[18:21]
	v_mfma_f32_16x16x32_bf16 v[6:9], v[156:159], v[204:207], v[6:9]
	v_mfma_f32_16x16x32_bf16 v[2:5], v[172:175], v[204:207], v[2:5]
	s_barrier
	s_add_u32 s10, s10, 0x100
	s_addc_u32 s11, s11, 0
	s_add_u32 s6, s6, 0x100
	s_addc_u32 s7, s7, 0
	s_cmp_ge_i32 s25, s13
	s_mov_b32 s8, s25
	s_cbranch_scc0 .LBB0_752

; #define SEAM(k) do { if (!MK_PER_PHASE && IN(k) && IN((k) + 1)) xcd_barrier(bar); } while (0)
; __device__ __forceinline__ void xcd_barrier(const XcdBarrier& b) {
;     asm volatile("s_waitcnt vmcnt(0)" ::: "memory");
;     __syncthreads();
;     if (threadIdx.x == 0) {
;         unsigned* bar = b.bar;
;         __builtin_amdgcn_s_waitcnt(0);
;         unsigned nloc = b.st[0], nx = b.st[1];
; __global__ void __launch_bounds__(NWAVES * 64, 2) mk_fwd(Args args) {
;     ...
;         SEAM(p + 5);
;     }
;     if (IN(N_PHASES - 1)) final_norm_phase(F, hout, HB, ssq, I.final_g);
.LBB0_775:
	v_readlane_b32 s0, v254, 51
	s_add_i32 s0, s0, 7
	s_cmp_ge_i32 s0, s57
	s_cbranch_scc1 .LBB0_108
	v_readlane_b32 s2, v254, 52
	s_cmp_eq_u32 s2, 3
	s_cbranch_scc1 .Llb6_entry
	s_waitcnt vmcnt(0)
	s_waitcnt vmcnt(0) lgkmcnt(0)
	s_barrier
	s_mov_b64 s[4:5], exec
	v_readlane_b32 s2, v252, 11
	v_readlane_b32 s3, v252, 12
	s_and_b64 s[2:3], s[4:5], s[2:3]
	s_mov_b64 exec, s[2:3]
	s_cbranch_execz .LBB0_107
	v_readlane_b32 s0, v254, 41
	s_waitcnt vmcnt(0) expcnt(0) lgkmcnt(0)
	s_nop 0
	v_mov_b32_e32 v2, s0
	ds_read_b32 v4, v2
	v_readlane_b32 s0, v254, 42
	s_waitcnt lgkmcnt(0)
	v_cmp_ne_u32_e32 vcc, 0, v4
	v_mov_b32_e32 v2, s0
	ds_read_b32 v2, v2
	s_cbranch_vccnz .LBB0_792
	v_readlane_b32 s6, v252, 0
	v_readlane_b32 s7, v252, 1
	s_load_dwordx2 s[2:3], s[6:7], 0x4
	s_waitcnt lgkmcnt(0)
	s_mul_i32 s0, s2, s77
	s_mul_i32 s0, s0, s3
	s_mov_b32 s2, 1
	s_branch .LBB0_780

; #define GAS __attribute__((address_space(1)))
; __device__ __forceinline__ void refresh(Frame& F) { int t = threadIdx.x; asm volatile("" : "+v"(t)); F.tid = t; F.lane = t & 63; F.wave = __builtin_amdgcn_readfirstlane(t >> 6); }
; __device__ __forceinline__ void final_norm_phase(Frame& F, float* out, const bf16* HB, const float* ssq, const float* gf) {
;     refresh(F);
;     const int gw = F.vcu * NWAVES + F.wave, NGW = F.G * NWAVES;
;     const GAS f32x4* gr = (const GAS f32x4*)gf + F.lane; const f32x4 g0 = gr[0], g1 = gr[64], g2 = gr[128], g3 = gr[192];
;     for (int m0 = 4 * gw; m0 < M; m0 += 4 * NGW) {
;         float sp[4]; v2u hw[4][4];
; #pragma unroll
;         for (int j = 0; j < 4; ++j) { const int m = m0 + j; sp[j] = F.lane < 16 ? pg8::ld_agent(ssq + (size_t)F.lane * M + m) : 0.f;
;             const GAS v2u* hr = (const GAS v2u*)(HB + (size_t)m * D) + F.lane;
; #pragma unroll
;             for (int jj = 0; jj < 4; ++jj) hw[j][jj] = hr[64 * jj]; }
; #pragma unroll
;         for (int j = 0; j < 4; ++j) { const float r = __builtin_amdgcn_rsqf(wave_sum(sp[j]) * (1.0f / 1024.0f) + pg8::RMS_EPS);
;             GAS f32x4* xr = (GAS f32x4*)(out + (size_t)(m0 + j) * D) + F.lane;
;             xr[0]   = (f32x4){bflo(hw[j][0].x), bfhi(hw[j][0].x), bflo(hw[j][0].y), bfhi(hw[j][0].y)} * r * g0;
;             xr[64]  = (f32x4){bflo(hw[j][1].x), bfhi(hw[j][1].x), bflo(hw[j][1].y), bfhi(hw[j][1].y)} * r * g1;
;             xr[128] = (f32x4){bflo(hw[j][2].x), bfhi(hw[j][2].x), bflo(hw[j][2].y), bfhi(hw[j][2].y)} * r * g2;
;             xr[192] = (f32x4){bflo(hw[j][3].x), bfhi(hw[j][3].x), bflo(hw[j][3].y), bfhi(hw[j][3].y)} * r * g3; }
.LBB0_827:
	s_cmp_lt_i32 s56, 26
	s_cselect_b64 s[0:1], -1, 0
	s_cmp_gt_i32 s57, 25
	s_cselect_b64 s[2:3], -1, 0
	s_and_b64 s[0:1], s[0:1], s[2:3]
	s_and_b64 vcc, exec, s[0:1]
	s_cbranch_vccz .LBB0_839
	v_readlane_b32 s1, v252, 2
	v_readfirstlane_b32 s0, v0
	s_ashr_i32 s0, s0, 4
	s_and_b32 s0, s0, -4
	s_lshl_b32 s0, s0, 1
	s_lshr_b32 s4, s1, 5
	s_lshl_b32 s4, s4, 11
	s_add_i32 s4, s4, s0
	s_and_b32 s0, s1, 7
	s_lshl_b32 s0, s0, 8
	s_add_i32 s4, s4, s0
	s_bfe_u32 s0, s1, 0x20003
	s_lshl_b32 s0, s0, 6
	s_add_i32 s4, s4, s0
	s_add_i32 s101, s4, 8
	s_cmpk_gt_i32 s4, 0x3fff
	s_cbranch_scc1 .LBB0_839
	v_readlane_b32 s8, v252, 3
	v_and_b32_e32 v18, 63, v0
	v_readlane_b32 s9, v252, 4
	v_readlane_b32 s10, v252, 5
	v_readlane_b32 s11, v252, 6
	v_readlane_b32 s12, v252, 7
	v_readlane_b32 s13, v252, 8
	v_lshlrev_b32_e32 v16, 4, v18
	v_readlane_b32 s14, v252, 9
	v_readlane_b32 s15, v252, 10
	s_mov_b64 s[8:9], s[12:13]
	s_waitcnt lgkmcnt(0)
	global_load_dwordx4 v[0:3], v16, s[8:9]
	global_load_dwordx4 v[4:7], v16, s[8:9] offset:1024
	global_load_dwordx4 v[8:11], v16, s[8:9] offset:2048
	global_load_dwordx4 v[12:15], v16, s[8:9] offset:3072
	v_and_b32_e32 v19, 64, v242
	v_add_u32_e32 v19, 64, v19
	v_xor_b32_e32 v20, 1, v242
	v_cmp_lt_i32_e32 vcc, v20, v19
	s_ashr_i32 s5, s4, 31
	s_mov_b64 s[10:11], s[14:15]
	v_cndmask_b32_e32 v20, v242, v20, vcc
	v_lshlrev_b32_e32 v50, 2, v20
	v_xor_b32_e32 v20, 2, v242
	v_cmp_lt_i32_e32 vcc, v20, v19
	s_mov_b32 s6, 4
	s_lshl_b64 s[2:3], s[4:5], 12
	v_cndmask_b32_e32 v20, v242, v20, vcc
	v_lshlrev_b32_e32 v51, 2, v20
	v_xor_b32_e32 v20, 4, v242
	v_cmp_lt_i32_e32 vcc, v20, v19
	s_add_u32 s2, s10, s2
	v_mov_b32_e32 v17, 0
	v_cndmask_b32_e32 v20, v242, v20, vcc
	v_lshlrev_b32_e32 v52, 2, v20
	v_xor_b32_e32 v20, 8, v242
	v_cmp_lt_i32_e32 vcc, v20, v19
	s_addc_u32 s3, s11, s3
	v_mov_b32_e32 v21, v17
	v_cndmask_b32_e32 v20, v242, v20, vcc
	v_lshlrev_b32_e32 v53, 2, v20
	v_xor_b32_e32 v20, 16, v242
	v_cmp_lt_i32_e32 vcc, v20, v19
	v_lshl_add_u64 v[16:17], s[2:3], 0, v[16:17]
	s_mov_b64 s[2:3], 0x3c00
	v_cndmask_b32_e32 v20, v242, v20, vcc
	v_lshlrev_b32_e32 v54, 2, v20
	v_xor_b32_e32 v20, 32, v242
	v_cmp_lt_i32_e32 vcc, v20, v19
	v_lshl_add_u64 v[16:17], v[16:17], 0, s[2:3]
	s_ashr_i32 s7, s6, 31
	v_cndmask_b32_e32 v19, v242, v20, vcc
	v_lshlrev_b32_e32 v20, 16, v18
	s_lshl_b64 s[2:3], s[4:5], 11
	v_readlane_b32 s18, v253, 52
	v_lshlrev_b32_e32 v55, 2, v19
	v_cmp_gt_u32_e64 s[0:1], 16, v18
	s_lshl_b64 s[8:9], s[6:7], 12
	v_lshl_or_b32 v18, v18, 3, s2
	v_mov_b32_e32 v19, s3
	s_lshl_b64 s[10:11], s[6:7], 11
	v_lshl_add_u64 v[20:21], s[4:5], 2, v[20:21]
	s_lshl_b64 s[12:13], s[6:7], 2
	v_mov_b32_e32 v56, 0x3727c5ac
	s_movk_i32 s5, 0xd000
	s_movk_i32 s7, 0xe000
	s_movk_i32 s14, 0xf000
	v_readlane_b32 s19, v253, 53
	s_branch .LBB0_831
.LBB0_830:
	s_or_b64 exec, exec, s[2:3]
	s_waitcnt vmcnt(0)
	ds_bpermute_b32 v42, v50, v60
	v_lshlrev_b32_e32 v62, 16, v40
	v_and_b32_e32 v63, 0xffff0000, v40
	v_lshlrev_b32_e32 v68, 16, v36
	v_and_b32_e32 v69, 0xffff0000, v36
	s_waitcnt lgkmcnt(0)
	v_add_f32_e32 v42, v60, v42
	ds_bpermute_b32 v43, v51, v42
	v_add_co_u32_e32 v60, vcc, 0x5a01000, v28
	ds_bpermute_b32 v73, v50, v59
	v_lshlrev_b32_e32 v64, 16, v41
	s_waitcnt lgkmcnt(1)
	v_add_f32_e32 v28, v42, v43
	ds_bpermute_b32 v42, v52, v28
	v_and_b32_e32 v65, 0xffff0000, v41
	v_addc_co_u32_e32 v61, vcc, 0, v29, vcc
	v_add_co_u32_e64 v66, s[2:3], s5, v16
	s_waitcnt lgkmcnt(0)
	v_add_f32_e32 v28, v28, v42
	ds_bpermute_b32 v40, v53, v28
	v_lshlrev_b32_e32 v70, 16, v37
	v_and_b32_e32 v71, 0xffff0000, v37
	v_addc_co_u32_e64 v67, s[2:3], -1, v17, s[2:3]
	s_waitcnt lgkmcnt(0)
	v_add_f32_e32 v28, v28, v40
	ds_bpermute_b32 v40, v54, v28
	v_add_f32_e32 v59, v59, v73
	s_add_i32 s4, s4, s6
	v_lshl_add_u64 v[18:19], v[18:19], 0, s[10:11]
	s_cmp_lt_i32 s4, s101
	s_waitcnt lgkmcnt(0)
	v_add_f32_e32 v28, v28, v40
	ds_bpermute_b32 v36, v55, v28
	v_lshl_add_u64 v[20:21], v[20:21], 0, s[12:13]
	s_waitcnt lgkmcnt(0)
	v_add_f32_e32 v28, v28, v36
	v_fmamk_f32 v28, v28, 0x3a800000, v56
	v_rsq_f32_e32 v72, v28
	global_load_dwordx2 v[42:43], v[60:61], off offset:2048
	global_load_dwordx2 v[40:41], v[60:61], off offset:2560
	global_load_dwordx2 v[36:37], v[60:61], off offset:3072
	global_load_dwordx2 v[28:29], v[60:61], off offset:3584
	v_pk_mul_f32 v[60:61], v[72:73], v[62:63] op_sel_hi:[0,1]
	v_pk_mul_f32 v[62:63], v[72:73], v[64:65] op_sel_hi:[0,1]
	v_pk_mul_f32 v[68:69], v[72:73], v[68:69] op_sel_hi:[0,1]
	v_pk_mul_f32 v[64:65], v[72:73], v[70:71] op_sel_hi:[0,1]
	v_pk_mul_f32 v[62:63], v[2:3], v[62:63]
	v_pk_mul_f32 v[60:61], v[0:1], v[60:61]
	v_pk_mul_f32 v[64:65], v[6:7], v[64:65]
	global_store_dwordx4 v[66:67], v[60:63], off offset:-3072
	s_nop 1
	v_pk_mul_f32 v[62:63], v[4:5], v[68:69]
	global_store_dwordx4 v[66:67], v[62:65], off offset:-2048
	ds_bpermute_b32 v62, v51, v59
	v_lshlrev_b32_e32 v60, 16, v48
	v_and_b32_e32 v61, 0xffff0000, v48
	v_lshlrev_b32_e32 v48, 16, v49
	v_and_b32_e32 v49, 0xffff0000, v49
	s_waitcnt lgkmcnt(0)
	v_add_f32_e32 v59, v59, v62
	ds_bpermute_b32 v64, v52, v59
	v_pk_mul_f32 v[60:61], v[72:73], v[60:61] op_sel_hi:[0,1]
	v_pk_mul_f32 v[48:49], v[72:73], v[48:49] op_sel_hi:[0,1]
	v_pk_mul_f32 v[62:63], v[10:11], v[48:49]
	v_pk_mul_f32 v[60:61], v[8:9], v[60:61]
	s_waitcnt lgkmcnt(0)
	v_add_f32_e32 v59, v59, v64
	global_store_dwordx4 v[66:67], v[60:63], off offset:-1024
	ds_bpermute_b32 v60, v53, v59
	v_lshlrev_b32_e32 v48, 16, v44
	v_and_b32_e32 v49, 0xffff0000, v44
	v_lshlrev_b32_e32 v44, 16, v45
	v_and_b32_e32 v45, 0xffff0000, v45
	s_waitcnt lgkmcnt(0)
; #define GAS __attribute__((address_space(1)))
; __device__ __forceinline__ void final_norm_phase(Frame& F, float* out, const bf16* HB, const float* ssq, const float* gf) {
;     ...
;         for (int j = 0; j < 4; ++j) { const float r = __builtin_amdgcn_rsqf(wave_sum(sp[j]) * (1.0f / 1024.0f) + pg8::RMS_EPS);
;             GAS f32x4* xr = (GAS f32x4*)(out + (size_t)(m0 + j) * D) + F.lane;
;             xr[0]   = (f32x4){bflo(hw[j][0].x), bfhi(hw[j][0].x), bflo(hw[j][0].y), bfhi(hw[j][0].y)} * r * g0;
;             xr[64]  = (f32x4){bflo(hw[j][1].x), bfhi(hw[j][1].x), bflo(hw[j][1].y), bfhi(hw[j][1].y)} * r * g1;
;             xr[128] = (f32x4){bflo(hw[j][2].x), bfhi(hw[j][2].x), bflo(hw[j][2].y), bfhi(hw[j][2].y)} * r * g2;
;             xr[192] = (f32x4){bflo(hw[j][3].x), bfhi(hw[j][3].x), bflo(hw[j][3].y), bfhi(hw[j][3].y)} * r * g3; }
	v_add_f32_e32 v59, v59, v60
	ds_bpermute_b32 v64, v54, v59
	v_pk_mul_f32 v[44:45], v[72:73], v[44:45] op_sel_hi:[0,1]
	v_pk_mul_f32 v[62:63], v[14:15], v[44:45]
	v_pk_mul_f32 v[48:49], v[72:73], v[48:49] op_sel_hi:[0,1]
	v_pk_mul_f32 v[60:61], v[12:13], v[48:49]
	s_waitcnt lgkmcnt(0)
	v_add_f32_e32 v44, v59, v64
	ds_bpermute_b32 v45, v55, v44
	v_add_co_u32_e32 v48, vcc, s7, v16
	ds_bpermute_b32 v59, v50, v58
	s_nop 0
	v_addc_co_u32_e32 v49, vcc, -1, v17, vcc
	s_waitcnt lgkmcnt(1)
	v_add_f32_e32 v44, v44, v45
	v_fmamk_f32 v44, v44, 0x3a800000, v56
	global_store_dwordx4 v[48:49], v[60:63], off offset:-4096
	v_and_b32_e32 v45, 0xffff0000, v46
	s_waitcnt lgkmcnt(0)
	v_add_f32_e32 v58, v58, v59
	v_rsq_f32_e32 v60, v44
	v_lshlrev_b32_e32 v44, 16, v46
	v_lshlrev_b32_e32 v46, 16, v47
	v_and_b32_e32 v47, 0xffff0000, v47
	v_pk_mul_f32 v[44:45], v[60:61], v[44:45] op_sel_hi:[0,1]
	v_pk_mul_f32 v[46:47], v[60:61], v[46:47] op_sel_hi:[0,1]
	ds_bpermute_b32 v59, v51, v58
	v_pk_mul_f32 v[46:47], v[2:3], v[46:47]
	v_pk_mul_f32 v[44:45], v[0:1], v[44:45]
	global_store_dwordx4 v[48:49], v[44:47], off offset:-3072
	s_nop 1
	v_lshlrev_b32_e32 v44, 16, v38
	v_and_b32_e32 v45, 0xffff0000, v38
	v_lshlrev_b32_e32 v38, 16, v39
	v_and_b32_e32 v39, 0xffff0000, v39
	v_pk_mul_f32 v[44:45], v[60:61], v[44:45] op_sel_hi:[0,1]
	v_pk_mul_f32 v[38:39], v[60:61], v[38:39] op_sel_hi:[0,1]
	v_pk_mul_f32 v[46:47], v[6:7], v[38:39]
	v_pk_mul_f32 v[44:45], v[4:5], v[44:45]
	global_store_dwordx4 v[48:49], v[44:47], off offset:-2048
	v_lshlrev_b32_e32 v38, 16, v34
	v_and_b32_e32 v39, 0xffff0000, v34
	s_waitcnt lgkmcnt(0)
	v_add_f32_e32 v44, v58, v59
	ds_bpermute_b32 v45, v52, v44
	v_pk_mul_f32 v[38:39], v[60:61], v[38:39] op_sel_hi:[0,1]
	v_lshlrev_b32_e32 v34, 16, v35
	v_and_b32_e32 v35, 0xffff0000, v35
	v_pk_mul_f32 v[34:35], v[60:61], v[34:35] op_sel_hi:[0,1]
	s_waitcnt lgkmcnt(0)
	v_add_f32_e32 v58, v44, v45
	ds_bpermute_b32 v59, v53, v58
	v_pk_mul_f32 v[44:45], v[8:9], v[38:39]
	v_pk_mul_f32 v[46:47], v[10:11], v[34:35]
	v_lshlrev_b32_e32 v34, 16, v30
	v_and_b32_e32 v35, 0xffff0000, v30
	s_waitcnt lgkmcnt(0)
	v_add_f32_e32 v38, v58, v59
	ds_bpermute_b32 v39, v54, v38
	v_lshlrev_b32_e32 v30, 16, v31
	v_and_b32_e32 v31, 0xffff0000, v31
	v_pk_mul_f32 v[30:31], v[60:61], v[30:31] op_sel_hi:[0,1]
	global_store_dwordx4 v[48:49], v[44:47], off offset:-1024
	s_waitcnt lgkmcnt(0)
	v_add_f32_e32 v38, v38, v39
	ds_bpermute_b32 v39, v55, v38
	v_pk_mul_f32 v[46:47], v[14:15], v[30:31]
	v_pk_mul_f32 v[34:35], v[60:61], v[34:35] op_sel_hi:[0,1]
	v_pk_mul_f32 v[44:45], v[12:13], v[34:35]
	v_and_b32_e32 v31, 0xffff0000, v32
	s_waitcnt lgkmcnt(0)
	v_add_f32_e32 v30, v38, v39
	v_fmamk_f32 v30, v30, 0x3a800000, v56
	v_rsq_f32_e32 v34, v30
	v_lshlrev_b32_e32 v30, 16, v32
	v_lshlrev_b32_e32 v32, 16, v33
	v_and_b32_e32 v33, 0xffff0000, v33
	v_pk_mul_f32 v[30:31], v[34:35], v[30:31] op_sel_hi:[0,1]
	v_pk_mul_f32 v[32:33], v[34:35], v[32:33] op_sel_hi:[0,1]
	ds_bpermute_b32 v35, v50, v57
	v_add_co_u32_e32 v38, vcc, s14, v16
	v_pk_mul_f32 v[32:33], v[2:3], v[32:33]
	v_pk_mul_f32 v[30:31], v[0:1], v[30:31]
	v_addc_co_u32_e32 v39, vcc, -1, v17, vcc
	global_store_dwordx4 v[38:39], v[30:33], off offset:-3072
	global_store_dwordx4 v[48:49], v[44:47], off
	s_nop 0
	v_lshlrev_b32_e32 v30, 16, v26
	v_and_b32_e32 v31, 0xffff0000, v26
	v_lshlrev_b32_e32 v26, 16, v27
	v_and_b32_e32 v27, 0xffff0000, v27
	s_waitcnt lgkmcnt(0)
	v_pk_mul_f32 v[30:31], v[34:35], v[30:31] op_sel_hi:[0,1]
	v_pk_mul_f32 v[26:27], v[34:35], v[26:27] op_sel_hi:[0,1]
	v_add_f32_e32 v35, v57, v35
	ds_bpermute_b32 v44, v51, v35
	v_pk_mul_f32 v[32:33], v[6:7], v[26:27]
	v_pk_mul_f32 v[30:31], v[4:5], v[30:31]
	global_store_dwordx4 v[38:39], v[30:33], off offset:-2048
	v_lshlrev_b32_e32 v26, 16, v24
	v_and_b32_e32 v27, 0xffff0000, v24
	s_waitcnt lgkmcnt(0)
	v_add_f32_e32 v32, v35, v44
	ds_bpermute_b32 v33, v52, v32
	v_lshlrev_b32_e32 v24, 16, v25
	v_and_b32_e32 v25, 0xffff0000, v25
	v_pk_mul_f32 v[30:31], v[34:35], v[26:27] op_sel_hi:[0,1]
	v_pk_mul_f32 v[24:25], v[34:35], v[24:25] op_sel_hi:[0,1]
	s_waitcnt lgkmcnt(0)
	v_add_f32_e32 v32, v32, v33
	ds_bpermute_b32 v33, v53, v32
	v_pk_mul_f32 v[26:27], v[10:11], v[24:25]
	v_pk_mul_f32 v[24:25], v[8:9], v[30:31]
	global_store_dwordx4 v[38:39], v[24:27], off offset:-1024
	s_waitcnt lgkmcnt(0)
	v_add_f32_e32 v30, v32, v33
	ds_bpermute_b32 v31, v54, v30
	v_lshlrev_b32_e32 v24, 16, v22
	v_and_b32_e32 v25, 0xffff0000, v22
	v_lshlrev_b32_e32 v22, 16, v23
	v_and_b32_e32 v23, 0xffff0000, v23
	s_waitcnt lgkmcnt(0)
	v_add_f32_e32 v30, v30, v31
	ds_bpermute_b32 v31, v55, v30
	v_pk_mul_f32 v[26:27], v[34:35], v[24:25] op_sel_hi:[0,1]
	v_pk_mul_f32 v[22:23], v[34:35], v[22:23] op_sel_hi:[0,1]
	v_pk_mul_f32 v[24:25], v[14:15], v[22:23]
	v_pk_mul_f32 v[22:23], v[12:13], v[26:27]
	global_store_dwordx4 v[16:17], v[22:25], off offset:-4096
	s_waitcnt lgkmcnt(0)
	s_nop 0
	v_add_f32_e32 v22, v30, v31
	v_fmamk_f32 v22, v22, 0x3a800000, v56
	v_rsq_f32_e32 v26, v22
	s_waitcnt vmcnt(15)
	v_lshlrev_b32_e32 v22, 16, v42
	v_and_b32_e32 v23, 0xffff0000, v42
	v_lshlrev_b32_e32 v24, 16, v43
	v_and_b32_e32 v25, 0xffff0000, v43
	v_pk_mul_f32 v[22:23], v[26:27], v[22:23] op_sel_hi:[0,1]
	v_pk_mul_f32 v[24:25], v[26:27], v[24:25] op_sel_hi:[0,1]
	v_pk_mul_f32 v[24:25], v[2:3], v[24:25]
	v_pk_mul_f32 v[22:23], v[0:1], v[22:23]
	global_store_dwordx4 v[16:17], v[22:25], off offset:-3072
	s_waitcnt vmcnt(15)
	s_nop 0
	v_lshlrev_b32_e32 v22, 16, v40
	v_and_b32_e32 v23, 0xffff0000, v40
	v_lshlrev_b32_e32 v24, 16, v41
	v_and_b32_e32 v25, 0xffff0000, v41
	v_pk_mul_f32 v[22:23], v[26:27], v[22:23] op_sel_hi:[0,1]
	v_pk_mul_f32 v[24:25], v[26:27], v[24:25] op_sel_hi:[0,1]
	v_pk_mul_f32 v[24:25], v[6:7], v[24:25]
	v_pk_mul_f32 v[22:23], v[4:5], v[22:23]
	global_store_dwordx4 v[16:17], v[22:25], off offset:-2048
	s_waitcnt vmcnt(15)
	s_nop 0
	v_lshlrev_b32_e32 v22, 16, v36
	v_and_b32_e32 v23, 0xffff0000, v36
	v_lshlrev_b32_e32 v24, 16, v37
	v_and_b32_e32 v25, 0xffff0000, v37
	v_pk_mul_f32 v[22:23], v[26:27], v[22:23] op_sel_hi:[0,1]
	v_pk_mul_f32 v[24:25], v[26:27], v[24:25] op_sel_hi:[0,1]
	v_pk_mul_f32 v[24:25], v[10:11], v[24:25]
	v_pk_mul_f32 v[22:23], v[8:9], v[22:23]
	global_store_dwordx4 v[16:17], v[22:25], off offset:-1024
	s_waitcnt vmcnt(15)
	s_nop 0
	v_lshlrev_b32_e32 v22, 16, v28
	v_and_b32_e32 v23, 0xffff0000, v28
	v_lshlrev_b32_e32 v24, 16, v29
	v_and_b32_e32 v25, 0xffff0000, v29
	v_pk_mul_f32 v[22:23], v[26:27], v[22:23] op_sel_hi:[0,1]
	v_pk_mul_f32 v[24:25], v[26:27], v[24:25] op_sel_hi:[0,1]
	v_pk_mul_f32 v[24:25], v[14:15], v[24:25]
	v_pk_mul_f32 v[22:23], v[12:13], v[22:23]
	global_store_dwordx4 v[16:17], v[22:25], off
	v_lshl_add_u64 v[16:17], v[16:17], 0, s[8:9]
	s_cbranch_scc0 .LBB0_839
